# EPI_RES epilogues (FFN-down x3 code paths, w_out x2): residual row loads issued 8-deep per pass instead of one dependent load per row group
# speedup vs baseline: 1.0238x; 1.0135x over previous
; template <int EPI, int MI>
; DI void gemm_tile(const GemmDesc& g, int tm, int tn, char* smem) {
;     ...
;   const int srow = tid >> 3;
;   const int schunk = (tid & 7) ^ ((srow & 7) ^ ((srow >> 3) & 3));
;     ...
;   const int rowA = wm * (32 * MI) + r, rowB = wn * 64 + r;
;   const int hk = hh ^ ((r & 7) ^ ((r >> 3) & 3));
;     ...
;   G_GLDS(0, 0);
;   asm volatile("s_waitcnt vmcnt(0)" ::: "memory");
;   __syncthreads();
;   for (int kt = 0; kt < nk; kt += 2) {
;     if (kt + 1 < nk) G_GLDS(kt + 1, 1);
;     G_COMPUTE(0);
; template <int EPI, int MI>
; DI void gemm_phase(const GemmDesc& g, char* smem, int vb, int nvb) {
;     ...
;     const int mg = q / per;
;     const int rem = q - mg * per;
;     const int tn = rem / PM;
;     const int tm = mbase + mg * PM + (rem - tn * PM);
.LBB0_873:
	s_abs_i32 s1, s20
	v_readlane_b32 s4, v219, 50
	s_mul_hi_u32 s4, s1, s4
	v_readlane_b32 s16, v219, 49
	s_mul_i32 s5, s4, s16
	s_sub_i32 s1, s1, s5
	s_ashr_i32 s0, s20, 31
	s_add_i32 s5, s4, 1
	s_sub_i32 s15, s1, s16
	s_cmp_ge_u32 s1, s16
	s_cselect_b32 s4, s5, s4
	s_cselect_b32 s1, s15, s1
	s_add_i32 s5, s4, 1
	s_cmp_ge_u32 s1, s16
	s_cselect_b32 s1, s5, s4
	s_xor_b32 s1, s1, s0
	s_sub_i32 s0, s1, s0
	s_mul_i32 s1, s0, s16
	s_sub_i32 s1, s20, s1
	s_abs_i32 s5, s1
	v_readlane_b32 s15, v219, 52
	s_mul_hi_u32 s15, s5, s15
	v_readlane_b32 s18, v219, 51
	s_mul_i32 s16, s15, s18
	s_sub_i32 s5, s5, s16
	s_ashr_i32 s4, s1, 31
	s_add_i32 s16, s15, 1
	s_sub_i32 s17, s5, s18
	s_cmp_ge_u32 s5, s18
	s_cselect_b32 s15, s16, s15
	s_cselect_b32 s5, s17, s5
	s_add_i32 s16, s15, 1
	s_cmp_ge_u32 s5, s18
	s_cselect_b32 s5, s16, s15
	s_xor_b32 s5, s5, s4
	s_sub_i32 s4, s5, s4
	s_mul_i32 s0, s0, s18
	v_readlane_b32 s5, v223, 56
	v_mov_b32_e32 v74, v132
	s_add_i32 s0, s0, s5
	s_mul_i32 s5, s4, s18
	s_sub_i32 s1, s1, s5
	v_ashrrev_i32_e32 v2, 3, v74
	v_bfe_u32 v1, v74, 6, 2
	v_xor_b32_e32 v3, v2, v74
	s_add_i32 s1, s0, s1
	v_and_b32_e32 v0, 7, v74
	v_bitop3_b32 v3, v3, v1, 7 bitop3:0x6c
	v_lshrrev_b32_e32 v1, 3, v74
	s_lshl_b32 s38, s1, 7
	v_bfe_u32 v76, v74, 5, 1
	v_bitop3_b32 v0, v1, v0, 3 bitop3:0x6c
	v_xor_b32_e32 v6, v0, v76
	v_add_u32_e32 v0, s38, v2
	v_ashrrev_i32_e32 v1, 31, v0
	s_lshl_b32 s0, s4, 7
	v_lshlrev_b64 v[66:67], 10, v[0:1]
	v_lshl_add_u32 v90, v74, 4, 0
	v_lshl_add_u64 v[0:1], s[92:93], 0, v[66:67]
	v_lshlrev_b32_e32 v68, 4, v3
	v_mov_b32_e32 v69, v96
	v_add_u32_e32 v2, s0, v2
	v_readfirstlane_b32 s43, v90
	v_add_u32_e32 v91, 0x1000, v90
	v_lshl_add_u64 v[0:1], v[0:1], 0, v[68:69]
	v_ashrrev_i32_e32 v3, 31, v2
	v_readlane_b32 s4, v221, 31
	s_mov_b32 m0, s43
	s_mov_b64 s[72:73], 0x8000
	v_readfirstlane_b32 s44, v91
	v_add_u32_e32 v92, 0x2000, v90
	v_lshlrev_b64 v[2:3], 11, v[2:3]
	v_readlane_b32 s5, v221, 32
	global_load_lds_dwordx4 v[0:1], off
	v_lshl_add_u64 v[4:5], v[0:1], 0, s[72:73]
	s_mov_b32 m0, s44
	s_mov_b64 s[52:53], 0x10000
	v_readfirstlane_b32 s45, v92
	v_add_u32_e32 v93, 0x3000, v90
	v_lshl_add_u64 v[2:3], s[4:5], 0, v[2:3]
	global_load_lds_dwordx4 v[4:5], off
	v_lshl_add_u64 v[4:5], v[0:1], 0, s[52:53]
	s_mov_b32 m0, s45
	s_mov_b64 s[74:75], 0x18000
	v_readfirstlane_b32 s46, v93
	v_add_u32_e32 v94, 0x8000, v90
	global_load_lds_dwordx4 v[4:5], off
	v_lshl_add_u64 v[0:1], v[0:1], 0, s[74:75]
	s_mov_b32 m0, s46
	v_lshl_add_u64 v[64:65], v[2:3], 0, v[68:69]
	v_readfirstlane_b32 s47, v94
	v_add_u32_e32 v2, 0x9000, v90
	global_load_lds_dwordx4 v[0:1], off
	s_mov_b32 m0, s47
	v_readfirstlane_b32 s39, v2
	global_load_lds_dwordx4 v[64:65], off
	v_lshl_add_u64 v[0:1], v[64:65], 0, s[52:53]
	s_mov_b32 m0, s39
	s_mov_b64 s[4:5], 0x20000
	v_add_u32_e32 v2, 0xa000, v90
	global_load_lds_dwordx4 v[0:1], off
	v_lshl_add_u64 v[0:1], v[64:65], 0, s[4:5]
	v_readfirstlane_b32 s5, v2
	v_add_u32_e32 v2, 0xb000, v90
	s_mov_b32 m0, s5
	s_mov_b64 s[16:17], 0x30000
	v_readfirstlane_b32 s4, v2
	v_and_b32_e32 v73, 31, v74
	global_load_lds_dwordx4 v[0:1], off
	v_lshl_add_u64 v[0:1], v[64:65], 0, s[16:17]
	s_mov_b32 m0, s4
	v_ashrrev_i32_e32 v75, 7, v74
	global_load_lds_dwordx4 v[0:1], off
	v_lshlrev_b32_e32 v0, 7, v73
	v_lshlrev_b32_e32 v1, 7, v74
	v_lshl_or_b32 v0, v75, 13, v0
	v_and_b32_e32 v1, 0x2f80, v1
	v_lshlrev_b32_e32 v2, 4, v6
	v_add_u32_e32 v0, 0, v0
	v_add_u32_e32 v1, 0, v1
	v_xor_b32_e32 v3, 32, v2
	v_readlane_b32 s16, v220, 62
	v_add_u32_e32 v86, 0x4000, v90
	v_add_u32_e32 v81, v1, v2
	v_add_u32_e32 v80, v0, v2
	v_add_u32_e32 v79, v1, v3
	v_add_u32_e32 v78, v0, v3
	v_xor_b32_e32 v3, 64, v2
	v_xor_b32_e32 v2, 0x60, v2
	v_readlane_b32 s17, v220, 63
	v_add_u32_e32 v89, 0x5000, v90
	v_add_u32_e32 v77, v1, v3
	v_add_u32_e32 v72, v0, v3
	v_add_u32_e32 v71, v1, v2
	v_add_u32_e32 v70, v0, v2
	v_lshl_add_u64 v[0:1], s[16:17], 0, v[66:67]
	v_readfirstlane_b32 s15, v86
	v_add_u32_e32 v88, 0x6000, v90
	v_lshl_add_u64 v[0:1], v[0:1], 0, v[68:69]
	s_mov_b32 m0, s15
	v_readfirstlane_b32 s16, v89
	s_waitcnt vmcnt(0)
	s_waitcnt vmcnt(0) lgkmcnt(0)
	s_barrier
	v_add_u32_e32 v87, 0x7000, v90
	global_load_lds_dwordx4 v[0:1], off
	v_lshl_add_u64 v[2:3], v[0:1], 0, s[72:73]
	s_mov_b32 m0, s16
	v_readfirstlane_b32 s17, v88
	v_add_u32_e32 v83, 0xc000, v90
	global_load_lds_dwordx4 v[2:3], off
	v_lshl_add_u64 v[2:3], v[0:1], 0, s[52:53]
	s_mov_b32 m0, s17
	v_readfirstlane_b32 s18, v87
	global_load_lds_dwordx4 v[2:3], off
	v_lshl_add_u64 v[0:1], v[0:1], 0, s[74:75]
	s_mov_b32 m0, s18
	s_mov_b64 s[40:41], 0x80
	v_readfirstlane_b32 s19, v83
	v_add_u32_e32 v85, 0xd000, v90
	global_load_lds_dwordx4 v[0:1], off
	v_lshl_add_u64 v[0:1], v[64:65], 0, s[40:41]
	s_mov_b32 m0, s19
	s_mov_b64 s[40:41], 0x10080
	v_add_u32_e32 v84, 0xe000, v90
	global_load_lds_dwordx4 v[0:1], off
	v_lshl_add_u64 v[0:1], v[64:65], 0, s[40:41]
	v_readfirstlane_b32 s40, v85
	v_add_u32_e32 v82, 0xf000, v90
	s_mov_b32 m0, s40
	s_mov_b64 s[48:49], 0x20080
	v_readfirstlane_b32 s41, v84
	global_load_lds_dwordx4 v[0:1], off
	v_lshl_add_u64 v[0:1], v[64:65], 0, s[48:49]
	s_mov_b32 m0, s41
	s_mov_b64 s[48:49], 0x30080
	v_readfirstlane_b32 s42, v82
	global_load_lds_dwordx4 v[0:1], off
	v_lshl_add_u64 v[0:1], v[64:65], 0, s[48:49]
	s_mov_b32 m0, s42
	v_readlane_b32 s48, v219, 0
	global_load_lds_dwordx4 v[0:1], off
	ds_read_b128 v[0:3], v81 offset:32768
	ds_read_b128 v[16:19], v81 offset:36864
	ds_read_b128 v[4:7], v80
	s_waitcnt lgkmcnt(0)
; template <int EPI, int MI>
; DI void gemm_tile(const GemmDesc& g, int tm, int tn, char* smem) {
;     ...
;   const int rowA = wm * (32 * MI) + r, rowB = wn * 64 + r;
;   const int hk = hh ^ ((r & 7) ^ ((r >> 3) & 3));
;     ...
;   G_GLDS(0, 0);
;   asm volatile("s_waitcnt vmcnt(0)" ::: "memory");
;   __syncthreads();
;   for (int kt = 0; kt < nk; kt += 2) {
;     if (kt + 1 < nk) G_GLDS(kt + 1, 1);
;     G_COMPUTE(0);
;     asm volatile("s_waitcnt vmcnt(0)" ::: "memory");
;     __syncthreads();
;     if (kt + 1 < nk) {
;       if (kt + 2 < nk) G_GLDS(kt + 2, 0);
;       G_COMPUTE(1);
;       asm volatile("s_waitcnt vmcnt(0)" ::: "memory");
;       __syncthreads();
;     }
	v_mfma_f32_32x32x16_bf16 v[32:47], v[4:7], v[0:3], 0
	ds_read_b128 v[20:23], v80 offset:4096
	ds_read_b128 v[102:105], v79 offset:32768
	ds_read_b128 v[106:109], v79 offset:36864
	ds_read_b128 v[120:123], v78
	v_readlane_b32 s49, v219, 1
	s_mov_b32 m0, s43
	v_lshl_add_u32 v76, v76, 11, 0
	v_lshlrev_b32_e32 v75, 14, v75
	v_mfma_f32_32x32x16_bf16 v[48:63], v[4:7], v[16:19], 0
	s_waitcnt lgkmcnt(0)
	v_mfma_f32_32x32x16_bf16 v[32:47], v[120:123], v[102:105], v[32:47]
	v_mfma_f32_32x32x16_bf16 v[48:63], v[120:123], v[106:109], v[48:63]
	ds_read_b128 v[120:123], v78 offset:4096
	v_mfma_f32_32x32x16_bf16 v[0:15], v[20:23], v[0:3], 0
	v_mfma_f32_32x32x16_bf16 v[16:31], v[20:23], v[16:19], 0
	s_waitcnt lgkmcnt(0)
	v_mfma_f32_32x32x16_bf16 v[0:15], v[120:123], v[102:105], v[0:15]
	v_mfma_f32_32x32x16_bf16 v[16:31], v[120:123], v[106:109], v[16:31]
	ds_read_b128 v[102:105], v77 offset:32768
	ds_read_b128 v[106:109], v77 offset:36864
	ds_read_b128 v[120:123], v72
	s_waitcnt lgkmcnt(0)
	v_mfma_f32_32x32x16_bf16 v[32:47], v[120:123], v[102:105], v[32:47]
	v_mfma_f32_32x32x16_bf16 v[48:63], v[120:123], v[106:109], v[48:63]
	ds_read_b128 v[120:123], v72 offset:4096
	s_waitcnt lgkmcnt(0)
	v_mfma_f32_32x32x16_bf16 v[0:15], v[120:123], v[102:105], v[0:15]
	v_mfma_f32_32x32x16_bf16 v[16:31], v[120:123], v[106:109], v[16:31]
	ds_read_b128 v[102:105], v71 offset:32768
	ds_read_b128 v[106:109], v71 offset:36864
	ds_read_b128 v[120:123], v70
	s_waitcnt lgkmcnt(0)
	v_mfma_f32_32x32x16_bf16 v[32:47], v[120:123], v[102:105], v[32:47]
	v_mfma_f32_32x32x16_bf16 v[48:63], v[120:123], v[106:109], v[48:63]
	ds_read_b128 v[120:123], v70 offset:4096
	s_waitcnt vmcnt(0)
	s_waitcnt vmcnt(0) lgkmcnt(0)
	s_barrier
	v_mfma_f32_32x32x16_bf16 v[0:15], v[120:123], v[102:105], v[0:15]
	v_lshl_add_u64 v[102:103], s[48:49], 0, v[66:67]
	v_lshl_add_u64 v[102:103], v[102:103], 0, v[68:69]
	global_load_lds_dwordx4 v[102:103], off
	v_lshl_add_u64 v[104:105], v[102:103], 0, s[72:73]
	s_mov_b32 m0, s44
	s_mov_b64 s[48:49], 0x10100
	global_load_lds_dwordx4 v[104:105], off
	v_lshl_add_u64 v[104:105], v[102:103], 0, s[52:53]
	s_mov_b32 m0, s45
	v_lshl_add_u64 v[102:103], v[102:103], 0, s[74:75]
	global_load_lds_dwordx4 v[104:105], off
	s_mov_b32 m0, s46
	v_mfma_f32_32x32x16_bf16 v[16:31], v[120:123], v[106:109], v[16:31]
	global_load_lds_dwordx4 v[102:103], off
	v_lshl_add_u64 v[102:103], v[64:65], 0, s[12:13]
	s_mov_b32 m0, s47
	s_nop 0
	global_load_lds_dwordx4 v[102:103], off
	v_lshl_add_u64 v[102:103], v[64:65], 0, s[48:49]
	s_mov_b32 m0, s39
	s_mov_b64 s[48:49], 0x20100
	global_load_lds_dwordx4 v[102:103], off
	v_lshl_add_u64 v[102:103], v[64:65], 0, s[48:49]
	s_mov_b32 m0, s5
	s_mov_b64 s[48:49], 0x30100
	global_load_lds_dwordx4 v[102:103], off
	v_lshl_add_u64 v[102:103], v[64:65], 0, s[48:49]
	s_mov_b32 m0, s4
	v_readlane_b32 s48, v219, 2
	global_load_lds_dwordx4 v[102:103], off
	ds_read_b128 v[102:105], v81 offset:49152
	ds_read_b128 v[106:109], v81 offset:53248
	ds_read_b128 v[120:123], v80 offset:16384
	s_waitcnt lgkmcnt(0)
	v_mfma_f32_32x32x16_bf16 v[32:47], v[120:123], v[102:105], v[32:47]
	v_readlane_b32 s49, v219, 3
	s_mov_b32 m0, s15
	v_mfma_f32_32x32x16_bf16 v[48:63], v[120:123], v[106:109], v[48:63]
	ds_read_b128 v[120:123], v80 offset:20480
	s_waitcnt lgkmcnt(0)
	v_mfma_f32_32x32x16_bf16 v[0:15], v[120:123], v[102:105], v[0:15]
	v_mfma_f32_32x32x16_bf16 v[16:31], v[120:123], v[106:109], v[16:31]
	ds_read_b128 v[102:105], v79 offset:49152
	ds_read_b128 v[106:109], v79 offset:53248
	ds_read_b128 v[120:123], v78 offset:16384
	s_waitcnt lgkmcnt(0)
	v_mfma_f32_32x32x16_bf16 v[32:47], v[120:123], v[102:105], v[32:47]
	v_mfma_f32_32x32x16_bf16 v[48:63], v[120:123], v[106:109], v[48:63]
	ds_read_b128 v[120:123], v78 offset:20480
	s_waitcnt lgkmcnt(0)
	v_mfma_f32_32x32x16_bf16 v[0:15], v[120:123], v[102:105], v[0:15]
	v_mfma_f32_32x32x16_bf16 v[16:31], v[120:123], v[106:109], v[16:31]
	ds_read_b128 v[102:105], v77 offset:49152
	ds_read_b128 v[106:109], v77 offset:53248
	ds_read_b128 v[120:123], v72 offset:16384
	s_waitcnt lgkmcnt(0)
	v_mfma_f32_32x32x16_bf16 v[32:47], v[120:123], v[102:105], v[32:47]
	v_mfma_f32_32x32x16_bf16 v[48:63], v[120:123], v[106:109], v[48:63]
	ds_read_b128 v[120:123], v72 offset:20480
	s_waitcnt lgkmcnt(0)
	v_mfma_f32_32x32x16_bf16 v[0:15], v[120:123], v[102:105], v[0:15]
	v_mfma_f32_32x32x16_bf16 v[16:31], v[120:123], v[106:109], v[16:31]
	ds_read_b128 v[102:105], v71 offset:49152
	ds_read_b128 v[106:109], v71 offset:53248
	ds_read_b128 v[120:123], v70 offset:16384
	s_waitcnt lgkmcnt(0)
	v_mfma_f32_32x32x16_bf16 v[32:47], v[120:123], v[102:105], v[32:47]
	v_mfma_f32_32x32x16_bf16 v[48:63], v[120:123], v[106:109], v[48:63]
	ds_read_b128 v[120:123], v70 offset:20480
	s_waitcnt vmcnt(0)
	s_waitcnt vmcnt(0) lgkmcnt(0)
	s_barrier
; template <int EPI, int MI>
; DI void gemm_tile(const GemmDesc& g, int tm, int tn, char* smem) {
;     ...
;   const int rowA = wm * (32 * MI) + r, rowB = wn * 64 + r;
;   const int hk = hh ^ ((r & 7) ^ ((r >> 3) & 3));
;     ...
;   G_GLDS(0, 0);
;   asm volatile("s_waitcnt vmcnt(0)" ::: "memory");
;   __syncthreads();
;   for (int kt = 0; kt < nk; kt += 2) {
;     if (kt + 1 < nk) G_GLDS(kt + 1, 1);
;     G_COMPUTE(0);
;     asm volatile("s_waitcnt vmcnt(0)" ::: "memory");
;     __syncthreads();
;     if (kt + 1 < nk) {
;       if (kt + 2 < nk) G_GLDS(kt + 2, 0);
;       G_COMPUTE(1);
;       asm volatile("s_waitcnt vmcnt(0)" ::: "memory");
;       __syncthreads();
;     }
	v_mfma_f32_32x32x16_bf16 v[0:15], v[120:123], v[102:105], v[0:15]
	v_lshl_add_u64 v[102:103], s[48:49], 0, v[66:67]
	v_lshl_add_u64 v[102:103], v[102:103], 0, v[68:69]
	global_load_lds_dwordx4 v[102:103], off
	v_lshl_add_u64 v[104:105], v[102:103], 0, s[72:73]
	s_mov_b32 m0, s16
	s_mov_b64 s[48:49], 0x180
	global_load_lds_dwordx4 v[104:105], off
	v_lshl_add_u64 v[104:105], v[102:103], 0, s[52:53]
	s_mov_b32 m0, s17
	v_lshl_add_u64 v[102:103], v[102:103], 0, s[74:75]
	global_load_lds_dwordx4 v[104:105], off
	s_mov_b32 m0, s18
	v_mfma_f32_32x32x16_bf16 v[16:31], v[120:123], v[106:109], v[16:31]
	global_load_lds_dwordx4 v[102:103], off
	v_lshl_add_u64 v[102:103], v[64:65], 0, s[48:49]
	s_mov_b32 m0, s19
	s_mov_b64 s[48:49], 0x10180
	global_load_lds_dwordx4 v[102:103], off
	v_lshl_add_u64 v[102:103], v[64:65], 0, s[48:49]
	s_mov_b32 m0, s40
	s_mov_b64 s[48:49], 0x20180
	global_load_lds_dwordx4 v[102:103], off
	v_lshl_add_u64 v[102:103], v[64:65], 0, s[48:49]
	s_mov_b32 m0, s41
	s_mov_b64 s[48:49], 0x30180
	global_load_lds_dwordx4 v[102:103], off
	v_lshl_add_u64 v[102:103], v[64:65], 0, s[48:49]
	s_mov_b32 m0, s42
	v_readlane_b32 s48, v219, 4
	global_load_lds_dwordx4 v[102:103], off
	ds_read_b128 v[102:105], v81 offset:32768
	ds_read_b128 v[106:109], v81 offset:36864
	ds_read_b128 v[120:123], v80
	s_waitcnt lgkmcnt(0)
	v_mfma_f32_32x32x16_bf16 v[32:47], v[120:123], v[102:105], v[32:47]
	v_readlane_b32 s49, v219, 5
	s_mov_b32 m0, s43
	v_mfma_f32_32x32x16_bf16 v[48:63], v[120:123], v[106:109], v[48:63]
	ds_read_b128 v[120:123], v80 offset:4096
	s_waitcnt lgkmcnt(0)
	v_mfma_f32_32x32x16_bf16 v[0:15], v[120:123], v[102:105], v[0:15]
	v_mfma_f32_32x32x16_bf16 v[16:31], v[120:123], v[106:109], v[16:31]
	ds_read_b128 v[102:105], v79 offset:32768
	ds_read_b128 v[106:109], v79 offset:36864
	ds_read_b128 v[120:123], v78
	s_waitcnt lgkmcnt(0)
	v_mfma_f32_32x32x16_bf16 v[32:47], v[120:123], v[102:105], v[32:47]
	v_mfma_f32_32x32x16_bf16 v[48:63], v[120:123], v[106:109], v[48:63]
	ds_read_b128 v[120:123], v78 offset:4096
	s_waitcnt lgkmcnt(0)
	v_mfma_f32_32x32x16_bf16 v[0:15], v[120:123], v[102:105], v[0:15]
	v_mfma_f32_32x32x16_bf16 v[16:31], v[120:123], v[106:109], v[16:31]
	ds_read_b128 v[102:105], v77 offset:32768
	ds_read_b128 v[106:109], v77 offset:36864
	ds_read_b128 v[120:123], v72
	s_waitcnt lgkmcnt(0)
	v_mfma_f32_32x32x16_bf16 v[32:47], v[120:123], v[102:105], v[32:47]
	v_mfma_f32_32x32x16_bf16 v[48:63], v[120:123], v[106:109], v[48:63]
	ds_read_b128 v[120:123], v72 offset:4096
	s_waitcnt lgkmcnt(0)
	v_mfma_f32_32x32x16_bf16 v[0:15], v[120:123], v[102:105], v[0:15]
	v_mfma_f32_32x32x16_bf16 v[16:31], v[120:123], v[106:109], v[16:31]
	ds_read_b128 v[102:105], v71 offset:32768
	ds_read_b128 v[106:109], v71 offset:36864
	ds_read_b128 v[120:123], v70
	s_waitcnt lgkmcnt(0)
	v_mfma_f32_32x32x16_bf16 v[32:47], v[120:123], v[102:105], v[32:47]
	v_mfma_f32_32x32x16_bf16 v[48:63], v[120:123], v[106:109], v[48:63]
	ds_read_b128 v[120:123], v70 offset:4096
	s_waitcnt vmcnt(0)
	s_waitcnt vmcnt(0) lgkmcnt(0)
	s_barrier
	v_mfma_f32_32x32x16_bf16 v[0:15], v[120:123], v[102:105], v[0:15]
	v_lshl_add_u64 v[102:103], s[48:49], 0, v[66:67]
	v_lshl_add_u64 v[102:103], v[102:103], 0, v[68:69]
	global_load_lds_dwordx4 v[102:103], off
	v_lshl_add_u64 v[104:105], v[102:103], 0, s[72:73]
	s_mov_b32 m0, s44
	s_mov_b64 s[48:49], 0x200
	global_load_lds_dwordx4 v[104:105], off
	v_lshl_add_u64 v[104:105], v[102:103], 0, s[52:53]
	s_mov_b32 m0, s45
	v_lshl_add_u64 v[102:103], v[102:103], 0, s[74:75]
	global_load_lds_dwordx4 v[104:105], off
	s_mov_b32 m0, s46
	v_mfma_f32_32x32x16_bf16 v[16:31], v[120:123], v[106:109], v[16:31]
	global_load_lds_dwordx4 v[102:103], off
	v_lshl_add_u64 v[102:103], v[64:65], 0, s[48:49]
	s_mov_b32 m0, s47
	s_mov_b64 s[48:49], 0x10200
	global_load_lds_dwordx4 v[102:103], off
	v_lshl_add_u64 v[102:103], v[64:65], 0, s[48:49]
	s_mov_b32 m0, s39
	s_mov_b64 s[48:49], 0x20200
	global_load_lds_dwordx4 v[102:103], off
	v_lshl_add_u64 v[102:103], v[64:65], 0, s[48:49]
	s_mov_b32 m0, s5
	s_mov_b64 s[48:49], 0x30200
	global_load_lds_dwordx4 v[102:103], off
	v_lshl_add_u64 v[102:103], v[64:65], 0, s[48:49]
	s_mov_b32 m0, s4
	v_readlane_b32 s48, v219, 6
	global_load_lds_dwordx4 v[102:103], off
	ds_read_b128 v[102:105], v81 offset:49152
	ds_read_b128 v[106:109], v81 offset:53248
	ds_read_b128 v[120:123], v80 offset:16384
	s_waitcnt lgkmcnt(0)
	v_mfma_f32_32x32x16_bf16 v[32:47], v[120:123], v[102:105], v[32:47]
	v_readlane_b32 s49, v219, 7
	s_mov_b32 m0, s15
	v_mfma_f32_32x32x16_bf16 v[48:63], v[120:123], v[106:109], v[48:63]
	ds_read_b128 v[120:123], v80 offset:20480
	s_waitcnt lgkmcnt(0)
	v_mfma_f32_32x32x16_bf16 v[0:15], v[120:123], v[102:105], v[0:15]
	v_mfma_f32_32x32x16_bf16 v[16:31], v[120:123], v[106:109], v[16:31]
	ds_read_b128 v[102:105], v79 offset:49152
	ds_read_b128 v[106:109], v79 offset:53248
	ds_read_b128 v[120:123], v78 offset:16384
	s_waitcnt lgkmcnt(0)
	v_mfma_f32_32x32x16_bf16 v[32:47], v[120:123], v[102:105], v[32:47]
	v_mfma_f32_32x32x16_bf16 v[48:63], v[120:123], v[106:109], v[48:63]
	ds_read_b128 v[120:123], v78 offset:20480
	s_waitcnt lgkmcnt(0)
	v_mfma_f32_32x32x16_bf16 v[0:15], v[120:123], v[102:105], v[0:15]
	v_mfma_f32_32x32x16_bf16 v[16:31], v[120:123], v[106:109], v[16:31]
	ds_read_b128 v[102:105], v77 offset:49152
	ds_read_b128 v[106:109], v77 offset:53248
	ds_read_b128 v[120:123], v72 offset:16384
	s_waitcnt lgkmcnt(0)
	v_mfma_f32_32x32x16_bf16 v[32:47], v[120:123], v[102:105], v[32:47]
	v_mfma_f32_32x32x16_bf16 v[48:63], v[120:123], v[106:109], v[48:63]
	ds_read_b128 v[120:123], v72 offset:20480
	s_waitcnt lgkmcnt(0)
	v_mfma_f32_32x32x16_bf16 v[0:15], v[120:123], v[102:105], v[0:15]
	v_mfma_f32_32x32x16_bf16 v[16:31], v[120:123], v[106:109], v[16:31]
	ds_read_b128 v[102:105], v71 offset:49152
	ds_read_b128 v[106:109], v71 offset:53248
	ds_read_b128 v[120:123], v70 offset:16384
	s_waitcnt lgkmcnt(0)
	v_mfma_f32_32x32x16_bf16 v[32:47], v[120:123], v[102:105], v[32:47]
	v_mfma_f32_32x32x16_bf16 v[48:63], v[120:123], v[106:109], v[48:63]
	ds_read_b128 v[120:123], v70 offset:20480
	s_waitcnt vmcnt(0)
	s_waitcnt vmcnt(0) lgkmcnt(0)
	s_barrier
; template <int EPI, int MI>
; DI void gemm_tile(const GemmDesc& g, int tm, int tn, char* smem) {
;     ...
;   const int rowA = wm * (32 * MI) + r, rowB = wn * 64 + r;
;   const int hk = hh ^ ((r & 7) ^ ((r >> 3) & 3));
;     ...
;   G_GLDS(0, 0);
;   asm volatile("s_waitcnt vmcnt(0)" ::: "memory");
;   __syncthreads();
;   for (int kt = 0; kt < nk; kt += 2) {
;     if (kt + 1 < nk) G_GLDS(kt + 1, 1);
;     G_COMPUTE(0);
;     asm volatile("s_waitcnt vmcnt(0)" ::: "memory");
;     __syncthreads();
;     if (kt + 1 < nk) {
;       if (kt + 2 < nk) G_GLDS(kt + 2, 0);
;       G_COMPUTE(1);
;       asm volatile("s_waitcnt vmcnt(0)" ::: "memory");
;       __syncthreads();
;     }
	v_mfma_f32_32x32x16_bf16 v[0:15], v[120:123], v[102:105], v[0:15]
	v_lshl_add_u64 v[102:103], s[48:49], 0, v[66:67]
	v_lshl_add_u64 v[102:103], v[102:103], 0, v[68:69]
	global_load_lds_dwordx4 v[102:103], off
	v_lshl_add_u64 v[104:105], v[102:103], 0, s[72:73]
	s_mov_b32 m0, s16
	s_mov_b64 s[48:49], 0x280
	global_load_lds_dwordx4 v[104:105], off
	v_lshl_add_u64 v[104:105], v[102:103], 0, s[52:53]
	s_mov_b32 m0, s17
	v_lshl_add_u64 v[102:103], v[102:103], 0, s[74:75]
	global_load_lds_dwordx4 v[104:105], off
	s_mov_b32 m0, s18
	v_mfma_f32_32x32x16_bf16 v[16:31], v[120:123], v[106:109], v[16:31]
	global_load_lds_dwordx4 v[102:103], off
	v_lshl_add_u64 v[102:103], v[64:65], 0, s[48:49]
	s_mov_b32 m0, s19
	s_mov_b64 s[48:49], 0x10280
	global_load_lds_dwordx4 v[102:103], off
	v_lshl_add_u64 v[102:103], v[64:65], 0, s[48:49]
	s_mov_b32 m0, s40
	s_mov_b64 s[48:49], 0x20280
	global_load_lds_dwordx4 v[102:103], off
	v_lshl_add_u64 v[102:103], v[64:65], 0, s[48:49]
	s_mov_b32 m0, s41
	s_mov_b64 s[48:49], 0x30280
	global_load_lds_dwordx4 v[102:103], off
	v_lshl_add_u64 v[102:103], v[64:65], 0, s[48:49]
	s_mov_b32 m0, s42
	v_readlane_b32 s48, v219, 8
	global_load_lds_dwordx4 v[102:103], off
	ds_read_b128 v[102:105], v81 offset:32768
	ds_read_b128 v[106:109], v81 offset:36864
	ds_read_b128 v[120:123], v80
	s_waitcnt lgkmcnt(0)
	v_mfma_f32_32x32x16_bf16 v[32:47], v[120:123], v[102:105], v[32:47]
	v_readlane_b32 s49, v219, 9
	s_mov_b32 m0, s43
	v_readfirstlane_b32 s43, v94
	v_mfma_f32_32x32x16_bf16 v[48:63], v[120:123], v[106:109], v[48:63]
	ds_read_b128 v[120:123], v80 offset:4096
	s_waitcnt lgkmcnt(0)
	v_mfma_f32_32x32x16_bf16 v[0:15], v[120:123], v[102:105], v[0:15]
	v_mfma_f32_32x32x16_bf16 v[16:31], v[120:123], v[106:109], v[16:31]
	ds_read_b128 v[102:105], v79 offset:32768
	ds_read_b128 v[106:109], v79 offset:36864
	ds_read_b128 v[120:123], v78
	s_waitcnt lgkmcnt(0)
	v_mfma_f32_32x32x16_bf16 v[32:47], v[120:123], v[102:105], v[32:47]
	v_mfma_f32_32x32x16_bf16 v[48:63], v[120:123], v[106:109], v[48:63]
	ds_read_b128 v[120:123], v78 offset:4096
	s_waitcnt lgkmcnt(0)
	v_mfma_f32_32x32x16_bf16 v[0:15], v[120:123], v[102:105], v[0:15]
	v_mfma_f32_32x32x16_bf16 v[16:31], v[120:123], v[106:109], v[16:31]
	ds_read_b128 v[102:105], v77 offset:32768
	ds_read_b128 v[106:109], v77 offset:36864
	ds_read_b128 v[120:123], v72
	s_waitcnt lgkmcnt(0)
	v_mfma_f32_32x32x16_bf16 v[32:47], v[120:123], v[102:105], v[32:47]
	v_mfma_f32_32x32x16_bf16 v[48:63], v[120:123], v[106:109], v[48:63]
	ds_read_b128 v[120:123], v72 offset:4096
	s_waitcnt lgkmcnt(0)
	v_mfma_f32_32x32x16_bf16 v[0:15], v[120:123], v[102:105], v[0:15]
	v_mfma_f32_32x32x16_bf16 v[16:31], v[120:123], v[106:109], v[16:31]
	ds_read_b128 v[102:105], v71 offset:32768
	ds_read_b128 v[106:109], v71 offset:36864
	ds_read_b128 v[120:123], v70
	s_waitcnt lgkmcnt(0)
	v_mfma_f32_32x32x16_bf16 v[32:47], v[120:123], v[102:105], v[32:47]
	v_mfma_f32_32x32x16_bf16 v[48:63], v[120:123], v[106:109], v[48:63]
	ds_read_b128 v[120:123], v70 offset:4096
	s_waitcnt vmcnt(0)
	s_waitcnt vmcnt(0) lgkmcnt(0)
	s_barrier
	v_mfma_f32_32x32x16_bf16 v[0:15], v[120:123], v[102:105], v[0:15]
	v_lshl_add_u64 v[102:103], s[48:49], 0, v[66:67]
	v_lshl_add_u64 v[102:103], v[102:103], 0, v[68:69]
	global_load_lds_dwordx4 v[102:103], off
	v_lshl_add_u64 v[104:105], v[102:103], 0, s[72:73]
	s_mov_b32 m0, s44
	s_mov_b64 s[48:49], 0x20480
	global_load_lds_dwordx4 v[104:105], off
	v_lshl_add_u64 v[104:105], v[102:103], 0, s[52:53]
	s_mov_b32 m0, s45
	v_lshl_add_u64 v[102:103], v[102:103], 0, s[74:75]
	global_load_lds_dwordx4 v[104:105], off
	s_mov_b32 m0, s46
	s_mov_b64 s[44:45], 0x300
	global_load_lds_dwordx4 v[102:103], off
	v_lshl_add_u64 v[102:103], v[64:65], 0, s[44:45]
	s_mov_b32 m0, s47
	s_mov_b64 s[44:45], 0x10300
	global_load_lds_dwordx4 v[102:103], off
	v_lshl_add_u64 v[102:103], v[64:65], 0, s[44:45]
	s_mov_b32 m0, s39
	s_mov_b64 s[44:45], 0x20300
	global_load_lds_dwordx4 v[102:103], off
	v_lshl_add_u64 v[102:103], v[64:65], 0, s[44:45]
	s_mov_b32 m0, s5
	s_mov_b64 s[44:45], 0x30300
	global_load_lds_dwordx4 v[102:103], off
	v_lshl_add_u64 v[102:103], v[64:65], 0, s[44:45]
	s_mov_b32 m0, s4
	v_mfma_f32_32x32x16_bf16 v[16:31], v[120:123], v[106:109], v[16:31]
	global_load_lds_dwordx4 v[102:103], off
	ds_read_b128 v[102:105], v81 offset:49152
	ds_read_b128 v[106:109], v81 offset:53248
	ds_read_b128 v[120:123], v80 offset:16384
	v_readlane_b32 s44, v219, 10
	v_readlane_b32 s45, v219, 11
	s_mov_b32 m0, s15
	v_readfirstlane_b32 s46, v92
	s_waitcnt lgkmcnt(0)
	v_mfma_f32_32x32x16_bf16 v[32:47], v[120:123], v[102:105], v[32:47]
	v_readfirstlane_b32 s47, v93
	v_readfirstlane_b32 s15, v86
	v_mfma_f32_32x32x16_bf16 v[48:63], v[120:123], v[106:109], v[48:63]
	ds_read_b128 v[120:123], v80 offset:20480
	s_waitcnt lgkmcnt(0)
	v_mfma_f32_32x32x16_bf16 v[0:15], v[120:123], v[102:105], v[0:15]
	v_mfma_f32_32x32x16_bf16 v[16:31], v[120:123], v[106:109], v[16:31]
	ds_read_b128 v[102:105], v79 offset:49152
	ds_read_b128 v[106:109], v79 offset:53248
	ds_read_b128 v[120:123], v78 offset:16384
	s_waitcnt lgkmcnt(0)
	v_mfma_f32_32x32x16_bf16 v[32:47], v[120:123], v[102:105], v[32:47]
	v_mfma_f32_32x32x16_bf16 v[48:63], v[120:123], v[106:109], v[48:63]
	ds_read_b128 v[120:123], v78 offset:20480
	s_waitcnt lgkmcnt(0)
	v_mfma_f32_32x32x16_bf16 v[0:15], v[120:123], v[102:105], v[0:15]
	v_mfma_f32_32x32x16_bf16 v[16:31], v[120:123], v[106:109], v[16:31]
	ds_read_b128 v[102:105], v77 offset:49152
	ds_read_b128 v[106:109], v77 offset:53248
	ds_read_b128 v[120:123], v72 offset:16384
	s_waitcnt lgkmcnt(0)
	v_mfma_f32_32x32x16_bf16 v[32:47], v[120:123], v[102:105], v[32:47]
	v_mfma_f32_32x32x16_bf16 v[48:63], v[120:123], v[106:109], v[48:63]
	ds_read_b128 v[120:123], v72 offset:20480
	s_waitcnt lgkmcnt(0)
	v_mfma_f32_32x32x16_bf16 v[0:15], v[120:123], v[102:105], v[0:15]
	v_mfma_f32_32x32x16_bf16 v[16:31], v[120:123], v[106:109], v[16:31]
	ds_read_b128 v[102:105], v71 offset:49152
	ds_read_b128 v[106:109], v71 offset:53248
	ds_read_b128 v[120:123], v70 offset:16384
	s_waitcnt lgkmcnt(0)
	v_mfma_f32_32x32x16_bf16 v[32:47], v[120:123], v[102:105], v[32:47]
	v_mfma_f32_32x32x16_bf16 v[48:63], v[120:123], v[106:109], v[48:63]
	ds_read_b128 v[120:123], v70 offset:20480
	s_waitcnt vmcnt(0)
	s_waitcnt vmcnt(0) lgkmcnt(0)
	s_barrier
; template <int EPI, int MI>
; DI void gemm_tile(const GemmDesc& g, int tm, int tn, char* smem) {
;     ...
;   const int rowA = wm * (32 * MI) + r, rowB = wn * 64 + r;
;   const int hk = hh ^ ((r & 7) ^ ((r >> 3) & 3));
;     ...
;   G_GLDS(0, 0);
;   asm volatile("s_waitcnt vmcnt(0)" ::: "memory");
;   __syncthreads();
;   for (int kt = 0; kt < nk; kt += 2) {
;     if (kt + 1 < nk) G_GLDS(kt + 1, 1);
;     G_COMPUTE(0);
;     asm volatile("s_waitcnt vmcnt(0)" ::: "memory");
;     __syncthreads();
;     if (kt + 1 < nk) {
;       if (kt + 2 < nk) G_GLDS(kt + 2, 0);
;       G_COMPUTE(1);
;       asm volatile("s_waitcnt vmcnt(0)" ::: "memory");
;       __syncthreads();
;     }
	v_mfma_f32_32x32x16_bf16 v[0:15], v[120:123], v[102:105], v[0:15]
	v_lshl_add_u64 v[102:103], s[44:45], 0, v[66:67]
	v_lshl_add_u64 v[102:103], v[102:103], 0, v[68:69]
	global_load_lds_dwordx4 v[102:103], off
	v_lshl_add_u64 v[104:105], v[102:103], 0, s[72:73]
	s_mov_b32 m0, s16
	v_readfirstlane_b32 s44, v90
	global_load_lds_dwordx4 v[104:105], off
	v_lshl_add_u64 v[104:105], v[102:103], 0, s[52:53]
	s_mov_b32 m0, s17
	v_lshl_add_u64 v[102:103], v[102:103], 0, s[74:75]
	global_load_lds_dwordx4 v[104:105], off
	s_mov_b32 m0, s18
	s_mov_b64 s[16:17], 0x380
	global_load_lds_dwordx4 v[102:103], off
	v_lshl_add_u64 v[102:103], v[64:65], 0, s[16:17]
	s_mov_b32 m0, s19
	s_mov_b64 s[16:17], 0x10380
	global_load_lds_dwordx4 v[102:103], off
	v_lshl_add_u64 v[102:103], v[64:65], 0, s[16:17]
	s_mov_b32 m0, s40
	s_mov_b64 s[16:17], 0x20380
	global_load_lds_dwordx4 v[102:103], off
	v_lshl_add_u64 v[102:103], v[64:65], 0, s[16:17]
	s_mov_b32 m0, s41
	s_mov_b64 s[16:17], 0x30380
	global_load_lds_dwordx4 v[102:103], off
	v_lshl_add_u64 v[102:103], v[64:65], 0, s[16:17]
	s_mov_b32 m0, s42
	v_mfma_f32_32x32x16_bf16 v[16:31], v[120:123], v[106:109], v[16:31]
	global_load_lds_dwordx4 v[102:103], off
	ds_read_b128 v[102:105], v81 offset:32768
	ds_read_b128 v[106:109], v81 offset:36864
	ds_read_b128 v[120:123], v80
	v_readlane_b32 s16, v223, 59
	v_readlane_b32 s17, v223, 60
	s_mov_b32 m0, s44
	v_readfirstlane_b32 s45, v91
	s_waitcnt lgkmcnt(0)
	v_mfma_f32_32x32x16_bf16 v[32:47], v[120:123], v[102:105], v[32:47]
	v_readfirstlane_b32 s18, v87
	s_mov_b64 s[40:41], 0x480
	v_readfirstlane_b32 s19, v83
	v_lshl_add_u64 v[86:87], v[64:65], 0, s[40:41]
	s_mov_b64 s[40:41], 0x10480
	v_readfirstlane_b32 s42, v82
	v_mfma_f32_32x32x16_bf16 v[48:63], v[120:123], v[106:109], v[48:63]
	ds_read_b128 v[120:123], v80 offset:4096
	s_waitcnt lgkmcnt(0)
	v_mfma_f32_32x32x16_bf16 v[0:15], v[120:123], v[102:105], v[0:15]
	v_mfma_f32_32x32x16_bf16 v[16:31], v[120:123], v[106:109], v[16:31]
	ds_read_b128 v[102:105], v79 offset:32768
	ds_read_b128 v[106:109], v79 offset:36864
	ds_read_b128 v[120:123], v78
	s_waitcnt lgkmcnt(0)
	v_mfma_f32_32x32x16_bf16 v[32:47], v[120:123], v[102:105], v[32:47]
	v_mfma_f32_32x32x16_bf16 v[48:63], v[120:123], v[106:109], v[48:63]
	ds_read_b128 v[120:123], v78 offset:4096
	s_waitcnt lgkmcnt(0)
	v_mfma_f32_32x32x16_bf16 v[0:15], v[120:123], v[102:105], v[0:15]
	v_mfma_f32_32x32x16_bf16 v[16:31], v[120:123], v[106:109], v[16:31]
	ds_read_b128 v[102:105], v77 offset:32768
	ds_read_b128 v[106:109], v77 offset:36864
	ds_read_b128 v[120:123], v72
	s_waitcnt lgkmcnt(0)
	v_mfma_f32_32x32x16_bf16 v[32:47], v[120:123], v[102:105], v[32:47]
	v_mfma_f32_32x32x16_bf16 v[48:63], v[120:123], v[106:109], v[48:63]
	ds_read_b128 v[120:123], v72 offset:4096
	s_waitcnt lgkmcnt(0)
	v_mfma_f32_32x32x16_bf16 v[0:15], v[120:123], v[102:105], v[0:15]
	v_mfma_f32_32x32x16_bf16 v[16:31], v[120:123], v[106:109], v[16:31]
	ds_read_b128 v[102:105], v71 offset:32768
	ds_read_b128 v[106:109], v71 offset:36864
	ds_read_b128 v[120:123], v70
	s_waitcnt lgkmcnt(0)
	v_mfma_f32_32x32x16_bf16 v[32:47], v[120:123], v[102:105], v[32:47]
	v_mfma_f32_32x32x16_bf16 v[48:63], v[120:123], v[106:109], v[48:63]
	ds_read_b128 v[120:123], v70 offset:4096
	s_waitcnt vmcnt(0)
	s_waitcnt vmcnt(0) lgkmcnt(0)
	s_barrier
	v_mfma_f32_32x32x16_bf16 v[0:15], v[120:123], v[102:105], v[0:15]
	v_lshl_add_u64 v[102:103], s[16:17], 0, v[66:67]
	v_lshl_add_u64 v[102:103], v[102:103], 0, v[68:69]
	global_load_lds_dwordx4 v[102:103], off
	v_lshl_add_u64 v[104:105], v[102:103], 0, s[72:73]
	s_mov_b32 m0, s45
	v_lshl_add_u64 v[90:91], v[102:103], 0, s[52:53]
	global_load_lds_dwordx4 v[104:105], off
	s_mov_b32 m0, s46
	s_mov_b64 s[16:17], 0x400
	global_load_lds_dwordx4 v[90:91], off
	v_lshl_add_u64 v[90:91], v[102:103], 0, s[74:75]
	s_mov_b32 m0, s47
	v_mfma_f32_32x32x16_bf16 v[16:31], v[120:123], v[106:109], v[16:31]
	global_load_lds_dwordx4 v[90:91], off
	v_lshl_add_u64 v[90:91], v[64:65], 0, s[16:17]
	s_mov_b32 m0, s43
	s_mov_b64 s[16:17], 0x10400
	global_load_lds_dwordx4 v[90:91], off
	v_lshl_add_u64 v[90:91], v[64:65], 0, s[16:17]
	s_mov_b32 m0, s39
	s_mov_b64 s[16:17], 0x20400
	global_load_lds_dwordx4 v[90:91], off
	v_lshl_add_u64 v[90:91], v[64:65], 0, s[16:17]
	s_mov_b32 m0, s5
	s_mov_b64 s[16:17], 0x30400
	global_load_lds_dwordx4 v[90:91], off
	v_lshl_add_u64 v[90:91], v[64:65], 0, s[16:17]
	s_mov_b32 m0, s4
	v_readlane_b32 s16, v219, 24
	global_load_lds_dwordx4 v[90:91], off
	ds_read_b128 v[90:93], v81 offset:49152
	ds_read_b128 v[102:105], v81 offset:53248
	ds_read_b128 v[106:109], v80 offset:16384
	s_waitcnt lgkmcnt(0)
	v_mfma_f32_32x32x16_bf16 v[32:47], v[106:109], v[90:93], v[32:47]
	v_readlane_b32 s17, v219, 25
	s_mov_b32 m0, s15
	v_mfma_f32_32x32x16_bf16 v[48:63], v[106:109], v[102:105], v[48:63]
	ds_read_b128 v[106:109], v80 offset:20480
	s_waitcnt lgkmcnt(0)
	v_mfma_f32_32x32x16_bf16 v[0:15], v[106:109], v[90:93], v[0:15]
	v_mfma_f32_32x32x16_bf16 v[16:31], v[106:109], v[102:105], v[16:31]
	ds_read_b128 v[90:93], v79 offset:49152
	ds_read_b128 v[102:105], v79 offset:53248
	ds_read_b128 v[106:109], v78 offset:16384
	s_waitcnt lgkmcnt(0)
	v_mfma_f32_32x32x16_bf16 v[32:47], v[106:109], v[90:93], v[32:47]
	v_mfma_f32_32x32x16_bf16 v[48:63], v[106:109], v[102:105], v[48:63]
	ds_read_b128 v[106:109], v78 offset:20480
	s_waitcnt lgkmcnt(0)
	v_mfma_f32_32x32x16_bf16 v[0:15], v[106:109], v[90:93], v[0:15]
	v_mfma_f32_32x32x16_bf16 v[16:31], v[106:109], v[102:105], v[16:31]
	ds_read_b128 v[90:93], v77 offset:49152
	ds_read_b128 v[102:105], v77 offset:53248
	ds_read_b128 v[106:109], v72 offset:16384
	s_waitcnt lgkmcnt(0)
	v_mfma_f32_32x32x16_bf16 v[32:47], v[106:109], v[90:93], v[32:47]
	v_mfma_f32_32x32x16_bf16 v[48:63], v[106:109], v[102:105], v[48:63]
	ds_read_b128 v[106:109], v72 offset:20480
	s_waitcnt lgkmcnt(0)
	v_mfma_f32_32x32x16_bf16 v[0:15], v[106:109], v[90:93], v[0:15]
	v_mfma_f32_32x32x16_bf16 v[16:31], v[106:109], v[102:105], v[16:31]
	ds_read_b128 v[90:93], v71 offset:49152
	ds_read_b128 v[102:105], v71 offset:53248
	ds_read_b128 v[106:109], v70 offset:16384
	s_waitcnt lgkmcnt(0)
	v_mfma_f32_32x32x16_bf16 v[32:47], v[106:109], v[90:93], v[32:47]
	v_mfma_f32_32x32x16_bf16 v[48:63], v[106:109], v[102:105], v[48:63]
	ds_read_b128 v[106:109], v70 offset:20480
	s_waitcnt vmcnt(0)
	s_waitcnt vmcnt(0) lgkmcnt(0)
	s_barrier
; template <int EPI, int MI>
; DI void gemm_tile(const GemmDesc& g, int tm, int tn, char* smem) {
;     ...
;   const int rowA = wm * (32 * MI) + r, rowB = wn * 64 + r;
;   const int hk = hh ^ ((r & 7) ^ ((r >> 3) & 3));
;     ...
;   G_GLDS(0, 0);
;   asm volatile("s_waitcnt vmcnt(0)" ::: "memory");
;   __syncthreads();
;   for (int kt = 0; kt < nk; kt += 2) {
;     if (kt + 1 < nk) G_GLDS(kt + 1, 1);
;     G_COMPUTE(0);
;     asm volatile("s_waitcnt vmcnt(0)" ::: "memory");
;     __syncthreads();
;     if (kt + 1 < nk) {
;       if (kt + 2 < nk) G_GLDS(kt + 2, 0);
;       G_COMPUTE(1);
;       asm volatile("s_waitcnt vmcnt(0)" ::: "memory");
;       __syncthreads();
;     }
	v_mfma_f32_32x32x16_bf16 v[0:15], v[106:109], v[90:93], v[0:15]
	v_lshl_add_u64 v[90:91], s[16:17], 0, v[66:67]
	v_lshl_add_u64 v[90:91], v[90:91], 0, v[68:69]
	v_readfirstlane_b32 s16, v89
	global_load_lds_dwordx4 v[90:91], off
	v_lshl_add_u64 v[92:93], v[90:91], 0, s[72:73]
	s_mov_b32 m0, s16
	v_readfirstlane_b32 s17, v88
	global_load_lds_dwordx4 v[92:93], off
	v_lshl_add_u64 v[92:93], v[90:91], 0, s[52:53]
	s_mov_b32 m0, s17
	v_lshl_add_u64 v[88:89], v[90:91], 0, s[74:75]
	global_load_lds_dwordx4 v[92:93], off
	s_mov_b32 m0, s18
	v_mfma_f32_32x32x16_bf16 v[16:31], v[106:109], v[102:105], v[16:31]
	global_load_lds_dwordx4 v[88:89], off
	s_mov_b32 m0, s19
	s_nop 0
	global_load_lds_dwordx4 v[86:87], off
	v_lshl_add_u64 v[86:87], v[64:65], 0, s[40:41]
	v_readfirstlane_b32 s40, v85
	s_mov_b32 m0, s40
	v_readfirstlane_b32 s41, v84
	global_load_lds_dwordx4 v[86:87], off
	v_lshl_add_u64 v[86:87], v[64:65], 0, s[48:49]
	s_mov_b32 m0, s41
	s_mov_b64 s[48:49], 0x30480
	global_load_lds_dwordx4 v[86:87], off
	v_lshl_add_u64 v[84:85], v[64:65], 0, s[48:49]
	s_mov_b32 m0, s42
	v_readlane_b32 s48, v219, 26
	global_load_lds_dwordx4 v[84:85], off
	ds_read_b128 v[82:85], v81 offset:32768
	ds_read_b128 v[86:89], v81 offset:36864
	ds_read_b128 v[90:93], v80
	s_waitcnt lgkmcnt(0)
	v_mfma_f32_32x32x16_bf16 v[32:47], v[90:93], v[82:85], v[32:47]
	v_readlane_b32 s49, v219, 27
	s_mov_b32 m0, s44
	v_mfma_f32_32x32x16_bf16 v[48:63], v[90:93], v[86:89], v[48:63]
	ds_read_b128 v[90:93], v80 offset:4096
	s_waitcnt lgkmcnt(0)
	v_mfma_f32_32x32x16_bf16 v[0:15], v[90:93], v[82:85], v[0:15]
	v_mfma_f32_32x32x16_bf16 v[16:31], v[90:93], v[86:89], v[16:31]
	ds_read_b128 v[82:85], v79 offset:32768
	ds_read_b128 v[86:89], v79 offset:36864
	ds_read_b128 v[90:93], v78
	s_waitcnt lgkmcnt(0)
	v_mfma_f32_32x32x16_bf16 v[32:47], v[90:93], v[82:85], v[32:47]
	v_mfma_f32_32x32x16_bf16 v[48:63], v[90:93], v[86:89], v[48:63]
	ds_read_b128 v[90:93], v78 offset:4096
	s_waitcnt lgkmcnt(0)
	v_mfma_f32_32x32x16_bf16 v[0:15], v[90:93], v[82:85], v[0:15]
	v_mfma_f32_32x32x16_bf16 v[16:31], v[90:93], v[86:89], v[16:31]
	ds_read_b128 v[82:85], v77 offset:32768
	ds_read_b128 v[86:89], v77 offset:36864
	ds_read_b128 v[90:93], v72
	s_waitcnt lgkmcnt(0)
	v_mfma_f32_32x32x16_bf16 v[32:47], v[90:93], v[82:85], v[32:47]
	v_mfma_f32_32x32x16_bf16 v[48:63], v[90:93], v[86:89], v[48:63]
	ds_read_b128 v[90:93], v72 offset:4096
	s_waitcnt lgkmcnt(0)
	v_mfma_f32_32x32x16_bf16 v[0:15], v[90:93], v[82:85], v[0:15]
	v_mfma_f32_32x32x16_bf16 v[16:31], v[90:93], v[86:89], v[16:31]
	ds_read_b128 v[82:85], v71 offset:32768
	ds_read_b128 v[86:89], v71 offset:36864
	ds_read_b128 v[90:93], v70
	s_waitcnt lgkmcnt(0)
	v_mfma_f32_32x32x16_bf16 v[32:47], v[90:93], v[82:85], v[32:47]
	v_mfma_f32_32x32x16_bf16 v[48:63], v[90:93], v[86:89], v[48:63]
	ds_read_b128 v[90:93], v70 offset:4096
	s_waitcnt vmcnt(0)
	s_waitcnt vmcnt(0) lgkmcnt(0)
	s_barrier
	v_mfma_f32_32x32x16_bf16 v[0:15], v[90:93], v[82:85], v[0:15]
	v_lshl_add_u64 v[82:83], s[48:49], 0, v[66:67]
	v_lshl_add_u64 v[82:83], v[82:83], 0, v[68:69]
	global_load_lds_dwordx4 v[82:83], off
	v_lshl_add_u64 v[84:85], v[82:83], 0, s[72:73]
	s_mov_b32 m0, s45
	s_mov_b64 s[48:49], 0x500
	global_load_lds_dwordx4 v[84:85], off
	v_lshl_add_u64 v[84:85], v[82:83], 0, s[52:53]
	s_mov_b32 m0, s46
	v_lshl_add_u64 v[82:83], v[82:83], 0, s[74:75]
	global_load_lds_dwordx4 v[84:85], off
	s_mov_b32 m0, s47
	v_mfma_f32_32x32x16_bf16 v[16:31], v[90:93], v[86:89], v[16:31]
	global_load_lds_dwordx4 v[82:83], off
	v_lshl_add_u64 v[82:83], v[64:65], 0, s[48:49]
	s_mov_b32 m0, s43
	s_mov_b64 s[48:49], 0x10500
	global_load_lds_dwordx4 v[82:83], off
	v_lshl_add_u64 v[82:83], v[64:65], 0, s[48:49]
	s_mov_b32 m0, s39
	s_mov_b64 s[48:49], 0x20500
	global_load_lds_dwordx4 v[82:83], off
	v_lshl_add_u64 v[82:83], v[64:65], 0, s[48:49]
	s_mov_b32 m0, s5
	s_mov_b64 s[48:49], 0x30500
	global_load_lds_dwordx4 v[82:83], off
	v_lshl_add_u64 v[82:83], v[64:65], 0, s[48:49]
	s_mov_b32 m0, s4
	v_readlane_b32 s48, v219, 28
	global_load_lds_dwordx4 v[82:83], off
	ds_read_b128 v[82:85], v81 offset:49152
	ds_read_b128 v[86:89], v81 offset:53248
	ds_read_b128 v[90:93], v80 offset:16384
	s_waitcnt lgkmcnt(0)
	v_mfma_f32_32x32x16_bf16 v[32:47], v[90:93], v[82:85], v[32:47]
	v_readlane_b32 s49, v219, 29
	s_mov_b32 m0, s15
	v_mfma_f32_32x32x16_bf16 v[48:63], v[90:93], v[86:89], v[48:63]
	ds_read_b128 v[90:93], v80 offset:20480
	s_waitcnt lgkmcnt(0)
	v_mfma_f32_32x32x16_bf16 v[0:15], v[90:93], v[82:85], v[0:15]
	v_mfma_f32_32x32x16_bf16 v[16:31], v[90:93], v[86:89], v[16:31]
	ds_read_b128 v[82:85], v79 offset:49152
	ds_read_b128 v[86:89], v79 offset:53248
	ds_read_b128 v[90:93], v78 offset:16384
	s_waitcnt lgkmcnt(0)
	v_mfma_f32_32x32x16_bf16 v[32:47], v[90:93], v[82:85], v[32:47]
	v_mfma_f32_32x32x16_bf16 v[48:63], v[90:93], v[86:89], v[48:63]
	ds_read_b128 v[90:93], v78 offset:20480
	s_waitcnt lgkmcnt(0)
	v_mfma_f32_32x32x16_bf16 v[0:15], v[90:93], v[82:85], v[0:15]
	v_mfma_f32_32x32x16_bf16 v[16:31], v[90:93], v[86:89], v[16:31]
	ds_read_b128 v[82:85], v77 offset:49152
	ds_read_b128 v[86:89], v77 offset:53248
	ds_read_b128 v[90:93], v72 offset:16384
	s_waitcnt lgkmcnt(0)
	v_mfma_f32_32x32x16_bf16 v[32:47], v[90:93], v[82:85], v[32:47]
	v_mfma_f32_32x32x16_bf16 v[48:63], v[90:93], v[86:89], v[48:63]
	ds_read_b128 v[90:93], v72 offset:20480
	s_waitcnt lgkmcnt(0)
	v_mfma_f32_32x32x16_bf16 v[0:15], v[90:93], v[82:85], v[0:15]
	v_mfma_f32_32x32x16_bf16 v[16:31], v[90:93], v[86:89], v[16:31]
	ds_read_b128 v[82:85], v71 offset:49152
	ds_read_b128 v[86:89], v71 offset:53248
	ds_read_b128 v[90:93], v70 offset:16384
	s_waitcnt lgkmcnt(0)
	v_mfma_f32_32x32x16_bf16 v[32:47], v[90:93], v[82:85], v[32:47]
	v_mfma_f32_32x32x16_bf16 v[48:63], v[90:93], v[86:89], v[48:63]
	ds_read_b128 v[90:93], v70 offset:20480
	s_waitcnt vmcnt(0)
	s_waitcnt vmcnt(0) lgkmcnt(0)
	s_barrier
; template <int EPI, int MI>
; DI void gemm_tile(const GemmDesc& g, int tm, int tn, char* smem) {
;     ...
;   const int rowA = wm * (32 * MI) + r, rowB = wn * 64 + r;
;   const int hk = hh ^ ((r & 7) ^ ((r >> 3) & 3));
;     ...
;   G_GLDS(0, 0);
;   asm volatile("s_waitcnt vmcnt(0)" ::: "memory");
;   __syncthreads();
;   for (int kt = 0; kt < nk; kt += 2) {
;     if (kt + 1 < nk) G_GLDS(kt + 1, 1);
;     G_COMPUTE(0);
;     asm volatile("s_waitcnt vmcnt(0)" ::: "memory");
;     __syncthreads();
;     if (kt + 1 < nk) {
;       if (kt + 2 < nk) G_GLDS(kt + 2, 0);
;       G_COMPUTE(1);
;       asm volatile("s_waitcnt vmcnt(0)" ::: "memory");
;       __syncthreads();
;     }
	v_mfma_f32_32x32x16_bf16 v[0:15], v[90:93], v[82:85], v[0:15]
	v_lshl_add_u64 v[82:83], s[48:49], 0, v[66:67]
	v_lshl_add_u64 v[82:83], v[82:83], 0, v[68:69]
	global_load_lds_dwordx4 v[82:83], off
	v_lshl_add_u64 v[84:85], v[82:83], 0, s[72:73]
	s_mov_b32 m0, s16
	s_mov_b64 s[48:49], 0x580
	global_load_lds_dwordx4 v[84:85], off
	v_lshl_add_u64 v[84:85], v[82:83], 0, s[52:53]
	s_mov_b32 m0, s17
	v_lshl_add_u64 v[82:83], v[82:83], 0, s[74:75]
	global_load_lds_dwordx4 v[84:85], off
	s_mov_b32 m0, s18
	v_mfma_f32_32x32x16_bf16 v[16:31], v[90:93], v[86:89], v[16:31]
	global_load_lds_dwordx4 v[82:83], off
	v_lshl_add_u64 v[82:83], v[64:65], 0, s[48:49]
	s_mov_b32 m0, s19
	s_mov_b64 s[48:49], 0x10580
	global_load_lds_dwordx4 v[82:83], off
	v_lshl_add_u64 v[82:83], v[64:65], 0, s[48:49]
	s_mov_b32 m0, s40
	s_mov_b64 s[48:49], 0x20580
	global_load_lds_dwordx4 v[82:83], off
	v_lshl_add_u64 v[82:83], v[64:65], 0, s[48:49]
	s_mov_b32 m0, s41
	s_mov_b64 s[48:49], 0x30580
	global_load_lds_dwordx4 v[82:83], off
	v_lshl_add_u64 v[82:83], v[64:65], 0, s[48:49]
	s_mov_b32 m0, s42
	v_readlane_b32 s48, v219, 30
	global_load_lds_dwordx4 v[82:83], off
	ds_read_b128 v[82:85], v81 offset:32768
	ds_read_b128 v[86:89], v81 offset:36864
	ds_read_b128 v[90:93], v80
	s_waitcnt lgkmcnt(0)
	v_mfma_f32_32x32x16_bf16 v[32:47], v[90:93], v[82:85], v[32:47]
	v_readlane_b32 s49, v219, 31
	s_mov_b32 m0, s44
	v_mfma_f32_32x32x16_bf16 v[48:63], v[90:93], v[86:89], v[48:63]
	ds_read_b128 v[90:93], v80 offset:4096
	s_waitcnt lgkmcnt(0)
	v_mfma_f32_32x32x16_bf16 v[0:15], v[90:93], v[82:85], v[0:15]
	v_mfma_f32_32x32x16_bf16 v[16:31], v[90:93], v[86:89], v[16:31]
	ds_read_b128 v[82:85], v79 offset:32768
	ds_read_b128 v[86:89], v79 offset:36864
	ds_read_b128 v[90:93], v78
	s_waitcnt lgkmcnt(0)
	v_mfma_f32_32x32x16_bf16 v[32:47], v[90:93], v[82:85], v[32:47]
	v_mfma_f32_32x32x16_bf16 v[48:63], v[90:93], v[86:89], v[48:63]
	ds_read_b128 v[90:93], v78 offset:4096
	s_waitcnt lgkmcnt(0)
	v_mfma_f32_32x32x16_bf16 v[0:15], v[90:93], v[82:85], v[0:15]
	v_mfma_f32_32x32x16_bf16 v[16:31], v[90:93], v[86:89], v[16:31]
	ds_read_b128 v[82:85], v77 offset:32768
	ds_read_b128 v[86:89], v77 offset:36864
	ds_read_b128 v[90:93], v72
	s_waitcnt lgkmcnt(0)
	v_mfma_f32_32x32x16_bf16 v[32:47], v[90:93], v[82:85], v[32:47]
	v_mfma_f32_32x32x16_bf16 v[48:63], v[90:93], v[86:89], v[48:63]
	ds_read_b128 v[90:93], v72 offset:4096
	s_waitcnt lgkmcnt(0)
	v_mfma_f32_32x32x16_bf16 v[0:15], v[90:93], v[82:85], v[0:15]
	v_mfma_f32_32x32x16_bf16 v[16:31], v[90:93], v[86:89], v[16:31]
	ds_read_b128 v[82:85], v71 offset:32768
	ds_read_b128 v[86:89], v71 offset:36864
	ds_read_b128 v[90:93], v70
	s_waitcnt lgkmcnt(0)
	v_mfma_f32_32x32x16_bf16 v[32:47], v[90:93], v[82:85], v[32:47]
	v_mfma_f32_32x32x16_bf16 v[48:63], v[90:93], v[86:89], v[48:63]
	ds_read_b128 v[90:93], v70 offset:4096
	s_waitcnt vmcnt(0)
	s_waitcnt vmcnt(0) lgkmcnt(0)
	s_barrier
	v_mfma_f32_32x32x16_bf16 v[0:15], v[90:93], v[82:85], v[0:15]
	v_lshl_add_u64 v[82:83], s[48:49], 0, v[66:67]
	v_lshl_add_u64 v[82:83], v[82:83], 0, v[68:69]
	global_load_lds_dwordx4 v[82:83], off
	v_lshl_add_u64 v[84:85], v[82:83], 0, s[72:73]
	s_mov_b32 m0, s45
	s_mov_b64 s[48:49], 0x600
	global_load_lds_dwordx4 v[84:85], off
	v_lshl_add_u64 v[84:85], v[82:83], 0, s[52:53]
	s_mov_b32 m0, s46
	v_lshl_add_u64 v[82:83], v[82:83], 0, s[74:75]
	global_load_lds_dwordx4 v[84:85], off
	s_mov_b32 m0, s47
	v_mfma_f32_32x32x16_bf16 v[16:31], v[90:93], v[86:89], v[16:31]
	global_load_lds_dwordx4 v[82:83], off
	v_lshl_add_u64 v[82:83], v[64:65], 0, s[48:49]
	s_mov_b32 m0, s43
	s_mov_b64 s[48:49], 0x10600
	global_load_lds_dwordx4 v[82:83], off
	v_lshl_add_u64 v[82:83], v[64:65], 0, s[48:49]
	s_mov_b32 m0, s39
	s_mov_b64 s[48:49], 0x20600
	global_load_lds_dwordx4 v[82:83], off
	v_lshl_add_u64 v[82:83], v[64:65], 0, s[48:49]
	s_mov_b32 m0, s5
	s_mov_b64 s[48:49], 0x30600
	global_load_lds_dwordx4 v[82:83], off
	v_lshl_add_u64 v[82:83], v[64:65], 0, s[48:49]
	s_mov_b32 m0, s4
	v_readlane_b32 s48, v219, 32
	global_load_lds_dwordx4 v[82:83], off
	ds_read_b128 v[82:85], v81 offset:49152
	ds_read_b128 v[86:89], v81 offset:53248
	ds_read_b128 v[90:93], v80 offset:16384
	s_waitcnt lgkmcnt(0)
	v_mfma_f32_32x32x16_bf16 v[32:47], v[90:93], v[82:85], v[32:47]
	v_readlane_b32 s49, v219, 33
	s_mov_b32 m0, s15
	v_mfma_f32_32x32x16_bf16 v[48:63], v[90:93], v[86:89], v[48:63]
	ds_read_b128 v[90:93], v80 offset:20480
	s_waitcnt lgkmcnt(0)
	v_mfma_f32_32x32x16_bf16 v[0:15], v[90:93], v[82:85], v[0:15]
	v_mfma_f32_32x32x16_bf16 v[16:31], v[90:93], v[86:89], v[16:31]
	ds_read_b128 v[82:85], v79 offset:49152
	ds_read_b128 v[86:89], v79 offset:53248
	ds_read_b128 v[90:93], v78 offset:16384
	s_waitcnt lgkmcnt(0)
	v_mfma_f32_32x32x16_bf16 v[32:47], v[90:93], v[82:85], v[32:47]
	v_mfma_f32_32x32x16_bf16 v[48:63], v[90:93], v[86:89], v[48:63]
	ds_read_b128 v[90:93], v78 offset:20480
	s_waitcnt lgkmcnt(0)
	v_mfma_f32_32x32x16_bf16 v[0:15], v[90:93], v[82:85], v[0:15]
	v_mfma_f32_32x32x16_bf16 v[16:31], v[90:93], v[86:89], v[16:31]
	ds_read_b128 v[82:85], v77 offset:49152
	ds_read_b128 v[86:89], v77 offset:53248
	ds_read_b128 v[90:93], v72 offset:16384
	s_waitcnt lgkmcnt(0)
	v_mfma_f32_32x32x16_bf16 v[32:47], v[90:93], v[82:85], v[32:47]
	v_mfma_f32_32x32x16_bf16 v[48:63], v[90:93], v[86:89], v[48:63]
	ds_read_b128 v[90:93], v72 offset:20480
	s_waitcnt lgkmcnt(0)
	v_mfma_f32_32x32x16_bf16 v[0:15], v[90:93], v[82:85], v[0:15]
	v_mfma_f32_32x32x16_bf16 v[16:31], v[90:93], v[86:89], v[16:31]
	ds_read_b128 v[82:85], v71 offset:49152
	ds_read_b128 v[86:89], v71 offset:53248
	ds_read_b128 v[90:93], v70 offset:16384
	s_waitcnt lgkmcnt(0)
	v_mfma_f32_32x32x16_bf16 v[32:47], v[90:93], v[82:85], v[32:47]
	v_mfma_f32_32x32x16_bf16 v[48:63], v[90:93], v[86:89], v[48:63]
	ds_read_b128 v[90:93], v70 offset:20480
	s_waitcnt vmcnt(0)
	s_waitcnt vmcnt(0) lgkmcnt(0)
	s_barrier
; template <int EPI, int MI>
; DI void gemm_tile(const GemmDesc& g, int tm, int tn, char* smem) {
;     ...
;   const int rowA = wm * (32 * MI) + r, rowB = wn * 64 + r;
;   const int hk = hh ^ ((r & 7) ^ ((r >> 3) & 3));
;     ...
;   G_GLDS(0, 0);
;   asm volatile("s_waitcnt vmcnt(0)" ::: "memory");
;   __syncthreads();
;   for (int kt = 0; kt < nk; kt += 2) {
;     if (kt + 1 < nk) G_GLDS(kt + 1, 1);
;     G_COMPUTE(0);
;     asm volatile("s_waitcnt vmcnt(0)" ::: "memory");
;     __syncthreads();
;     if (kt + 1 < nk) {
;       if (kt + 2 < nk) G_GLDS(kt + 2, 0);
;       G_COMPUTE(1);
;       asm volatile("s_waitcnt vmcnt(0)" ::: "memory");
;       __syncthreads();
;     }
	v_mfma_f32_32x32x16_bf16 v[0:15], v[90:93], v[82:85], v[0:15]
	v_lshl_add_u64 v[82:83], s[48:49], 0, v[66:67]
	v_lshl_add_u64 v[82:83], v[82:83], 0, v[68:69]
	global_load_lds_dwordx4 v[82:83], off
	v_lshl_add_u64 v[84:85], v[82:83], 0, s[72:73]
	s_mov_b32 m0, s16
	s_mov_b64 s[48:49], 0x680
	global_load_lds_dwordx4 v[84:85], off
	v_lshl_add_u64 v[84:85], v[82:83], 0, s[52:53]
	s_mov_b32 m0, s17
	v_lshl_add_u64 v[82:83], v[82:83], 0, s[74:75]
	global_load_lds_dwordx4 v[84:85], off
	s_mov_b32 m0, s18
	v_mfma_f32_32x32x16_bf16 v[16:31], v[90:93], v[86:89], v[16:31]
	global_load_lds_dwordx4 v[82:83], off
	v_lshl_add_u64 v[82:83], v[64:65], 0, s[48:49]
	s_mov_b32 m0, s19
	s_mov_b64 s[48:49], 0x10680
	global_load_lds_dwordx4 v[82:83], off
	v_lshl_add_u64 v[82:83], v[64:65], 0, s[48:49]
	s_mov_b32 m0, s40
	s_mov_b64 s[48:49], 0x20680
	global_load_lds_dwordx4 v[82:83], off
	v_lshl_add_u64 v[82:83], v[64:65], 0, s[48:49]
	s_mov_b32 m0, s41
	s_mov_b64 s[48:49], 0x30680
	global_load_lds_dwordx4 v[82:83], off
	v_lshl_add_u64 v[82:83], v[64:65], 0, s[48:49]
	s_mov_b32 m0, s42
	v_readlane_b32 s48, v219, 34
	global_load_lds_dwordx4 v[82:83], off
	ds_read_b128 v[82:85], v81 offset:32768
	ds_read_b128 v[86:89], v81 offset:36864
	ds_read_b128 v[90:93], v80
	s_waitcnt lgkmcnt(0)
	v_mfma_f32_32x32x16_bf16 v[32:47], v[90:93], v[82:85], v[32:47]
	v_readlane_b32 s49, v219, 35
	s_mov_b32 m0, s44
	v_mfma_f32_32x32x16_bf16 v[48:63], v[90:93], v[86:89], v[48:63]
	ds_read_b128 v[90:93], v80 offset:4096
	s_waitcnt lgkmcnt(0)
	v_mfma_f32_32x32x16_bf16 v[0:15], v[90:93], v[82:85], v[0:15]
	v_mfma_f32_32x32x16_bf16 v[16:31], v[90:93], v[86:89], v[16:31]
	ds_read_b128 v[82:85], v79 offset:32768
	ds_read_b128 v[86:89], v79 offset:36864
	ds_read_b128 v[90:93], v78
	s_waitcnt lgkmcnt(0)
	v_mfma_f32_32x32x16_bf16 v[32:47], v[90:93], v[82:85], v[32:47]
	v_mfma_f32_32x32x16_bf16 v[48:63], v[90:93], v[86:89], v[48:63]
	ds_read_b128 v[90:93], v78 offset:4096
	s_waitcnt lgkmcnt(0)
	v_mfma_f32_32x32x16_bf16 v[0:15], v[90:93], v[82:85], v[0:15]
	v_mfma_f32_32x32x16_bf16 v[16:31], v[90:93], v[86:89], v[16:31]
	ds_read_b128 v[82:85], v77 offset:32768
	ds_read_b128 v[86:89], v77 offset:36864
	ds_read_b128 v[90:93], v72
	s_waitcnt lgkmcnt(0)
	v_mfma_f32_32x32x16_bf16 v[32:47], v[90:93], v[82:85], v[32:47]
	v_mfma_f32_32x32x16_bf16 v[48:63], v[90:93], v[86:89], v[48:63]
	ds_read_b128 v[90:93], v72 offset:4096
	s_waitcnt lgkmcnt(0)
	v_mfma_f32_32x32x16_bf16 v[0:15], v[90:93], v[82:85], v[0:15]
	v_mfma_f32_32x32x16_bf16 v[16:31], v[90:93], v[86:89], v[16:31]
	ds_read_b128 v[82:85], v71 offset:32768
	ds_read_b128 v[86:89], v71 offset:36864
	ds_read_b128 v[90:93], v70
	s_waitcnt lgkmcnt(0)
	v_mfma_f32_32x32x16_bf16 v[32:47], v[90:93], v[82:85], v[32:47]
	v_mfma_f32_32x32x16_bf16 v[48:63], v[90:93], v[86:89], v[48:63]
	ds_read_b128 v[90:93], v70 offset:4096
	s_waitcnt vmcnt(0)
	s_waitcnt vmcnt(0) lgkmcnt(0)
	s_barrier
	v_mfma_f32_32x32x16_bf16 v[0:15], v[90:93], v[82:85], v[0:15]
	v_lshl_add_u64 v[82:83], s[48:49], 0, v[66:67]
	v_lshl_add_u64 v[82:83], v[82:83], 0, v[68:69]
	global_load_lds_dwordx4 v[82:83], off
	v_lshl_add_u64 v[84:85], v[82:83], 0, s[72:73]
	s_mov_b32 m0, s45
	s_mov_b64 s[44:45], 0x700
	global_load_lds_dwordx4 v[84:85], off
	v_lshl_add_u64 v[84:85], v[82:83], 0, s[52:53]
	s_mov_b32 m0, s46
	v_lshl_add_u64 v[82:83], v[82:83], 0, s[74:75]
	global_load_lds_dwordx4 v[84:85], off
	s_mov_b32 m0, s47
	v_mfma_f32_32x32x16_bf16 v[16:31], v[90:93], v[86:89], v[16:31]
	global_load_lds_dwordx4 v[82:83], off
	v_lshl_add_u64 v[82:83], v[64:65], 0, s[44:45]
	s_mov_b32 m0, s43
	s_mov_b64 s[44:45], 0x10700
	global_load_lds_dwordx4 v[82:83], off
	v_lshl_add_u64 v[82:83], v[64:65], 0, s[44:45]
	s_mov_b32 m0, s39
	s_mov_b64 s[44:45], 0x20700
	global_load_lds_dwordx4 v[82:83], off
	v_lshl_add_u64 v[82:83], v[64:65], 0, s[44:45]
	s_mov_b32 m0, s5
	s_mov_b64 s[44:45], 0x30700
	global_load_lds_dwordx4 v[82:83], off
	v_lshl_add_u64 v[82:83], v[64:65], 0, s[44:45]
	s_mov_b32 m0, s4
	v_readlane_b32 s4, v219, 36
	global_load_lds_dwordx4 v[82:83], off
	ds_read_b128 v[82:85], v81 offset:49152
	ds_read_b128 v[86:89], v81 offset:53248
	ds_read_b128 v[90:93], v80 offset:16384
	s_waitcnt lgkmcnt(0)
	v_mfma_f32_32x32x16_bf16 v[32:47], v[90:93], v[82:85], v[32:47]
	v_readlane_b32 s5, v219, 37
	s_mov_b32 m0, s15
	v_readlane_b32 s39, v221, 34
	v_lshl_add_u64 v[66:67], s[4:5], 0, v[66:67]
	v_lshl_add_u64 v[66:67], v[66:67], 0, v[68:69]
	v_lshl_add_u64 v[68:69], v[66:67], 0, s[72:73]
	s_mov_b64 s[4:5], 0x780
	v_mfma_f32_32x32x16_bf16 v[48:63], v[90:93], v[86:89], v[48:63]
	ds_read_b128 v[90:93], v80 offset:20480
	s_waitcnt lgkmcnt(0)
	v_mfma_f32_32x32x16_bf16 v[0:15], v[90:93], v[82:85], v[0:15]
	v_mfma_f32_32x32x16_bf16 v[16:31], v[90:93], v[86:89], v[16:31]
	ds_read_b128 v[82:85], v79 offset:49152
	ds_read_b128 v[86:89], v79 offset:53248
	ds_read_b128 v[90:93], v78 offset:16384
	s_waitcnt lgkmcnt(0)
	v_mfma_f32_32x32x16_bf16 v[32:47], v[90:93], v[82:85], v[32:47]
	v_mfma_f32_32x32x16_bf16 v[48:63], v[90:93], v[86:89], v[48:63]
	ds_read_b128 v[90:93], v78 offset:20480
	s_waitcnt lgkmcnt(0)
	v_mfma_f32_32x32x16_bf16 v[0:15], v[90:93], v[82:85], v[0:15]
	v_mfma_f32_32x32x16_bf16 v[16:31], v[90:93], v[86:89], v[16:31]
	ds_read_b128 v[82:85], v77 offset:49152
	ds_read_b128 v[86:89], v77 offset:53248
	ds_read_b128 v[90:93], v72 offset:16384
	s_waitcnt lgkmcnt(0)
	v_mfma_f32_32x32x16_bf16 v[32:47], v[90:93], v[82:85], v[32:47]
	v_mfma_f32_32x32x16_bf16 v[48:63], v[90:93], v[86:89], v[48:63]
	ds_read_b128 v[90:93], v72 offset:20480
	s_waitcnt lgkmcnt(0)
	v_mfma_f32_32x32x16_bf16 v[0:15], v[90:93], v[82:85], v[0:15]
	v_mfma_f32_32x32x16_bf16 v[16:31], v[90:93], v[86:89], v[16:31]
	ds_read_b128 v[82:85], v71 offset:49152
	ds_read_b128 v[86:89], v71 offset:53248
	ds_read_b128 v[90:93], v70 offset:16384
	s_waitcnt lgkmcnt(0)
	v_mfma_f32_32x32x16_bf16 v[32:47], v[90:93], v[82:85], v[32:47]
	v_mfma_f32_32x32x16_bf16 v[48:63], v[90:93], v[86:89], v[48:63]
	ds_read_b128 v[90:93], v70 offset:20480
	s_waitcnt vmcnt(0)
	s_waitcnt vmcnt(0) lgkmcnt(0)
	s_barrier
; template <int EPI, int MI>
; DI void gemm_tile(const GemmDesc& g, int tm, int tn, char* smem) {
;     ...
;   G_GLDS(0, 0);
;   asm volatile("s_waitcnt vmcnt(0)" ::: "memory");
;   __syncthreads();
;   for (int kt = 0; kt < nk; kt += 2) {
;     if (kt + 1 < nk) G_GLDS(kt + 1, 1);
;     G_COMPUTE(0);
;     asm volatile("s_waitcnt vmcnt(0)" ::: "memory");
;     __syncthreads();
;     if (kt + 1 < nk) {
;       if (kt + 2 < nk) G_GLDS(kt + 2, 0);
;       G_COMPUTE(1);
;       asm volatile("s_waitcnt vmcnt(0)" ::: "memory");
;       __syncthreads();
;     }
;   }
;     ...
;     const int c4 = (tid & 31) * 4;
;     const int rgA = m0 < LAT ? (m0 >> 11) : 8;
;     const int mlast = m0 + BM - 1;
;     const int rgB = mlast < LAT ? (mlast >> 11) : 8;
;     const f32x4v m4a = *(const f32x4v*)(g.mod + (size_t)rgA * 9216 + g.gidx * 1024 + n0 + c4);
;     const f32x4v m4b = *(const f32x4v*)(g.mod + (size_t)rgB * 9216 + g.gidx * 1024 + n0 + c4);
	global_load_lds_dwordx4 v[66:67], off
	s_mov_b32 m0, s16
	v_mfma_f32_32x32x16_bf16 v[0:15], v[90:93], v[82:85], v[0:15]
	global_load_lds_dwordx4 v[68:69], off
	v_lshl_add_u64 v[68:69], v[66:67], 0, s[52:53]
	s_mov_b32 m0, s17
	v_lshl_add_u64 v[66:67], v[66:67], 0, s[74:75]
	global_load_lds_dwordx4 v[68:69], off
	s_mov_b32 m0, s18
	v_mfma_f32_32x32x16_bf16 v[16:31], v[90:93], v[86:89], v[16:31]
	global_load_lds_dwordx4 v[66:67], off
	v_lshl_add_u64 v[66:67], v[64:65], 0, s[4:5]
	s_mov_b32 m0, s19
	s_mov_b64 s[4:5], 0x10780
	global_load_lds_dwordx4 v[66:67], off
	v_lshl_add_u64 v[66:67], v[64:65], 0, s[4:5]
	s_mov_b32 m0, s40
	s_mov_b64 s[4:5], 0x20780
	global_load_lds_dwordx4 v[66:67], off
	v_lshl_add_u64 v[66:67], v[64:65], 0, s[4:5]
	s_mov_b32 m0, s41
	s_mov_b64 s[4:5], 0x30780
	global_load_lds_dwordx4 v[66:67], off
	v_lshl_add_u64 v[64:65], v[64:65], 0, s[4:5]
	s_mov_b32 m0, s42
	s_min_i32 s4, s1, 0x80
	global_load_lds_dwordx4 v[64:65], off
	ds_read_b128 v[64:67], v81 offset:32768
	ds_read_b128 v[82:85], v81 offset:36864
	ds_read_b128 v[86:89], v80
	s_waitcnt lgkmcnt(0)
	v_mfma_f32_32x32x16_bf16 v[32:47], v[86:89], v[64:67], v[32:47]
	s_ashr_i32 s15, s4, 4
	s_or_b32 s4, s38, 0x7f
	s_ashr_i32 s1, s1, 4
	s_cmpk_lt_i32 s4, 0x4000
	s_mul_i32 s4, s15, 0x9000
	v_readlane_b32 s19, v221, 33
	s_cselect_b32 s17, s1, 8
	v_mfma_f32_32x32x16_bf16 v[48:63], v[86:89], v[82:85], v[48:63]
	ds_read_b128 v[86:89], v80 offset:4096
	s_mul_hi_i32 s1, s15, 0x9000
	s_add_u32 s16, s19, s4
	s_addc_u32 s18, s39, s1
	s_ashr_i32 s1, s0, 31
	s_lshl_b64 s[4:5], s[0:1], 2
	s_add_u32 s0, s16, s4
	s_waitcnt lgkmcnt(0)
	v_mfma_f32_32x32x16_bf16 v[0:15], v[86:89], v[64:67], v[0:15]
	s_addc_u32 s1, s18, s5
	s_movk_i32 s18, 0x5000
	s_mov_b32 s16, 0
	v_mfma_f32_32x32x16_bf16 v[16:31], v[86:89], v[82:85], v[16:31]
	ds_read_b128 v[64:67], v79 offset:32768
	ds_read_b128 v[82:85], v79 offset:36864
	ds_read_b128 v[86:89], v78
	s_waitcnt lgkmcnt(0)
	v_mfma_f32_32x32x16_bf16 v[32:47], v[86:89], v[64:67], v[32:47]
	v_mfma_f32_32x32x16_bf16 v[48:63], v[86:89], v[82:85], v[48:63]
	ds_read_b128 v[86:89], v78 offset:4096
	s_waitcnt lgkmcnt(0)
	v_mfma_f32_32x32x16_bf16 v[0:15], v[86:89], v[64:67], v[0:15]
	v_mfma_f32_32x32x16_bf16 v[16:31], v[86:89], v[82:85], v[16:31]
	ds_read_b128 v[64:67], v77 offset:32768
	ds_read_b128 v[82:85], v77 offset:36864
	ds_read_b128 v[86:89], v72
	s_waitcnt lgkmcnt(0)
	v_mfma_f32_32x32x16_bf16 v[32:47], v[86:89], v[64:67], v[32:47]
	v_mfma_f32_32x32x16_bf16 v[48:63], v[86:89], v[82:85], v[48:63]
	ds_read_b128 v[86:89], v72 offset:4096
	s_waitcnt lgkmcnt(0)
	v_mfma_f32_32x32x16_bf16 v[0:15], v[86:89], v[64:67], v[0:15]
	v_mfma_f32_32x32x16_bf16 v[16:31], v[86:89], v[82:85], v[16:31]
	ds_read_b128 v[64:67], v71 offset:32768
	ds_read_b128 v[82:85], v71 offset:36864
	ds_read_b128 v[86:89], v70
	s_waitcnt lgkmcnt(0)
	v_mfma_f32_32x32x16_bf16 v[32:47], v[86:89], v[64:67], v[32:47]
	v_mfma_f32_32x32x16_bf16 v[48:63], v[86:89], v[82:85], v[48:63]
	ds_read_b128 v[86:89], v70 offset:4096
	s_waitcnt vmcnt(0)
	s_waitcnt vmcnt(0) lgkmcnt(0)
	s_barrier
	v_mfma_f32_32x32x16_bf16 v[0:15], v[86:89], v[64:67], v[0:15]
	v_mfma_f32_32x32x16_bf16 v[16:31], v[86:89], v[82:85], v[16:31]
	ds_read_b128 v[64:67], v81 offset:49152
	ds_read_b128 v[82:85], v81 offset:53248
	ds_read_b128 v[86:89], v80 offset:16384
	s_waitcnt lgkmcnt(0)
	v_mfma_f32_32x32x16_bf16 v[32:47], v[86:89], v[64:67], v[32:47]
	v_mfma_f32_32x32x16_bf16 v[48:63], v[86:89], v[82:85], v[48:63]
	ds_read_b128 v[86:89], v80 offset:20480
	s_waitcnt lgkmcnt(0)
	v_mfma_f32_32x32x16_bf16 v[0:15], v[86:89], v[64:67], v[0:15]
	v_mfma_f32_32x32x16_bf16 v[16:31], v[86:89], v[82:85], v[16:31]
	ds_read_b128 v[64:67], v79 offset:49152
	ds_read_b128 v[80:83], v79 offset:53248
	ds_read_b128 v[84:87], v78 offset:16384
	s_waitcnt lgkmcnt(0)
	v_mfma_f32_32x32x16_bf16 v[32:47], v[84:87], v[64:67], v[32:47]
	v_mfma_f32_32x32x16_bf16 v[48:63], v[84:87], v[80:83], v[48:63]
	ds_read_b128 v[84:87], v78 offset:20480
	s_waitcnt lgkmcnt(0)
	v_mfma_f32_32x32x16_bf16 v[0:15], v[84:87], v[64:67], v[0:15]
	v_mfma_f32_32x32x16_bf16 v[16:31], v[84:87], v[80:83], v[16:31]
	ds_read_b128 v[64:67], v77 offset:49152
	ds_read_b128 v[78:81], v77 offset:53248
	ds_read_b128 v[82:85], v72 offset:16384
	v_and_b32_e32 v77, 64, v74
	v_lshlrev_b32_e32 v77, 2, v77
	s_waitcnt lgkmcnt(0)
	v_mfma_f32_32x32x16_bf16 v[32:47], v[82:85], v[64:67], v[32:47]
	v_mfma_f32_32x32x16_bf16 v[48:63], v[82:85], v[78:81], v[48:63]
	ds_read_b128 v[82:85], v72 offset:20480
	s_waitcnt lgkmcnt(0)
	v_mfma_f32_32x32x16_bf16 v[0:15], v[82:85], v[64:67], v[0:15]
	v_mfma_f32_32x32x16_bf16 v[16:31], v[82:85], v[78:81], v[16:31]
	ds_read_b128 v[64:67], v71 offset:49152
	ds_read_b128 v[78:81], v71 offset:53248
	ds_read_b128 v[82:85], v70 offset:16384
	ds_read_b128 v[68:71], v70 offset:20480
	s_waitcnt vmcnt(0)
	s_waitcnt lgkmcnt(0)
	s_barrier
; template <int EPI, int MI>
; DI void gemm_tile(const GemmDesc& g, int tm, int tn, char* smem) {
;     ...
;   } else if (EPI == EPI_RES) {
;     float* es = (float*)smem;
;     const int c4 = (tid & 31) * 4;
;     const int rgA = m0 < LAT ? (m0 >> 11) : 8;
;     const int mlast = m0 + BM - 1;
;     const int rgB = mlast < LAT ? (mlast >> 11) : 8;
;     const f32x4v m4a = *(const f32x4v*)(g.mod + (size_t)rgA * 9216 + g.gidx * 1024 + n0 + c4);
;     const f32x4v m4b = *(const f32x4v*)(g.mod + (size_t)rgB * 9216 + g.gidx * 1024 + n0 + c4);
; #pragma unroll
;     for (int mi = 0; mi < MI; ++mi) {
; #pragma unroll
;       for (int ni = 0; ni < 2; ++ni)
; #pragma unroll
;         for (int i = 0; i < 16; ++i) {
;           const int lrow = wm * 32 + (i & 3) + 8 * (i >> 2) + 4 * hh;
;           es[lrow * 128 + wn * 64 + ni * 32 + r] = acc[mi][ni][i];
;         }
;       __syncthreads();
	v_mfma_f32_32x32x16_bf16 v[32:47], v[82:85], v[64:67], v[32:47]
	v_mfma_f32_32x32x16_bf16 v[0:15], v[68:71], v[64:67], v[0:15]
	v_lshlrev_b32_e32 v64, 2, v74
	v_and_b32_e32 v72, 0x7c, v64
	v_mfma_f32_32x32x16_bf16 v[16:31], v[68:71], v[78:81], v[16:31]
	v_lshlrev_b32_e32 v68, 2, v72
	v_mov_b32_e32 v69, v96
	v_lshl_add_u64 v[64:65], s[0:1], 0, v[68:69]
	s_mul_hi_i32 s0, s17, 0x9000
	s_mul_i32 s17, s17, 0x9000
	s_add_u32 s1, s19, s17
	s_addc_u32 s17, s39, s0
	s_add_u32 s0, s1, s4
	v_add_co_u32_e32 v64, vcc, s18, v64
	s_addc_u32 s1, s17, s5
	s_nop 0
	v_addc_co_u32_e32 v65, vcc, 0, v65, vcc
	v_lshl_add_u64 v[68:69], s[0:1], 0, v[68:69]
	v_add_co_u32_e32 v68, vcc, s18, v68
	global_load_dwordx4 v[64:67], v[64:65], off
	s_nop 0
	v_addc_co_u32_e32 v69, vcc, 0, v69, vcc
	global_load_dwordx4 v[68:71], v[68:69], off
	v_mfma_f32_32x32x16_bf16 v[48:63], v[82:85], v[78:81], v[48:63]
	v_lshlrev_b32_e32 v78, 2, v73
	v_add3_u32 v76, v76, v77, v78
	v_ashrrev_i32_e32 v77, 5, v74
	v_add_u32_e32 v74, v76, v75
	s_nop 7
	ds_write2_b32 v74, v32, v48 offset1:32
	ds_write2_b32 v74, v33, v49 offset0:128 offset1:160
	v_add_u32_e32 v48, 0x400, v74
	v_add_u32_e32 v32, 8, v77
	ds_write2_b32 v48, v34, v50 offset1:32
	ds_write2_b32 v48, v35, v51 offset0:128 offset1:160
	v_add_u32_e32 v49, 0x1000, v74
	v_and_b32_e32 v35, 31, v32
	v_add_u32_e32 v32, 24, v77
	ds_write2_b32 v49, v36, v52 offset1:32
	ds_write2_b32 v49, v37, v53 offset0:128 offset1:160
	v_add_u32_e32 v50, 0x1400, v74
	v_add_u32_e32 v51, 0x2000, v74
	v_and_b32_e32 v37, 31, v32
	v_lshlrev_b32_e32 v32, 4, v73
	ds_write2_b32 v50, v38, v54 offset1:32
	ds_write2_b32 v50, v39, v55 offset0:128 offset1:160
	ds_write2_b32 v51, v40, v56 offset1:32
	ds_write2_b32 v51, v41, v57 offset0:128 offset1:160
	v_add_u32_e32 v40, 0x2400, v74
	v_lshl_or_b32 v32, v77, 9, v32
	v_lshlrev_b32_e32 v39, 1, v77
	ds_write2_b32 v40, v42, v58 offset1:32
	ds_write2_b32 v40, v43, v59 offset0:128 offset1:160
	v_add_u32_e32 v41, 0x3000, v74
	v_add_u32_e32 v42, 0x3400, v74
	v_and_b32_e32 v34, 31, v77
	v_bitop3_b32 v36, v77, 16, 31 bitop3:0x6c
	v_add_u32_e32 v38, 0, v32
	v_mov_b32_e32 v43, v39
	ds_write2_b32 v41, v44, v60 offset1:32
	ds_write2_b32 v41, v45, v61 offset0:128 offset1:160
	ds_write2_b32 v42, v46, v62 offset1:32
	ds_write2_b32 v42, v47, v63 offset0:128 offset1:160
	v_lshlrev_b32_e32 v32, 2, v72
	v_mov_b32_e32 v33, 0
	s_mov_b32 s16, s38
	v_or_b32_e32 v224, s16, v34
	v_mov_b32_e32 v226, s68
	v_mov_b32_e32 v227, s69
	v_mov_b32_e32 v52, s3
	v_mov_b32_e32 v53, s33
	v_cmp_gt_i32_e32 vcc, s8, v224
	v_add_u32_e32 v225, 0xffffc000, v224
	s_nop 0
	v_cndmask_b32_e32 v224, v225, v224, vcc
	v_cndmask_b32_e32 v226, v52, v226, vcc
	v_cndmask_b32_e32 v227, v53, v227, vcc
	v_mov_b32_e32 v225, 0
	v_lshlrev_b64 v[224:225], 12, v[224:225]
	v_lshl_add_u64 v[224:225], v[226:227], 0, v[224:225]
	v_lshl_add_u64 v[224:225], v[224:225], 0, s[4:5]
	v_lshl_add_u64 v[52:53], v[224:225], 0, v[32:33]
	global_load_dwordx4 v[224:227], v[52:53], off
	v_or_b32_e32 v228, s16, v35
	v_mov_b32_e32 v230, s68
	v_mov_b32_e32 v231, s69
	v_mov_b32_e32 v54, s3
	v_mov_b32_e32 v55, s33
	v_cmp_gt_i32_e32 vcc, s8, v228
	v_add_u32_e32 v229, 0xffffc000, v228
	s_nop 0
	v_cndmask_b32_e32 v228, v229, v228, vcc
	v_cndmask_b32_e32 v230, v54, v230, vcc
	v_cndmask_b32_e32 v231, v55, v231, vcc
	v_mov_b32_e32 v229, 0
	v_lshlrev_b64 v[228:229], 12, v[228:229]
	v_lshl_add_u64 v[228:229], v[230:231], 0, v[228:229]
	v_lshl_add_u64 v[228:229], v[228:229], 0, s[4:5]
	v_lshl_add_u64 v[54:55], v[228:229], 0, v[32:33]
	global_load_dwordx4 v[228:231], v[54:55], off
	v_or_b32_e32 v232, s16, v36
	v_mov_b32_e32 v234, s68
	v_mov_b32_e32 v235, s69
	v_mov_b32_e32 v56, s3
	v_mov_b32_e32 v57, s33
	v_cmp_gt_i32_e32 vcc, s8, v232
	v_add_u32_e32 v233, 0xffffc000, v232
	s_nop 0
	v_cndmask_b32_e32 v232, v233, v232, vcc
	v_cndmask_b32_e32 v234, v56, v234, vcc
	v_cndmask_b32_e32 v235, v57, v235, vcc
	v_mov_b32_e32 v233, 0
	v_lshlrev_b64 v[232:233], 12, v[232:233]
	v_lshl_add_u64 v[232:233], v[234:235], 0, v[232:233]
	v_lshl_add_u64 v[232:233], v[232:233], 0, s[4:5]
	v_lshl_add_u64 v[56:57], v[232:233], 0, v[32:33]
	global_load_dwordx4 v[232:235], v[56:57], off
	v_or_b32_e32 v236, s16, v37
	v_mov_b32_e32 v238, s68
	v_mov_b32_e32 v239, s69
	v_mov_b32_e32 v58, s3
	v_mov_b32_e32 v59, s33
	v_cmp_gt_i32_e32 vcc, s8, v236
	v_add_u32_e32 v237, 0xffffc000, v236
	s_nop 0
	v_cndmask_b32_e32 v236, v237, v236, vcc
	v_cndmask_b32_e32 v238, v58, v238, vcc
	v_cndmask_b32_e32 v239, v59, v239, vcc
	v_mov_b32_e32 v237, 0
	v_lshlrev_b64 v[236:237], 12, v[236:237]
	v_lshl_add_u64 v[236:237], v[238:239], 0, v[236:237]
	v_lshl_add_u64 v[236:237], v[236:237], 0, s[4:5]
	v_lshl_add_u64 v[58:59], v[236:237], 0, v[32:33]
	global_load_dwordx4 v[236:239], v[58:59], off
	s_add_u32 s16, s38, 64
	v_or_b32_e32 v240, s16, v34
	v_mov_b32_e32 v242, s68
	v_mov_b32_e32 v243, s69
	v_mov_b32_e32 v60, s3
	v_mov_b32_e32 v61, s33
	v_cmp_gt_i32_e32 vcc, s8, v240
	v_add_u32_e32 v241, 0xffffc000, v240
	s_nop 0
	v_cndmask_b32_e32 v240, v241, v240, vcc
	v_cndmask_b32_e32 v242, v60, v242, vcc
	v_cndmask_b32_e32 v243, v61, v243, vcc
	v_mov_b32_e32 v241, 0
	v_lshlrev_b64 v[240:241], 12, v[240:241]
	v_lshl_add_u64 v[240:241], v[242:243], 0, v[240:241]
	v_lshl_add_u64 v[240:241], v[240:241], 0, s[4:5]
	v_lshl_add_u64 v[60:61], v[240:241], 0, v[32:33]
	global_load_dwordx4 v[240:243], v[60:61], off
	v_or_b32_e32 v244, s16, v35
	v_mov_b32_e32 v246, s68
	v_mov_b32_e32 v247, s69
	v_mov_b32_e32 v62, s3
	v_mov_b32_e32 v63, s33
	v_cmp_gt_i32_e32 vcc, s8, v244
	v_add_u32_e32 v245, 0xffffc000, v244
	s_nop 0
	v_cndmask_b32_e32 v244, v245, v244, vcc
	v_cndmask_b32_e32 v246, v62, v246, vcc
; template <int EPI, int MI>
; DI void gemm_tile(const GemmDesc& g, int tm, int tn, char* smem) {
;     ...
;       __syncthreads();
; #pragma unroll 4
;       for (int j = 0; j < 8; ++j) {
;         const int lrow = (tid >> 5) + 8 * j;
;         const int grow = m0 + (lrow >> 5) * (32 * MI) + mi * 32 + (lrow & 31);
;         const f32x4v a4 = *(const f32x4v*)(es + lrow * 128 + c4);
;         const int rg = grow < LAT ? (grow >> 11) : 8;
;         const f32x4v m4 = rg == rgA ? m4a : m4b;
;         float* rp = (grow < LAT ? g.xres + (size_t)grow * 1024 : g.hres + (size_t)(grow - LAT) * 1024) + n0 + c4;
;         f32x4v x4 = *(const f32x4v*)rp;
;         x4 += (m4 * a4) * g.coef;
;         *(f32x4v*)rp = x4;
;       }
	v_cndmask_b32_e32 v247, v63, v247, vcc
	v_mov_b32_e32 v245, 0
	v_lshlrev_b64 v[244:245], 12, v[244:245]
	v_lshl_add_u64 v[244:245], v[246:247], 0, v[244:245]
	v_lshl_add_u64 v[244:245], v[244:245], 0, s[4:5]
	v_lshl_add_u64 v[62:63], v[244:245], 0, v[32:33]
	global_load_dwordx4 v[244:247], v[62:63], off
	v_or_b32_e32 v248, s16, v36
	v_mov_b32_e32 v250, s68
	v_mov_b32_e32 v251, s69
	v_mov_b32_e32 v44, s3
	v_mov_b32_e32 v45, s33
	v_cmp_gt_i32_e32 vcc, s8, v248
	v_add_u32_e32 v249, 0xffffc000, v248
	s_nop 0
	v_cndmask_b32_e32 v248, v249, v248, vcc
	v_cndmask_b32_e32 v250, v44, v250, vcc
	v_cndmask_b32_e32 v251, v45, v251, vcc
	v_mov_b32_e32 v249, 0
	v_lshlrev_b64 v[248:249], 12, v[248:249]
	v_lshl_add_u64 v[248:249], v[250:251], 0, v[248:249]
	v_lshl_add_u64 v[248:249], v[248:249], 0, s[4:5]
	v_lshl_add_u64 v[44:45], v[248:249], 0, v[32:33]
	global_load_dwordx4 v[248:251], v[44:45], off
	v_or_b32_e32 v252, s16, v37
	v_mov_b32_e32 v254, s68
	v_mov_b32_e32 v255, s69
	v_mov_b32_e32 v46, s3
	v_mov_b32_e32 v47, s33
	v_cmp_gt_i32_e32 vcc, s8, v252
	v_add_u32_e32 v253, 0xffffc000, v252
	s_nop 0
	v_cndmask_b32_e32 v252, v253, v252, vcc
	v_cndmask_b32_e32 v254, v46, v254, vcc
	v_cndmask_b32_e32 v255, v47, v255, vcc
	v_mov_b32_e32 v253, 0
	v_lshlrev_b64 v[252:253], 12, v[252:253]
	v_lshl_add_u64 v[252:253], v[254:255], 0, v[252:253]
	v_lshl_add_u64 v[252:253], v[252:253], 0, s[4:5]
	v_lshl_add_u64 v[46:47], v[252:253], 0, v[32:33]
	global_load_dwordx4 v[252:255], v[46:47], off
	s_waitcnt lgkmcnt(0)
	s_barrier
	s_waitcnt vmcnt(8)
	ds_read_b128 v[78:81], v38
	s_mov_b32 s16, s38
	s_ashr_i32 s17, s16, 11
	v_or_b32_e32 v86, s16, v34
	v_mov_b32_e32 v87, s17
	v_cmp_gt_i32_e32 vcc, s8, v86
	ds_read_b128 v[82:85], v38 offset:4096
	s_nop 0
	v_cndmask_b32_e32 v87, 8, v87, vcc
	v_cmp_eq_u32_e64 s[0:1], s15, v87
	s_nop 1
	v_cndmask_b32_e64 v87, v69, v65, s[0:1]
	v_cndmask_b32_e64 v86, v68, v64, s[0:1]
	v_cndmask_b32_e64 v89, v71, v67, s[0:1]
	v_cndmask_b32_e64 v88, v70, v66, s[0:1]
	s_waitcnt lgkmcnt(1)
	s_waitcnt vmcnt(7)
	v_pk_fma_f32 v[78:79], v[78:79], v[86:87], v[224:225]
	v_pk_fma_f32 v[80:81], v[80:81], v[88:89], v[226:227]
	global_store_dwordx4 v[52:53], v[78:81], off
	v_or_b32_e32 v86, s16, v35
	v_mov_b32_e32 v87, s17
	v_cmp_gt_i32_e32 vcc, s8, v86
	ds_read_b128 v[78:81], v38 offset:8192
	s_nop 0
	v_cndmask_b32_e32 v87, 8, v87, vcc
	v_cmp_eq_u32_e64 s[0:1], s15, v87
	s_nop 1
	v_cndmask_b32_e64 v87, v69, v65, s[0:1]
	v_cndmask_b32_e64 v86, v68, v64, s[0:1]
	v_cndmask_b32_e64 v89, v71, v67, s[0:1]
	v_cndmask_b32_e64 v88, v70, v66, s[0:1]
	s_waitcnt lgkmcnt(1)
	s_waitcnt vmcnt(7)
	v_pk_fma_f32 v[82:83], v[82:83], v[86:87], v[228:229]
	v_pk_fma_f32 v[84:85], v[84:85], v[88:89], v[230:231]
	global_store_dwordx4 v[54:55], v[82:85], off
	v_or_b32_e32 v86, s16, v36
	v_mov_b32_e32 v87, s17
	v_cmp_gt_i32_e32 vcc, s8, v86
	ds_read_b128 v[82:85], v38 offset:12288
	s_nop 0
	v_cndmask_b32_e32 v87, 8, v87, vcc
	v_cmp_eq_u32_e64 s[0:1], s15, v87
	s_nop 1
	v_cndmask_b32_e64 v87, v69, v65, s[0:1]
	v_cndmask_b32_e64 v86, v68, v64, s[0:1]
	v_cndmask_b32_e64 v89, v71, v67, s[0:1]
	v_cndmask_b32_e64 v88, v70, v66, s[0:1]
	s_waitcnt lgkmcnt(1)
	s_waitcnt vmcnt(7)
	v_pk_fma_f32 v[78:79], v[78:79], v[86:87], v[232:233]
	v_pk_fma_f32 v[80:81], v[80:81], v[88:89], v[234:235]
	global_store_dwordx4 v[56:57], v[78:81], off
	v_or_b32_e32 v86, s16, v37
	v_mov_b32_e32 v87, s17
	v_cmp_gt_i32_e32 vcc, s8, v86
	ds_read_b128 v[78:81], v38 offset:16384
	s_nop 0
	v_cndmask_b32_e32 v87, 8, v87, vcc
	v_cmp_eq_u32_e64 s[0:1], s15, v87
	s_nop 1
	v_cndmask_b32_e64 v87, v69, v65, s[0:1]
	v_cndmask_b32_e64 v86, v68, v64, s[0:1]
	v_cndmask_b32_e64 v89, v71, v67, s[0:1]
	v_cndmask_b32_e64 v88, v70, v66, s[0:1]
	s_waitcnt lgkmcnt(1)
	s_waitcnt vmcnt(7)
	v_pk_fma_f32 v[82:83], v[82:83], v[86:87], v[236:237]
	v_pk_fma_f32 v[84:85], v[84:85], v[88:89], v[238:239]
	global_store_dwordx4 v[58:59], v[82:85], off
	s_add_u32 s16, s38, 64
	s_ashr_i32 s17, s16, 11
	v_or_b32_e32 v86, s16, v34
	v_mov_b32_e32 v87, s17
	v_cmp_gt_i32_e32 vcc, s8, v86
	ds_read_b128 v[82:85], v38 offset:20480
	s_nop 0
	v_cndmask_b32_e32 v87, 8, v87, vcc
	v_cmp_eq_u32_e64 s[0:1], s15, v87
	s_nop 1
	v_cndmask_b32_e64 v87, v69, v65, s[0:1]
	v_cndmask_b32_e64 v86, v68, v64, s[0:1]
	v_cndmask_b32_e64 v89, v71, v67, s[0:1]
	v_cndmask_b32_e64 v88, v70, v66, s[0:1]
	s_waitcnt lgkmcnt(1)
	s_waitcnt vmcnt(7)
	v_pk_fma_f32 v[78:79], v[78:79], v[86:87], v[240:241]
	v_pk_fma_f32 v[80:81], v[80:81], v[88:89], v[242:243]
	global_store_dwordx4 v[60:61], v[78:81], off
	v_or_b32_e32 v86, s16, v35
	v_mov_b32_e32 v87, s17
	v_cmp_gt_i32_e32 vcc, s8, v86
	ds_read_b128 v[78:81], v38 offset:24576
	s_nop 0
	v_cndmask_b32_e32 v87, 8, v87, vcc
	v_cmp_eq_u32_e64 s[0:1], s15, v87
	s_nop 1
	v_cndmask_b32_e64 v87, v69, v65, s[0:1]
	v_cndmask_b32_e64 v86, v68, v64, s[0:1]
	v_cndmask_b32_e64 v89, v71, v67, s[0:1]
	v_cndmask_b32_e64 v88, v70, v66, s[0:1]
	s_waitcnt lgkmcnt(1)
	s_waitcnt vmcnt(7)
	v_pk_fma_f32 v[82:83], v[82:83], v[86:87], v[244:245]
	v_pk_fma_f32 v[84:85], v[84:85], v[88:89], v[246:247]
	global_store_dwordx4 v[62:63], v[82:85], off
	v_or_b32_e32 v86, s16, v36
	v_mov_b32_e32 v87, s17
	v_cmp_gt_i32_e32 vcc, s8, v86
	ds_read_b128 v[82:85], v38 offset:28672
	s_nop 0
	v_cndmask_b32_e32 v87, 8, v87, vcc
	v_cmp_eq_u32_e64 s[0:1], s15, v87
	s_nop 1
	v_cndmask_b32_e64 v87, v69, v65, s[0:1]
	v_cndmask_b32_e64 v86, v68, v64, s[0:1]
	v_cndmask_b32_e64 v89, v71, v67, s[0:1]
	v_cndmask_b32_e64 v88, v70, v66, s[0:1]
	s_waitcnt lgkmcnt(1)
	s_waitcnt vmcnt(7)
; template <int EPI, int MI>
; DI void gemm_tile(const GemmDesc& g, int tm, int tn, char* smem) {
;     ...
; #pragma unroll 4
;       for (int j = 0; j < 8; ++j) {
;         const int lrow = (tid >> 5) + 8 * j;
;         const int grow = m0 + (lrow >> 5) * (32 * MI) + mi * 32 + (lrow & 31);
;         const f32x4v a4 = *(const f32x4v*)(es + lrow * 128 + c4);
;         const int rg = grow < LAT ? (grow >> 11) : 8;
;         const f32x4v m4 = rg == rgA ? m4a : m4b;
;         float* rp = (grow < LAT ? g.xres + (size_t)grow * 1024 : g.hres + (size_t)(grow - LAT) * 1024) + n0 + c4;
;         f32x4v x4 = *(const f32x4v*)rp;
;         x4 += (m4 * a4) * g.coef;
;         *(f32x4v*)rp = x4;
;       }
;       __syncthreads();
	v_pk_fma_f32 v[78:79], v[78:79], v[86:87], v[248:249]
	v_pk_fma_f32 v[80:81], v[80:81], v[88:89], v[250:251]
	global_store_dwordx4 v[44:45], v[78:81], off
	v_or_b32_e32 v86, s16, v37
	v_mov_b32_e32 v87, s17
	v_cmp_gt_i32_e32 vcc, s8, v86
	s_nop 1
	v_cndmask_b32_e32 v87, 8, v87, vcc
	v_cmp_eq_u32_e64 s[0:1], s15, v87
	s_nop 1
	v_cndmask_b32_e64 v87, v69, v65, s[0:1]
	v_cndmask_b32_e64 v86, v68, v64, s[0:1]
	v_cndmask_b32_e64 v89, v71, v67, s[0:1]
	v_cndmask_b32_e64 v88, v70, v66, s[0:1]
	s_waitcnt lgkmcnt(0)
	s_waitcnt vmcnt(7)
	v_pk_fma_f32 v[82:83], v[82:83], v[86:87], v[252:253]
	v_pk_fma_f32 v[84:85], v[84:85], v[88:89], v[254:255]
	global_store_dwordx4 v[46:47], v[82:85], off
	s_add_u32 s16, s38, 32
	v_or_b32_e32 v224, s16, v34
	v_mov_b32_e32 v226, s68
	v_mov_b32_e32 v227, s69
	v_mov_b32_e32 v52, s3
	v_mov_b32_e32 v53, s33
	v_cmp_gt_i32_e32 vcc, s8, v224
	v_add_u32_e32 v225, 0xffffc000, v224
	s_nop 0
	v_cndmask_b32_e32 v224, v225, v224, vcc
	v_cndmask_b32_e32 v226, v52, v226, vcc
	v_cndmask_b32_e32 v227, v53, v227, vcc
	v_mov_b32_e32 v225, 0
	v_lshlrev_b64 v[224:225], 12, v[224:225]
	v_lshl_add_u64 v[224:225], v[226:227], 0, v[224:225]
	v_lshl_add_u64 v[224:225], v[224:225], 0, s[4:5]
	v_lshl_add_u64 v[52:53], v[224:225], 0, v[32:33]
	global_load_dwordx4 v[224:227], v[52:53], off
	v_or_b32_e32 v228, s16, v35
	v_mov_b32_e32 v230, s68
	v_mov_b32_e32 v231, s69
	v_mov_b32_e32 v54, s3
	v_mov_b32_e32 v55, s33
	v_cmp_gt_i32_e32 vcc, s8, v228
	v_add_u32_e32 v229, 0xffffc000, v228
	s_nop 0
	v_cndmask_b32_e32 v228, v229, v228, vcc
	v_cndmask_b32_e32 v230, v54, v230, vcc
	v_cndmask_b32_e32 v231, v55, v231, vcc
	v_mov_b32_e32 v229, 0
	v_lshlrev_b64 v[228:229], 12, v[228:229]
	v_lshl_add_u64 v[228:229], v[230:231], 0, v[228:229]
	v_lshl_add_u64 v[228:229], v[228:229], 0, s[4:5]
	v_lshl_add_u64 v[54:55], v[228:229], 0, v[32:33]
	global_load_dwordx4 v[228:231], v[54:55], off
	v_or_b32_e32 v232, s16, v36
	v_mov_b32_e32 v234, s68
	v_mov_b32_e32 v235, s69
	v_mov_b32_e32 v56, s3
	v_mov_b32_e32 v57, s33
	v_cmp_gt_i32_e32 vcc, s8, v232
	v_add_u32_e32 v233, 0xffffc000, v232
	s_nop 0
	v_cndmask_b32_e32 v232, v233, v232, vcc
	v_cndmask_b32_e32 v234, v56, v234, vcc
	v_cndmask_b32_e32 v235, v57, v235, vcc
	v_mov_b32_e32 v233, 0
	v_lshlrev_b64 v[232:233], 12, v[232:233]
	v_lshl_add_u64 v[232:233], v[234:235], 0, v[232:233]
	v_lshl_add_u64 v[232:233], v[232:233], 0, s[4:5]
	v_lshl_add_u64 v[56:57], v[232:233], 0, v[32:33]
	global_load_dwordx4 v[232:235], v[56:57], off
	v_or_b32_e32 v236, s16, v37
	v_mov_b32_e32 v238, s68
	v_mov_b32_e32 v239, s69
	v_mov_b32_e32 v58, s3
	v_mov_b32_e32 v59, s33
	v_cmp_gt_i32_e32 vcc, s8, v236
	v_add_u32_e32 v237, 0xffffc000, v236
	s_nop 0
	v_cndmask_b32_e32 v236, v237, v236, vcc
	v_cndmask_b32_e32 v238, v58, v238, vcc
	v_cndmask_b32_e32 v239, v59, v239, vcc
	v_mov_b32_e32 v237, 0
	v_lshlrev_b64 v[236:237], 12, v[236:237]
	v_lshl_add_u64 v[236:237], v[238:239], 0, v[236:237]
	v_lshl_add_u64 v[236:237], v[236:237], 0, s[4:5]
	v_lshl_add_u64 v[58:59], v[236:237], 0, v[32:33]
	global_load_dwordx4 v[236:239], v[58:59], off
	s_add_u32 s16, s38, 96
	v_or_b32_e32 v240, s16, v34
	v_mov_b32_e32 v242, s68
	v_mov_b32_e32 v243, s69
	v_mov_b32_e32 v60, s3
	v_mov_b32_e32 v61, s33
	v_cmp_gt_i32_e32 vcc, s8, v240
	v_add_u32_e32 v241, 0xffffc000, v240
	s_nop 0
	v_cndmask_b32_e32 v240, v241, v240, vcc
	v_cndmask_b32_e32 v242, v60, v242, vcc
	v_cndmask_b32_e32 v243, v61, v243, vcc
	v_mov_b32_e32 v241, 0
	v_lshlrev_b64 v[240:241], 12, v[240:241]
	v_lshl_add_u64 v[240:241], v[242:243], 0, v[240:241]
	v_lshl_add_u64 v[240:241], v[240:241], 0, s[4:5]
	v_lshl_add_u64 v[60:61], v[240:241], 0, v[32:33]
	global_load_dwordx4 v[240:243], v[60:61], off
	v_or_b32_e32 v244, s16, v35
	v_mov_b32_e32 v246, s68
	v_mov_b32_e32 v247, s69
	v_mov_b32_e32 v62, s3
	v_mov_b32_e32 v63, s33
	v_cmp_gt_i32_e32 vcc, s8, v244
	v_add_u32_e32 v245, 0xffffc000, v244
	s_nop 0
	v_cndmask_b32_e32 v244, v245, v244, vcc
	v_cndmask_b32_e32 v246, v62, v246, vcc
	v_cndmask_b32_e32 v247, v63, v247, vcc
	v_mov_b32_e32 v245, 0
	v_lshlrev_b64 v[244:245], 12, v[244:245]
	v_lshl_add_u64 v[244:245], v[246:247], 0, v[244:245]
	v_lshl_add_u64 v[244:245], v[244:245], 0, s[4:5]
	v_lshl_add_u64 v[62:63], v[244:245], 0, v[32:33]
	global_load_dwordx4 v[244:247], v[62:63], off
	v_or_b32_e32 v248, s16, v36
	v_mov_b32_e32 v250, s68
	v_mov_b32_e32 v251, s69
	v_mov_b32_e32 v44, s3
	v_mov_b32_e32 v45, s33
	v_cmp_gt_i32_e32 vcc, s8, v248
	v_add_u32_e32 v249, 0xffffc000, v248
	s_nop 0
	v_cndmask_b32_e32 v248, v249, v248, vcc
	v_cndmask_b32_e32 v250, v44, v250, vcc
	v_cndmask_b32_e32 v251, v45, v251, vcc
	v_mov_b32_e32 v249, 0
	v_lshlrev_b64 v[248:249], 12, v[248:249]
	v_lshl_add_u64 v[248:249], v[250:251], 0, v[248:249]
	v_lshl_add_u64 v[248:249], v[248:249], 0, s[4:5]
	v_lshl_add_u64 v[44:45], v[248:249], 0, v[32:33]
	global_load_dwordx4 v[248:251], v[44:45], off
	v_or_b32_e32 v252, s16, v37
	v_mov_b32_e32 v254, s68
	v_mov_b32_e32 v255, s69
	v_mov_b32_e32 v46, s3
	v_mov_b32_e32 v47, s33
	v_cmp_gt_i32_e32 vcc, s8, v252
	v_add_u32_e32 v253, 0xffffc000, v252
	s_nop 0
	v_cndmask_b32_e32 v252, v253, v252, vcc
	v_cndmask_b32_e32 v254, v46, v254, vcc
	v_cndmask_b32_e32 v255, v47, v255, vcc
	v_mov_b32_e32 v253, 0
	v_lshlrev_b64 v[252:253], 12, v[252:253]
	v_lshl_add_u64 v[252:253], v[254:255], 0, v[252:253]
	v_lshl_add_u64 v[252:253], v[252:253], 0, s[4:5]
	v_lshl_add_u64 v[46:47], v[252:253], 0, v[32:33]
	global_load_dwordx4 v[252:255], v[46:47], off
	s_mov_b32 s16, 0
	s_barrier
; template <int EPI, int MI>
; DI void gemm_tile(const GemmDesc& g, int tm, int tn, char* smem) {
;     ...
;     for (int mi = 0; mi < MI; ++mi) {
; #pragma unroll
;       for (int ni = 0; ni < 2; ++ni)
; #pragma unroll
;         for (int i = 0; i < 16; ++i) {
;           const int lrow = wm * 32 + (i & 3) + 8 * (i >> 2) + 4 * hh;
;           es[lrow * 128 + wn * 64 + ni * 32 + r] = acc[mi][ni][i];
;         }
;       __syncthreads();
; #pragma unroll 4
;       for (int j = 0; j < 8; ++j) {
;         const int lrow = (tid >> 5) + 8 * j;
;         const int grow = m0 + (lrow >> 5) * (32 * MI) + mi * 32 + (lrow & 31);
;         const f32x4v a4 = *(const f32x4v*)(es + lrow * 128 + c4);
;         const int rg = grow < LAT ? (grow >> 11) : 8;
;         const f32x4v m4 = rg == rgA ? m4a : m4b;
;         float* rp = (grow < LAT ? g.xres + (size_t)grow * 1024 : g.hres + (size_t)(grow - LAT) * 1024) + n0 + c4;
;         f32x4v x4 = *(const f32x4v*)rp;
;         x4 += (m4 * a4) * g.coef;
;         *(f32x4v*)rp = x4;
;       }
;       __syncthreads();
	ds_write2_b32 v74, v0, v16 offset1:32
	ds_write2_b32 v74, v1, v17 offset0:128 offset1:160
	ds_write2_b32 v48, v2, v18 offset1:32
	ds_write2_b32 v48, v3, v19 offset0:128 offset1:160
	ds_write2_b32 v49, v4, v20 offset1:32
	ds_write2_b32 v49, v5, v21 offset0:128 offset1:160
	ds_write2_b32 v50, v6, v22 offset1:32
	ds_write2_b32 v50, v7, v23 offset0:128 offset1:160
	ds_write2_b32 v51, v8, v24 offset1:32
	ds_write2_b32 v51, v9, v25 offset0:128 offset1:160
	ds_write2_b32 v40, v10, v26 offset1:32
	ds_write2_b32 v40, v11, v27 offset0:128 offset1:160
	ds_write2_b32 v41, v12, v28 offset1:32
	ds_write2_b32 v41, v13, v29 offset0:128 offset1:160
	ds_write2_b32 v42, v14, v30 offset1:32
	ds_write2_b32 v42, v15, v31 offset0:128 offset1:160
	s_waitcnt lgkmcnt(0)
	s_barrier
	ds_read_b128 v[78:81], v38
	s_add_u32 s16, s38, 32
	s_ashr_i32 s17, s16, 11
	v_or_b32_e32 v86, s16, v34
	v_mov_b32_e32 v87, s17
	v_cmp_gt_i32_e32 vcc, s8, v86
	ds_read_b128 v[82:85], v38 offset:4096
	s_nop 0
	v_cndmask_b32_e32 v87, 8, v87, vcc
	v_cmp_eq_u32_e64 s[0:1], s15, v87
	s_nop 1
	v_cndmask_b32_e64 v87, v69, v65, s[0:1]
	v_cndmask_b32_e64 v86, v68, v64, s[0:1]
	v_cndmask_b32_e64 v89, v71, v67, s[0:1]
	v_cndmask_b32_e64 v88, v70, v66, s[0:1]
	s_waitcnt lgkmcnt(1)
	s_waitcnt vmcnt(7)
	v_pk_fma_f32 v[78:79], v[78:79], v[86:87], v[224:225]
	v_pk_fma_f32 v[80:81], v[80:81], v[88:89], v[226:227]
	global_store_dwordx4 v[52:53], v[78:81], off
	v_or_b32_e32 v86, s16, v35
	v_mov_b32_e32 v87, s17
	v_cmp_gt_i32_e32 vcc, s8, v86
	ds_read_b128 v[78:81], v38 offset:8192
	s_nop 0
	v_cndmask_b32_e32 v87, 8, v87, vcc
	v_cmp_eq_u32_e64 s[0:1], s15, v87
	s_nop 1
	v_cndmask_b32_e64 v87, v69, v65, s[0:1]
	v_cndmask_b32_e64 v86, v68, v64, s[0:1]
	v_cndmask_b32_e64 v89, v71, v67, s[0:1]
	v_cndmask_b32_e64 v88, v70, v66, s[0:1]
	s_waitcnt lgkmcnt(1)
	s_waitcnt vmcnt(7)
	v_pk_fma_f32 v[82:83], v[82:83], v[86:87], v[228:229]
	v_pk_fma_f32 v[84:85], v[84:85], v[88:89], v[230:231]
	global_store_dwordx4 v[54:55], v[82:85], off
	v_or_b32_e32 v86, s16, v36
	v_mov_b32_e32 v87, s17
	v_cmp_gt_i32_e32 vcc, s8, v86
	ds_read_b128 v[82:85], v38 offset:12288
	s_nop 0
	v_cndmask_b32_e32 v87, 8, v87, vcc
	v_cmp_eq_u32_e64 s[0:1], s15, v87
	s_nop 1
	v_cndmask_b32_e64 v87, v69, v65, s[0:1]
	v_cndmask_b32_e64 v86, v68, v64, s[0:1]
	v_cndmask_b32_e64 v89, v71, v67, s[0:1]
	v_cndmask_b32_e64 v88, v70, v66, s[0:1]
	s_waitcnt lgkmcnt(1)
	s_waitcnt vmcnt(7)
	v_pk_fma_f32 v[78:79], v[78:79], v[86:87], v[232:233]
	v_pk_fma_f32 v[80:81], v[80:81], v[88:89], v[234:235]
	global_store_dwordx4 v[56:57], v[78:81], off
	v_or_b32_e32 v86, s16, v37
	v_mov_b32_e32 v87, s17
	v_cmp_gt_i32_e32 vcc, s8, v86
	ds_read_b128 v[78:81], v38 offset:16384
	s_nop 0
	v_cndmask_b32_e32 v87, 8, v87, vcc
	v_cmp_eq_u32_e64 s[0:1], s15, v87
	s_nop 1
	v_cndmask_b32_e64 v87, v69, v65, s[0:1]
	v_cndmask_b32_e64 v86, v68, v64, s[0:1]
	v_cndmask_b32_e64 v89, v71, v67, s[0:1]
	v_cndmask_b32_e64 v88, v70, v66, s[0:1]
	s_waitcnt lgkmcnt(1)
	s_waitcnt vmcnt(7)
	v_pk_fma_f32 v[82:83], v[82:83], v[86:87], v[236:237]
	v_pk_fma_f32 v[84:85], v[84:85], v[88:89], v[238:239]
	global_store_dwordx4 v[58:59], v[82:85], off
	s_add_u32 s16, s38, 96
	s_ashr_i32 s17, s16, 11
	v_or_b32_e32 v86, s16, v34
	v_mov_b32_e32 v87, s17
	v_cmp_gt_i32_e32 vcc, s8, v86
	ds_read_b128 v[82:85], v38 offset:20480
	s_nop 0
	v_cndmask_b32_e32 v87, 8, v87, vcc
	v_cmp_eq_u32_e64 s[0:1], s15, v87
	s_nop 1
	v_cndmask_b32_e64 v87, v69, v65, s[0:1]
	v_cndmask_b32_e64 v86, v68, v64, s[0:1]
	v_cndmask_b32_e64 v89, v71, v67, s[0:1]
	v_cndmask_b32_e64 v88, v70, v66, s[0:1]
	s_waitcnt lgkmcnt(1)
	s_waitcnt vmcnt(7)
	v_pk_fma_f32 v[78:79], v[78:79], v[86:87], v[240:241]
	v_pk_fma_f32 v[80:81], v[80:81], v[88:89], v[242:243]
	global_store_dwordx4 v[60:61], v[78:81], off
	v_or_b32_e32 v86, s16, v35
	v_mov_b32_e32 v87, s17
	v_cmp_gt_i32_e32 vcc, s8, v86
	ds_read_b128 v[78:81], v38 offset:24576
	s_nop 0
	v_cndmask_b32_e32 v87, 8, v87, vcc
	v_cmp_eq_u32_e64 s[0:1], s15, v87
	s_nop 1
	v_cndmask_b32_e64 v87, v69, v65, s[0:1]
	v_cndmask_b32_e64 v86, v68, v64, s[0:1]
	v_cndmask_b32_e64 v89, v71, v67, s[0:1]
	v_cndmask_b32_e64 v88, v70, v66, s[0:1]
	s_waitcnt lgkmcnt(1)
	s_waitcnt vmcnt(7)
	v_pk_fma_f32 v[82:83], v[82:83], v[86:87], v[244:245]
	v_pk_fma_f32 v[84:85], v[84:85], v[88:89], v[246:247]
	global_store_dwordx4 v[62:63], v[82:85], off
	v_or_b32_e32 v86, s16, v36
	v_mov_b32_e32 v87, s17
	v_cmp_gt_i32_e32 vcc, s8, v86
	ds_read_b128 v[82:85], v38 offset:28672
	s_nop 0
	v_cndmask_b32_e32 v87, 8, v87, vcc
	v_cmp_eq_u32_e64 s[0:1], s15, v87
	s_nop 1
	v_cndmask_b32_e64 v87, v69, v65, s[0:1]
	v_cndmask_b32_e64 v86, v68, v64, s[0:1]
	v_cndmask_b32_e64 v89, v71, v67, s[0:1]
	v_cndmask_b32_e64 v88, v70, v66, s[0:1]
	s_waitcnt lgkmcnt(1)
	s_waitcnt vmcnt(7)
	v_pk_fma_f32 v[78:79], v[78:79], v[86:87], v[248:249]
	v_pk_fma_f32 v[80:81], v[80:81], v[88:89], v[250:251]
	global_store_dwordx4 v[44:45], v[78:81], off
	v_or_b32_e32 v86, s16, v37
	v_mov_b32_e32 v87, s17
	v_cmp_gt_i32_e32 vcc, s8, v86
	s_nop 1
	v_cndmask_b32_e32 v87, 8, v87, vcc
	v_cmp_eq_u32_e64 s[0:1], s15, v87
	s_nop 1
	v_cndmask_b32_e64 v87, v69, v65, s[0:1]
	v_cndmask_b32_e64 v86, v68, v64, s[0:1]
	v_cndmask_b32_e64 v89, v71, v67, s[0:1]
	v_cndmask_b32_e64 v88, v70, v66, s[0:1]
	s_waitcnt lgkmcnt(0)
	s_waitcnt vmcnt(7)
	v_pk_fma_f32 v[82:83], v[82:83], v[86:87], v[252:253]
	v_pk_fma_f32 v[84:85], v[84:85], v[88:89], v[254:255]
	global_store_dwordx4 v[46:47], v[82:85], off
	v_readlane_b32 s0, v218, 38
	s_add_i32 s20, s20, s0
	v_readlane_b32 s0, v221, 35
	s_cmp_lt_i32 s20, s0
	s_barrier
	s_cbranch_scc1 .LBB0_873

; template <int EPI, int MI>
; DI void gemm_tile(const GemmDesc& g, int tm, int tn, char* smem) {
;     ...
;     float* es = (float*)smem;
;     const int c4 = (tid & 31) * 4;
;     const int rgA = m0 < LAT ? (m0 >> 11) : 8;
;     const int mlast = m0 + BM - 1;
;     const int rgB = mlast < LAT ? (mlast >> 11) : 8;
;     const f32x4v m4a = *(const f32x4v*)(g.mod + (size_t)rgA * 9216 + g.gidx * 1024 + n0 + c4);
;     const f32x4v m4b = *(const f32x4v*)(g.mod + (size_t)rgB * 9216 + g.gidx * 1024 + n0 + c4);
; #pragma unroll
;     for (int mi = 0; mi < MI; ++mi) {
; #pragma unroll
;       for (int ni = 0; ni < 2; ++ni)
; #pragma unroll
;         for (int i = 0; i < 16; ++i) {
;           const int lrow = wm * 32 + (i & 3) + 8 * (i >> 2) + 4 * hh;
;           es[lrow * 128 + wn * 64 + ni * 32 + r] = acc[mi][ni][i];
;         }
;       __syncthreads();
; #pragma unroll 4
;       for (int j = 0; j < 8; ++j) {
;         const int lrow = (tid >> 5) + 8 * j;
;         const int grow = m0 + (lrow >> 5) * (32 * MI) + mi * 32 + (lrow & 31);
;         const f32x4v a4 = *(const f32x4v*)(es + lrow * 128 + c4);
;         const int rg = grow < LAT ? (grow >> 11) : 8;
;         const f32x4v m4 = rg == rgA ? m4a : m4b;
;         float* rp = (grow < LAT ? g.xres + (size_t)grow * 1024 : g.hres + (size_t)(grow - LAT) * 1024) + n0 + c4;
;         f32x4v x4 = *(const f32x4v*)rp;
;         x4 += (m4 * a4) * g.coef;
.LBB0_1291:
	s_ashr_i32 s4, s39, 11
	s_cmpk_lt_i32 s1, 0x56
	s_cselect_b32 s15, s4, 8
	s_add_i32 s4, s39, 0xbf
	s_ashr_i32 s4, s4, 11
	s_cmpk_lt_i32 s1, 0x55
	s_cselect_b32 s16, s4, 8
	s_mul_i32 s4, s15, 0x9000
	v_readlane_b32 s19, v223, 61
	s_mul_hi_i32 s1, s15, 0x9000
	s_add_u32 s17, s19, s4
	v_readlane_b32 s40, v223, 62
	s_addc_u32 s18, s40, s1
	s_ashr_i32 s1, s0, 31
	v_lshlrev_b32_e32 v98, 2, v108
	s_lshl_b64 s[4:5], s[0:1], 2
	v_and_b32_e32 v106, 0x7c, v98
	s_add_u32 s0, s17, s4
	s_addc_u32 s1, s18, s5
	v_lshlrev_b32_e32 v98, 2, v106
	v_mov_b32_e32 v99, v96
	v_lshl_add_u64 v[100:101], s[0:1], 0, v[98:99]
	s_mul_hi_i32 s0, s16, 0x9000
	s_mul_i32 s16, s16, 0x9000
	s_add_u32 s1, s19, s16
	s_addc_u32 s16, s40, s0
	s_movk_i32 s17, 0x5000
	s_add_u32 s0, s1, s4
	v_add_co_u32_e32 v100, vcc, s17, v100
	s_addc_u32 s1, s16, s5
	s_nop 0
	v_addc_co_u32_e32 v101, vcc, 0, v101, vcc
	v_lshl_add_u64 v[98:99], s[0:1], 0, v[98:99]
	v_add_co_u32_e32 v102, vcc, s17, v98
	v_and_b32_e32 v107, 64, v108
	s_nop 0
	v_addc_co_u32_e32 v103, vcc, 0, v99, vcc
	global_load_dwordx4 v[98:101], v[100:101], off
	s_nop 0
	global_load_dwordx4 v[102:105], v[102:103], off
	v_lshlrev_b32_e32 v115, 11, v115
	v_lshlrev_b32_e32 v107, 2, v107
	v_lshlrev_b32_e32 v109, 14, v109
	v_add3_u32 v115, 0, v115, v107
	v_lshlrev_b32_e32 v120, 2, v97
	v_ashrrev_i32_e32 v107, 5, v108
	v_add3_u32 v108, v115, v120, v109
	ds_write2_b32 v108, v64, v80 offset1:32
	ds_write2_b32 v108, v65, v81 offset0:128 offset1:160
	v_add_u32_e32 v80, 0x400, v108
	v_add_u32_e32 v64, 8, v107
	ds_write2_b32 v80, v66, v82 offset1:32
	ds_write2_b32 v80, v67, v83 offset0:128 offset1:160
	v_add_u32_e32 v81, 0x1000, v108
	v_add_u32_e32 v82, 0x1400, v108
	v_and_b32_e32 v67, 31, v64
	v_add_u32_e32 v64, 24, v107
	ds_write2_b32 v81, v68, v84 offset1:32
	ds_write2_b32 v81, v69, v85 offset0:128 offset1:160
	ds_write2_b32 v82, v70, v86 offset1:32
	ds_write2_b32 v82, v71, v87 offset0:128 offset1:160
	v_add_u32_e32 v71, 0x2000, v108
	v_and_b32_e32 v69, 31, v64
	v_lshlrev_b32_e32 v64, 4, v97
	ds_write2_b32 v71, v72, v88 offset1:32
	ds_write2_b32 v71, v73, v89 offset0:128 offset1:160
	v_add_u32_e32 v72, 0x2400, v108
	v_lshl_or_b32 v64, v107, 9, v64
	s_mov_b32 s16, 0
	ds_write2_b32 v72, v74, v90 offset1:32
	ds_write2_b32 v72, v75, v91 offset0:128 offset1:160
	v_add_u32_e32 v73, 0x3000, v108
	v_add_u32_e32 v74, 0x3400, v108
	v_and_b32_e32 v66, 31, v107
	v_bitop3_b32 v68, v107, 16, 31 bitop3:0x6c
	v_add_u32_e32 v70, 0, v64
	v_mov_b32_e32 v75, v107
	ds_write2_b32 v73, v76, v92 offset1:32
	ds_write2_b32 v73, v77, v93 offset0:128 offset1:160
	ds_write2_b32 v74, v78, v94 offset1:32
	ds_write2_b32 v74, v79, v95 offset0:128 offset1:160
	v_lshlrev_b32_e32 v64, 2, v106
	v_mov_b32_e32 v65, 0
	s_mov_b32 s16, s39
	v_or_b32_e32 v224, s16, v66
	v_mov_b32_e32 v226, s68
	v_mov_b32_e32 v227, s69
	v_mov_b32_e32 v162, s3
	v_mov_b32_e32 v163, s33
	v_cmp_gt_i32_e32 vcc, s8, v224
	v_add_u32_e32 v225, 0xffffc000, v224
	s_nop 0
	v_cndmask_b32_e32 v224, v225, v224, vcc
	v_cndmask_b32_e32 v226, v162, v226, vcc
	v_cndmask_b32_e32 v227, v163, v227, vcc
	v_mov_b32_e32 v225, 0
	v_lshlrev_b64 v[224:225], 12, v[224:225]
	v_lshl_add_u64 v[224:225], v[226:227], 0, v[224:225]
	v_lshl_add_u64 v[224:225], v[224:225], 0, s[4:5]
	v_lshl_add_u64 v[162:163], v[224:225], 0, v[64:65]
	global_load_dwordx4 v[224:227], v[162:163], off
	v_or_b32_e32 v228, s16, v67
	v_mov_b32_e32 v230, s68
	v_mov_b32_e32 v231, s69
	v_mov_b32_e32 v164, s3
	v_mov_b32_e32 v165, s33
	v_cmp_gt_i32_e32 vcc, s8, v228
	v_add_u32_e32 v229, 0xffffc000, v228
	s_nop 0
	v_cndmask_b32_e32 v228, v229, v228, vcc
	v_cndmask_b32_e32 v230, v164, v230, vcc
	v_cndmask_b32_e32 v231, v165, v231, vcc
	v_mov_b32_e32 v229, 0
	v_lshlrev_b64 v[228:229], 12, v[228:229]
	v_lshl_add_u64 v[228:229], v[230:231], 0, v[228:229]
	v_lshl_add_u64 v[228:229], v[228:229], 0, s[4:5]
	v_lshl_add_u64 v[164:165], v[228:229], 0, v[64:65]
	global_load_dwordx4 v[228:231], v[164:165], off
	v_or_b32_e32 v232, s16, v68
	v_mov_b32_e32 v234, s68
	v_mov_b32_e32 v235, s69
	v_mov_b32_e32 v166, s3
	v_mov_b32_e32 v167, s33
	v_cmp_gt_i32_e32 vcc, s8, v232
	v_add_u32_e32 v233, 0xffffc000, v232
	s_nop 0
	v_cndmask_b32_e32 v232, v233, v232, vcc
	v_cndmask_b32_e32 v234, v166, v234, vcc
	v_cndmask_b32_e32 v235, v167, v235, vcc
	v_mov_b32_e32 v233, 0
	v_lshlrev_b64 v[232:233], 12, v[232:233]
	v_lshl_add_u64 v[232:233], v[234:235], 0, v[232:233]
	v_lshl_add_u64 v[232:233], v[232:233], 0, s[4:5]
	v_lshl_add_u64 v[166:167], v[232:233], 0, v[64:65]
	global_load_dwordx4 v[232:235], v[166:167], off
	v_or_b32_e32 v236, s16, v69
	v_mov_b32_e32 v238, s68
	v_mov_b32_e32 v239, s69
	v_mov_b32_e32 v168, s3
	v_mov_b32_e32 v169, s33
	v_cmp_gt_i32_e32 vcc, s8, v236
	v_add_u32_e32 v237, 0xffffc000, v236
	s_nop 0
	v_cndmask_b32_e32 v236, v237, v236, vcc
	v_cndmask_b32_e32 v238, v168, v238, vcc
	v_cndmask_b32_e32 v239, v169, v239, vcc
	v_mov_b32_e32 v237, 0
	v_lshlrev_b64 v[236:237], 12, v[236:237]
	v_lshl_add_u64 v[236:237], v[238:239], 0, v[236:237]
	v_lshl_add_u64 v[236:237], v[236:237], 0, s[4:5]
	v_lshl_add_u64 v[168:169], v[236:237], 0, v[64:65]
	global_load_dwordx4 v[236:239], v[168:169], off
	s_add_u32 s16, s39, 96
	v_or_b32_e32 v240, s16, v66
	v_mov_b32_e32 v242, s68
	v_mov_b32_e32 v243, s69
	v_mov_b32_e32 v170, s3
	v_mov_b32_e32 v171, s33
	v_cmp_gt_i32_e32 vcc, s8, v240
	v_add_u32_e32 v241, 0xffffc000, v240
	s_nop 0
	v_cndmask_b32_e32 v240, v241, v240, vcc
	v_cndmask_b32_e32 v242, v170, v242, vcc
	v_cndmask_b32_e32 v243, v171, v243, vcc
	v_mov_b32_e32 v241, 0
	v_lshlrev_b64 v[240:241], 12, v[240:241]
	v_lshl_add_u64 v[240:241], v[242:243], 0, v[240:241]
; template <int EPI, int MI>
; DI void gemm_tile(const GemmDesc& g, int tm, int tn, char* smem) {
;     ...
; #pragma unroll 4
;       for (int j = 0; j < 8; ++j) {
;         const int lrow = (tid >> 5) + 8 * j;
;         const int grow = m0 + (lrow >> 5) * (32 * MI) + mi * 32 + (lrow & 31);
;         const f32x4v a4 = *(const f32x4v*)(es + lrow * 128 + c4);
;         const int rg = grow < LAT ? (grow >> 11) : 8;
;         const f32x4v m4 = rg == rgA ? m4a : m4b;
;         float* rp = (grow < LAT ? g.xres + (size_t)grow * 1024 : g.hres + (size_t)(grow - LAT) * 1024) + n0 + c4;
;         f32x4v x4 = *(const f32x4v*)rp;
;         x4 += (m4 * a4) * g.coef;
;         *(f32x4v*)rp = x4;
;       }
	v_lshl_add_u64 v[240:241], v[240:241], 0, s[4:5]
	v_lshl_add_u64 v[170:171], v[240:241], 0, v[64:65]
	global_load_dwordx4 v[240:243], v[170:171], off
	v_or_b32_e32 v244, s16, v67
	v_mov_b32_e32 v246, s68
	v_mov_b32_e32 v247, s69
	v_mov_b32_e32 v172, s3
	v_mov_b32_e32 v173, s33
	v_cmp_gt_i32_e32 vcc, s8, v244
	v_add_u32_e32 v245, 0xffffc000, v244
	s_nop 0
	v_cndmask_b32_e32 v244, v245, v244, vcc
	v_cndmask_b32_e32 v246, v172, v246, vcc
	v_cndmask_b32_e32 v247, v173, v247, vcc
	v_mov_b32_e32 v245, 0
	v_lshlrev_b64 v[244:245], 12, v[244:245]
	v_lshl_add_u64 v[244:245], v[246:247], 0, v[244:245]
	v_lshl_add_u64 v[244:245], v[244:245], 0, s[4:5]
	v_lshl_add_u64 v[172:173], v[244:245], 0, v[64:65]
	global_load_dwordx4 v[244:247], v[172:173], off
	v_or_b32_e32 v248, s16, v68
	v_mov_b32_e32 v250, s68
	v_mov_b32_e32 v251, s69
	v_mov_b32_e32 v174, s3
	v_mov_b32_e32 v175, s33
	v_cmp_gt_i32_e32 vcc, s8, v248
	v_add_u32_e32 v249, 0xffffc000, v248
	s_nop 0
	v_cndmask_b32_e32 v248, v249, v248, vcc
	v_cndmask_b32_e32 v250, v174, v250, vcc
	v_cndmask_b32_e32 v251, v175, v251, vcc
	v_mov_b32_e32 v249, 0
	v_lshlrev_b64 v[248:249], 12, v[248:249]
	v_lshl_add_u64 v[248:249], v[250:251], 0, v[248:249]
	v_lshl_add_u64 v[248:249], v[248:249], 0, s[4:5]
	v_lshl_add_u64 v[174:175], v[248:249], 0, v[64:65]
	global_load_dwordx4 v[248:251], v[174:175], off
	v_or_b32_e32 v252, s16, v69
	v_mov_b32_e32 v254, s68
	v_mov_b32_e32 v255, s69
	v_mov_b32_e32 v176, s3
	v_mov_b32_e32 v177, s33
	v_cmp_gt_i32_e32 vcc, s8, v252
	v_add_u32_e32 v253, 0xffffc000, v252
	s_nop 0
	v_cndmask_b32_e32 v252, v253, v252, vcc
	v_cndmask_b32_e32 v254, v176, v254, vcc
	v_cndmask_b32_e32 v255, v177, v255, vcc
	v_mov_b32_e32 v253, 0
	v_lshlrev_b64 v[252:253], 12, v[252:253]
	v_lshl_add_u64 v[252:253], v[254:255], 0, v[252:253]
	v_lshl_add_u64 v[252:253], v[252:253], 0, s[4:5]
	v_lshl_add_u64 v[176:177], v[252:253], 0, v[64:65]
	global_load_dwordx4 v[252:255], v[176:177], off
	s_waitcnt lgkmcnt(0)
	s_barrier
	s_waitcnt vmcnt(8)
	ds_read_b128 v[84:87], v70
	s_mov_b32 s16, s39
	s_ashr_i32 s17, s16, 11
	v_or_b32_e32 v88, s16, v66
	v_mov_b32_e32 v89, s17
	v_cmp_gt_i32_e32 vcc, s8, v88
	ds_read_b128 v[92:95], v70 offset:4096
	s_nop 0
	v_cndmask_b32_e32 v89, 8, v89, vcc
	v_cmp_eq_u32_e64 s[0:1], s15, v89
	s_nop 1
	v_cndmask_b32_e64 v89, v103, v99, s[0:1]
	v_cndmask_b32_e64 v88, v102, v98, s[0:1]
	v_cndmask_b32_e64 v91, v105, v101, s[0:1]
	v_cndmask_b32_e64 v90, v104, v100, s[0:1]
	s_waitcnt lgkmcnt(1)
	s_waitcnt vmcnt(7)
	v_pk_fma_f32 v[84:85], v[84:85], v[88:89], v[224:225]
	v_pk_fma_f32 v[86:87], v[86:87], v[90:91], v[226:227]
	global_store_dwordx4 v[162:163], v[84:87], off
	v_or_b32_e32 v88, s16, v67
	v_mov_b32_e32 v89, s17
	v_cmp_gt_i32_e32 vcc, s8, v88
	ds_read_b128 v[84:87], v70 offset:8192
	s_nop 0
	v_cndmask_b32_e32 v89, 8, v89, vcc
	v_cmp_eq_u32_e64 s[0:1], s15, v89
	s_nop 1
	v_cndmask_b32_e64 v89, v103, v99, s[0:1]
	v_cndmask_b32_e64 v88, v102, v98, s[0:1]
	v_cndmask_b32_e64 v91, v105, v101, s[0:1]
	v_cndmask_b32_e64 v90, v104, v100, s[0:1]
	s_waitcnt lgkmcnt(1)
	s_waitcnt vmcnt(7)
	v_pk_fma_f32 v[92:93], v[92:93], v[88:89], v[228:229]
	v_pk_fma_f32 v[94:95], v[94:95], v[90:91], v[230:231]
	global_store_dwordx4 v[164:165], v[92:95], off
	v_or_b32_e32 v88, s16, v68
	v_mov_b32_e32 v89, s17
	v_cmp_gt_i32_e32 vcc, s8, v88
	ds_read_b128 v[92:95], v70 offset:12288
	s_nop 0
	v_cndmask_b32_e32 v89, 8, v89, vcc
	v_cmp_eq_u32_e64 s[0:1], s15, v89
	s_nop 1
	v_cndmask_b32_e64 v89, v103, v99, s[0:1]
	v_cndmask_b32_e64 v88, v102, v98, s[0:1]
	v_cndmask_b32_e64 v91, v105, v101, s[0:1]
	v_cndmask_b32_e64 v90, v104, v100, s[0:1]
	s_waitcnt lgkmcnt(1)
	s_waitcnt vmcnt(7)
	v_pk_fma_f32 v[84:85], v[84:85], v[88:89], v[232:233]
	v_pk_fma_f32 v[86:87], v[86:87], v[90:91], v[234:235]
	global_store_dwordx4 v[166:167], v[84:87], off
	v_or_b32_e32 v88, s16, v69
	v_mov_b32_e32 v89, s17
	v_cmp_gt_i32_e32 vcc, s8, v88
	ds_read_b128 v[84:87], v70 offset:16384
	s_nop 0
	v_cndmask_b32_e32 v89, 8, v89, vcc
	v_cmp_eq_u32_e64 s[0:1], s15, v89
	s_nop 1
	v_cndmask_b32_e64 v89, v103, v99, s[0:1]
	v_cndmask_b32_e64 v88, v102, v98, s[0:1]
	v_cndmask_b32_e64 v91, v105, v101, s[0:1]
	v_cndmask_b32_e64 v90, v104, v100, s[0:1]
	s_waitcnt lgkmcnt(1)
	s_waitcnt vmcnt(7)
	v_pk_fma_f32 v[92:93], v[92:93], v[88:89], v[236:237]
	v_pk_fma_f32 v[94:95], v[94:95], v[90:91], v[238:239]
	global_store_dwordx4 v[168:169], v[92:95], off
	s_add_u32 s16, s39, 96
	s_ashr_i32 s17, s16, 11
	v_or_b32_e32 v88, s16, v66
	v_mov_b32_e32 v89, s17
	v_cmp_gt_i32_e32 vcc, s8, v88
	ds_read_b128 v[92:95], v70 offset:20480
	s_nop 0
	v_cndmask_b32_e32 v89, 8, v89, vcc
	v_cmp_eq_u32_e64 s[0:1], s15, v89
	s_nop 1
	v_cndmask_b32_e64 v89, v103, v99, s[0:1]
	v_cndmask_b32_e64 v88, v102, v98, s[0:1]
	v_cndmask_b32_e64 v91, v105, v101, s[0:1]
	v_cndmask_b32_e64 v90, v104, v100, s[0:1]
	s_waitcnt lgkmcnt(1)
	s_waitcnt vmcnt(7)
	v_pk_fma_f32 v[84:85], v[84:85], v[88:89], v[240:241]
	v_pk_fma_f32 v[86:87], v[86:87], v[90:91], v[242:243]
	global_store_dwordx4 v[170:171], v[84:87], off
	v_or_b32_e32 v88, s16, v67
	v_mov_b32_e32 v89, s17
	v_cmp_gt_i32_e32 vcc, s8, v88
	ds_read_b128 v[84:87], v70 offset:24576
	s_nop 0
	v_cndmask_b32_e32 v89, 8, v89, vcc
	v_cmp_eq_u32_e64 s[0:1], s15, v89
	s_nop 1
	v_cndmask_b32_e64 v89, v103, v99, s[0:1]
	v_cndmask_b32_e64 v88, v102, v98, s[0:1]
	v_cndmask_b32_e64 v91, v105, v101, s[0:1]
	v_cndmask_b32_e64 v90, v104, v100, s[0:1]
	s_waitcnt lgkmcnt(1)
	s_waitcnt vmcnt(7)
; template <int EPI, int MI>
; DI void gemm_tile(const GemmDesc& g, int tm, int tn, char* smem) {
;     ...
; #pragma unroll 4
;       for (int j = 0; j < 8; ++j) {
;         const int lrow = (tid >> 5) + 8 * j;
;         const int grow = m0 + (lrow >> 5) * (32 * MI) + mi * 32 + (lrow & 31);
;         const f32x4v a4 = *(const f32x4v*)(es + lrow * 128 + c4);
;         const int rg = grow < LAT ? (grow >> 11) : 8;
;         const f32x4v m4 = rg == rgA ? m4a : m4b;
;         float* rp = (grow < LAT ? g.xres + (size_t)grow * 1024 : g.hres + (size_t)(grow - LAT) * 1024) + n0 + c4;
;         f32x4v x4 = *(const f32x4v*)rp;
;         x4 += (m4 * a4) * g.coef;
;         *(f32x4v*)rp = x4;
;       }
	v_pk_fma_f32 v[92:93], v[92:93], v[88:89], v[244:245]
	v_pk_fma_f32 v[94:95], v[94:95], v[90:91], v[246:247]
	global_store_dwordx4 v[172:173], v[92:95], off
	v_or_b32_e32 v88, s16, v68
	v_mov_b32_e32 v89, s17
	v_cmp_gt_i32_e32 vcc, s8, v88
	ds_read_b128 v[92:95], v70 offset:28672
	s_nop 0
	v_cndmask_b32_e32 v89, 8, v89, vcc
	v_cmp_eq_u32_e64 s[0:1], s15, v89
	s_nop 1
	v_cndmask_b32_e64 v89, v103, v99, s[0:1]
	v_cndmask_b32_e64 v88, v102, v98, s[0:1]
	v_cndmask_b32_e64 v91, v105, v101, s[0:1]
	v_cndmask_b32_e64 v90, v104, v100, s[0:1]
	s_waitcnt lgkmcnt(1)
	s_waitcnt vmcnt(7)
	v_pk_fma_f32 v[84:85], v[84:85], v[88:89], v[248:249]
	v_pk_fma_f32 v[86:87], v[86:87], v[90:91], v[250:251]
	global_store_dwordx4 v[174:175], v[84:87], off
	v_or_b32_e32 v88, s16, v69
	v_mov_b32_e32 v89, s17
	v_cmp_gt_i32_e32 vcc, s8, v88
	s_nop 1
	v_cndmask_b32_e32 v89, 8, v89, vcc
	v_cmp_eq_u32_e64 s[0:1], s15, v89
	s_nop 1
	v_cndmask_b32_e64 v89, v103, v99, s[0:1]
	v_cndmask_b32_e64 v88, v102, v98, s[0:1]
	v_cndmask_b32_e64 v91, v105, v101, s[0:1]
	v_cndmask_b32_e64 v90, v104, v100, s[0:1]
	s_waitcnt lgkmcnt(0)
	s_waitcnt vmcnt(7)
	v_pk_fma_f32 v[92:93], v[92:93], v[88:89], v[252:253]
	v_pk_fma_f32 v[94:95], v[94:95], v[90:91], v[254:255]
	global_store_dwordx4 v[176:177], v[92:95], off
	s_add_u32 s16, s39, 32
	v_or_b32_e32 v224, s16, v66
	v_mov_b32_e32 v226, s68
	v_mov_b32_e32 v227, s69
	v_mov_b32_e32 v162, s3
	v_mov_b32_e32 v163, s33
	v_cmp_gt_i32_e32 vcc, s8, v224
	v_add_u32_e32 v225, 0xffffc000, v224
	s_nop 0
	v_cndmask_b32_e32 v224, v225, v224, vcc
	v_cndmask_b32_e32 v226, v162, v226, vcc
	v_cndmask_b32_e32 v227, v163, v227, vcc
	v_mov_b32_e32 v225, 0
	v_lshlrev_b64 v[224:225], 12, v[224:225]
	v_lshl_add_u64 v[224:225], v[226:227], 0, v[224:225]
	v_lshl_add_u64 v[224:225], v[224:225], 0, s[4:5]
	v_lshl_add_u64 v[162:163], v[224:225], 0, v[64:65]
	global_load_dwordx4 v[224:227], v[162:163], off
	v_or_b32_e32 v228, s16, v67
	v_mov_b32_e32 v230, s68
	v_mov_b32_e32 v231, s69
	v_mov_b32_e32 v164, s3
	v_mov_b32_e32 v165, s33
	v_cmp_gt_i32_e32 vcc, s8, v228
	v_add_u32_e32 v229, 0xffffc000, v228
	s_nop 0
	v_cndmask_b32_e32 v228, v229, v228, vcc
	v_cndmask_b32_e32 v230, v164, v230, vcc
	v_cndmask_b32_e32 v231, v165, v231, vcc
	v_mov_b32_e32 v229, 0
	v_lshlrev_b64 v[228:229], 12, v[228:229]
	v_lshl_add_u64 v[228:229], v[230:231], 0, v[228:229]
	v_lshl_add_u64 v[228:229], v[228:229], 0, s[4:5]
	v_lshl_add_u64 v[164:165], v[228:229], 0, v[64:65]
	global_load_dwordx4 v[228:231], v[164:165], off
	v_or_b32_e32 v232, s16, v68
	v_mov_b32_e32 v234, s68
	v_mov_b32_e32 v235, s69
	v_mov_b32_e32 v166, s3
	v_mov_b32_e32 v167, s33
	v_cmp_gt_i32_e32 vcc, s8, v232
	v_add_u32_e32 v233, 0xffffc000, v232
	s_nop 0
	v_cndmask_b32_e32 v232, v233, v232, vcc
	v_cndmask_b32_e32 v234, v166, v234, vcc
	v_cndmask_b32_e32 v235, v167, v235, vcc
	v_mov_b32_e32 v233, 0
	v_lshlrev_b64 v[232:233], 12, v[232:233]
	v_lshl_add_u64 v[232:233], v[234:235], 0, v[232:233]
	v_lshl_add_u64 v[232:233], v[232:233], 0, s[4:5]
	v_lshl_add_u64 v[166:167], v[232:233], 0, v[64:65]
	global_load_dwordx4 v[232:235], v[166:167], off
	v_or_b32_e32 v236, s16, v69
	v_mov_b32_e32 v238, s68
	v_mov_b32_e32 v239, s69
	v_mov_b32_e32 v168, s3
	v_mov_b32_e32 v169, s33
	v_cmp_gt_i32_e32 vcc, s8, v236
	v_add_u32_e32 v237, 0xffffc000, v236
	s_nop 0
	v_cndmask_b32_e32 v236, v237, v236, vcc
	v_cndmask_b32_e32 v238, v168, v238, vcc
	v_cndmask_b32_e32 v239, v169, v239, vcc
	v_mov_b32_e32 v237, 0
	v_lshlrev_b64 v[236:237], 12, v[236:237]
	v_lshl_add_u64 v[236:237], v[238:239], 0, v[236:237]
	v_lshl_add_u64 v[236:237], v[236:237], 0, s[4:5]
	v_lshl_add_u64 v[168:169], v[236:237], 0, v[64:65]
	global_load_dwordx4 v[236:239], v[168:169], off
	s_add_u32 s16, s39, 128
	v_or_b32_e32 v240, s16, v66
	v_mov_b32_e32 v242, s68
	v_mov_b32_e32 v243, s69
	v_mov_b32_e32 v170, s3
	v_mov_b32_e32 v171, s33
	v_cmp_gt_i32_e32 vcc, s8, v240
	v_add_u32_e32 v241, 0xffffc000, v240
	s_nop 0
	v_cndmask_b32_e32 v240, v241, v240, vcc
	v_cndmask_b32_e32 v242, v170, v242, vcc
	v_cndmask_b32_e32 v243, v171, v243, vcc
	v_mov_b32_e32 v241, 0
	v_lshlrev_b64 v[240:241], 12, v[240:241]
	v_lshl_add_u64 v[240:241], v[242:243], 0, v[240:241]
	v_lshl_add_u64 v[240:241], v[240:241], 0, s[4:5]
	v_lshl_add_u64 v[170:171], v[240:241], 0, v[64:65]
	global_load_dwordx4 v[240:243], v[170:171], off
	v_or_b32_e32 v244, s16, v67
	v_mov_b32_e32 v246, s68
	v_mov_b32_e32 v247, s69
	v_mov_b32_e32 v172, s3
	v_mov_b32_e32 v173, s33
	v_cmp_gt_i32_e32 vcc, s8, v244
	v_add_u32_e32 v245, 0xffffc000, v244
	s_nop 0
	v_cndmask_b32_e32 v244, v245, v244, vcc
	v_cndmask_b32_e32 v246, v172, v246, vcc
	v_cndmask_b32_e32 v247, v173, v247, vcc
	v_mov_b32_e32 v245, 0
	v_lshlrev_b64 v[244:245], 12, v[244:245]
	v_lshl_add_u64 v[244:245], v[246:247], 0, v[244:245]
	v_lshl_add_u64 v[244:245], v[244:245], 0, s[4:5]
	v_lshl_add_u64 v[172:173], v[244:245], 0, v[64:65]
	global_load_dwordx4 v[244:247], v[172:173], off
	v_or_b32_e32 v248, s16, v68
	v_mov_b32_e32 v250, s68
	v_mov_b32_e32 v251, s69
	v_mov_b32_e32 v174, s3
	v_mov_b32_e32 v175, s33
	v_cmp_gt_i32_e32 vcc, s8, v248
	v_add_u32_e32 v249, 0xffffc000, v248
	s_nop 0
	v_cndmask_b32_e32 v248, v249, v248, vcc
	v_cndmask_b32_e32 v250, v174, v250, vcc
	v_cndmask_b32_e32 v251, v175, v251, vcc
	v_mov_b32_e32 v249, 0
	v_lshlrev_b64 v[248:249], 12, v[248:249]
	v_lshl_add_u64 v[248:249], v[250:251], 0, v[248:249]
	v_lshl_add_u64 v[248:249], v[248:249], 0, s[4:5]
	v_lshl_add_u64 v[174:175], v[248:249], 0, v[64:65]
	global_load_dwordx4 v[248:251], v[174:175], off
	v_or_b32_e32 v252, s16, v69
	v_mov_b32_e32 v254, s68
	v_mov_b32_e32 v255, s69
	v_mov_b32_e32 v176, s3
	v_mov_b32_e32 v177, s33
	v_cmp_gt_i32_e32 vcc, s8, v252
	v_add_u32_e32 v253, 0xffffc000, v252
	s_nop 0
	v_cndmask_b32_e32 v252, v253, v252, vcc
	v_cndmask_b32_e32 v254, v176, v254, vcc
	v_cndmask_b32_e32 v255, v177, v255, vcc
	v_mov_b32_e32 v253, 0
	v_lshlrev_b64 v[252:253], 12, v[252:253]
	v_lshl_add_u64 v[252:253], v[254:255], 0, v[252:253]
	v_lshl_add_u64 v[252:253], v[252:253], 0, s[4:5]
	v_lshl_add_u64 v[176:177], v[252:253], 0, v[64:65]
	global_load_dwordx4 v[252:255], v[176:177], off
	s_barrier
; template <int EPI, int MI>
; DI void gemm_tile(const GemmDesc& g, int tm, int tn, char* smem) {
;     ...
;     for (int mi = 0; mi < MI; ++mi) {
; #pragma unroll
;       for (int ni = 0; ni < 2; ++ni)
; #pragma unroll
;         for (int i = 0; i < 16; ++i) {
;           const int lrow = wm * 32 + (i & 3) + 8 * (i >> 2) + 4 * hh;
;           es[lrow * 128 + wn * 64 + ni * 32 + r] = acc[mi][ni][i];
;         }
;       __syncthreads();
; #pragma unroll 4
;       for (int j = 0; j < 8; ++j) {
;         const int lrow = (tid >> 5) + 8 * j;
;         const int grow = m0 + (lrow >> 5) * (32 * MI) + mi * 32 + (lrow & 31);
;         const f32x4v a4 = *(const f32x4v*)(es + lrow * 128 + c4);
;         const int rg = grow < LAT ? (grow >> 11) : 8;
;         const f32x4v m4 = rg == rgA ? m4a : m4b;
;         float* rp = (grow < LAT ? g.xres + (size_t)grow * 1024 : g.hres + (size_t)(grow - LAT) * 1024) + n0 + c4;
;         f32x4v x4 = *(const f32x4v*)rp;
;         x4 += (m4 * a4) * g.coef;
;         *(f32x4v*)rp = x4;
;       }
	ds_write2_b32 v108, v32, v48 offset1:32
	ds_write2_b32 v108, v33, v49 offset0:128 offset1:160
	ds_write2_b32 v80, v34, v50 offset1:32
	ds_write2_b32 v80, v35, v51 offset0:128 offset1:160
	ds_write2_b32 v81, v36, v52 offset1:32
	ds_write2_b32 v81, v37, v53 offset0:128 offset1:160
	ds_write2_b32 v82, v38, v54 offset1:32
	ds_write2_b32 v82, v39, v55 offset0:128 offset1:160
	ds_write2_b32 v71, v40, v56 offset1:32
	ds_write2_b32 v71, v41, v57 offset0:128 offset1:160
	ds_write2_b32 v72, v42, v58 offset1:32
	ds_write2_b32 v72, v43, v59 offset0:128 offset1:160
	ds_write2_b32 v73, v44, v60 offset1:32
	ds_write2_b32 v73, v45, v61 offset0:128 offset1:160
	ds_write2_b32 v74, v46, v62 offset1:32
	ds_write2_b32 v74, v47, v63 offset0:128 offset1:160
	s_or_b32 s16, s39, 32
	s_mov_b32 s17, 0
	v_mov_b32_e32 v32, v107
	s_waitcnt lgkmcnt(0)
	s_barrier
	ds_read_b128 v[84:87], v70
	s_add_u32 s16, s39, 32
	s_ashr_i32 s17, s16, 11
	v_or_b32_e32 v88, s16, v66
	v_mov_b32_e32 v89, s17
	v_cmp_gt_i32_e32 vcc, s8, v88
	ds_read_b128 v[92:95], v70 offset:4096
	s_nop 0
	v_cndmask_b32_e32 v89, 8, v89, vcc
	v_cmp_eq_u32_e64 s[0:1], s15, v89
	s_nop 1
	v_cndmask_b32_e64 v89, v103, v99, s[0:1]
	v_cndmask_b32_e64 v88, v102, v98, s[0:1]
	v_cndmask_b32_e64 v91, v105, v101, s[0:1]
	v_cndmask_b32_e64 v90, v104, v100, s[0:1]
	s_waitcnt lgkmcnt(1)
	s_waitcnt vmcnt(7)
	v_pk_fma_f32 v[84:85], v[84:85], v[88:89], v[224:225]
	v_pk_fma_f32 v[86:87], v[86:87], v[90:91], v[226:227]
	global_store_dwordx4 v[162:163], v[84:87], off
	v_or_b32_e32 v88, s16, v67
	v_mov_b32_e32 v89, s17
	v_cmp_gt_i32_e32 vcc, s8, v88
	ds_read_b128 v[84:87], v70 offset:8192
	s_nop 0
	v_cndmask_b32_e32 v89, 8, v89, vcc
	v_cmp_eq_u32_e64 s[0:1], s15, v89
	s_nop 1
	v_cndmask_b32_e64 v89, v103, v99, s[0:1]
	v_cndmask_b32_e64 v88, v102, v98, s[0:1]
	v_cndmask_b32_e64 v91, v105, v101, s[0:1]
	v_cndmask_b32_e64 v90, v104, v100, s[0:1]
	s_waitcnt lgkmcnt(1)
	s_waitcnt vmcnt(7)
	v_pk_fma_f32 v[92:93], v[92:93], v[88:89], v[228:229]
	v_pk_fma_f32 v[94:95], v[94:95], v[90:91], v[230:231]
	global_store_dwordx4 v[164:165], v[92:95], off
	v_or_b32_e32 v88, s16, v68
	v_mov_b32_e32 v89, s17
	v_cmp_gt_i32_e32 vcc, s8, v88
	ds_read_b128 v[92:95], v70 offset:12288
	s_nop 0
	v_cndmask_b32_e32 v89, 8, v89, vcc
	v_cmp_eq_u32_e64 s[0:1], s15, v89
	s_nop 1
	v_cndmask_b32_e64 v89, v103, v99, s[0:1]
	v_cndmask_b32_e64 v88, v102, v98, s[0:1]
	v_cndmask_b32_e64 v91, v105, v101, s[0:1]
	v_cndmask_b32_e64 v90, v104, v100, s[0:1]
	s_waitcnt lgkmcnt(1)
	s_waitcnt vmcnt(7)
	v_pk_fma_f32 v[84:85], v[84:85], v[88:89], v[232:233]
	v_pk_fma_f32 v[86:87], v[86:87], v[90:91], v[234:235]
	global_store_dwordx4 v[166:167], v[84:87], off
	v_or_b32_e32 v88, s16, v69
	v_mov_b32_e32 v89, s17
	v_cmp_gt_i32_e32 vcc, s8, v88
	ds_read_b128 v[84:87], v70 offset:16384
	s_nop 0
	v_cndmask_b32_e32 v89, 8, v89, vcc
	v_cmp_eq_u32_e64 s[0:1], s15, v89
	s_nop 1
	v_cndmask_b32_e64 v89, v103, v99, s[0:1]
	v_cndmask_b32_e64 v88, v102, v98, s[0:1]
	v_cndmask_b32_e64 v91, v105, v101, s[0:1]
	v_cndmask_b32_e64 v90, v104, v100, s[0:1]
	s_waitcnt lgkmcnt(1)
	s_waitcnt vmcnt(7)
	v_pk_fma_f32 v[92:93], v[92:93], v[88:89], v[236:237]
	v_pk_fma_f32 v[94:95], v[94:95], v[90:91], v[238:239]
	global_store_dwordx4 v[168:169], v[92:95], off
	s_add_u32 s16, s39, 128
	s_ashr_i32 s17, s16, 11
	v_or_b32_e32 v88, s16, v66
	v_mov_b32_e32 v89, s17
	v_cmp_gt_i32_e32 vcc, s8, v88
	ds_read_b128 v[92:95], v70 offset:20480
	s_nop 0
	v_cndmask_b32_e32 v89, 8, v89, vcc
	v_cmp_eq_u32_e64 s[0:1], s15, v89
	s_nop 1
	v_cndmask_b32_e64 v89, v103, v99, s[0:1]
	v_cndmask_b32_e64 v88, v102, v98, s[0:1]
	v_cndmask_b32_e64 v91, v105, v101, s[0:1]
	v_cndmask_b32_e64 v90, v104, v100, s[0:1]
	s_waitcnt lgkmcnt(1)
	s_waitcnt vmcnt(7)
	v_pk_fma_f32 v[84:85], v[84:85], v[88:89], v[240:241]
	v_pk_fma_f32 v[86:87], v[86:87], v[90:91], v[242:243]
	global_store_dwordx4 v[170:171], v[84:87], off
	v_or_b32_e32 v88, s16, v67
	v_mov_b32_e32 v89, s17
	v_cmp_gt_i32_e32 vcc, s8, v88
	ds_read_b128 v[84:87], v70 offset:24576
	s_nop 0
	v_cndmask_b32_e32 v89, 8, v89, vcc
	v_cmp_eq_u32_e64 s[0:1], s15, v89
	s_nop 1
	v_cndmask_b32_e64 v89, v103, v99, s[0:1]
	v_cndmask_b32_e64 v88, v102, v98, s[0:1]
	v_cndmask_b32_e64 v91, v105, v101, s[0:1]
	v_cndmask_b32_e64 v90, v104, v100, s[0:1]
	s_waitcnt lgkmcnt(1)
	s_waitcnt vmcnt(7)
	v_pk_fma_f32 v[92:93], v[92:93], v[88:89], v[244:245]
	v_pk_fma_f32 v[94:95], v[94:95], v[90:91], v[246:247]
	global_store_dwordx4 v[172:173], v[92:95], off
	v_or_b32_e32 v88, s16, v68
	v_mov_b32_e32 v89, s17
	v_cmp_gt_i32_e32 vcc, s8, v88
	ds_read_b128 v[92:95], v70 offset:28672
	s_nop 0
	v_cndmask_b32_e32 v89, 8, v89, vcc
	v_cmp_eq_u32_e64 s[0:1], s15, v89
	s_nop 1
	v_cndmask_b32_e64 v89, v103, v99, s[0:1]
	v_cndmask_b32_e64 v88, v102, v98, s[0:1]
	v_cndmask_b32_e64 v91, v105, v101, s[0:1]
	v_cndmask_b32_e64 v90, v104, v100, s[0:1]
	s_waitcnt lgkmcnt(1)
	s_waitcnt vmcnt(7)
	v_pk_fma_f32 v[84:85], v[84:85], v[88:89], v[248:249]
	v_pk_fma_f32 v[86:87], v[86:87], v[90:91], v[250:251]
	global_store_dwordx4 v[174:175], v[84:87], off
	v_or_b32_e32 v88, s16, v69
	v_mov_b32_e32 v89, s17
	v_cmp_gt_i32_e32 vcc, s8, v88
	s_nop 1
	v_cndmask_b32_e32 v89, 8, v89, vcc
	v_cmp_eq_u32_e64 s[0:1], s15, v89
	s_nop 1
	v_cndmask_b32_e64 v89, v103, v99, s[0:1]
	v_cndmask_b32_e64 v88, v102, v98, s[0:1]
	v_cndmask_b32_e64 v91, v105, v101, s[0:1]
	v_cndmask_b32_e64 v90, v104, v100, s[0:1]
	s_waitcnt lgkmcnt(0)
	s_waitcnt vmcnt(7)
; template <int EPI, int MI>
; DI void gemm_tile(const GemmDesc& g, int tm, int tn, char* smem) {
;     ...
; #pragma unroll 4
;       for (int j = 0; j < 8; ++j) {
;         const int lrow = (tid >> 5) + 8 * j;
;         const int grow = m0 + (lrow >> 5) * (32 * MI) + mi * 32 + (lrow & 31);
;         const f32x4v a4 = *(const f32x4v*)(es + lrow * 128 + c4);
;         const int rg = grow < LAT ? (grow >> 11) : 8;
;         const f32x4v m4 = rg == rgA ? m4a : m4b;
;         float* rp = (grow < LAT ? g.xres + (size_t)grow * 1024 : g.hres + (size_t)(grow - LAT) * 1024) + n0 + c4;
;         f32x4v x4 = *(const f32x4v*)rp;
;         x4 += (m4 * a4) * g.coef;
;         *(f32x4v*)rp = x4;
;       }
;       __syncthreads();
	v_pk_fma_f32 v[92:93], v[92:93], v[88:89], v[252:253]
	v_pk_fma_f32 v[94:95], v[94:95], v[90:91], v[254:255]
	global_store_dwordx4 v[176:177], v[92:95], off
	s_add_u32 s16, s39, 64
	v_or_b32_e32 v224, s16, v66
	v_mov_b32_e32 v226, s68
	v_mov_b32_e32 v227, s69
	v_mov_b32_e32 v162, s3
	v_mov_b32_e32 v163, s33
	v_cmp_gt_i32_e32 vcc, s8, v224
	v_add_u32_e32 v225, 0xffffc000, v224
	s_nop 0
	v_cndmask_b32_e32 v224, v225, v224, vcc
	v_cndmask_b32_e32 v226, v162, v226, vcc
	v_cndmask_b32_e32 v227, v163, v227, vcc
	v_mov_b32_e32 v225, 0
	v_lshlrev_b64 v[224:225], 12, v[224:225]
	v_lshl_add_u64 v[224:225], v[226:227], 0, v[224:225]
	v_lshl_add_u64 v[224:225], v[224:225], 0, s[4:5]
	v_lshl_add_u64 v[162:163], v[224:225], 0, v[64:65]
	global_load_dwordx4 v[224:227], v[162:163], off
	v_or_b32_e32 v228, s16, v67
	v_mov_b32_e32 v230, s68
	v_mov_b32_e32 v231, s69
	v_mov_b32_e32 v164, s3
	v_mov_b32_e32 v165, s33
	v_cmp_gt_i32_e32 vcc, s8, v228
	v_add_u32_e32 v229, 0xffffc000, v228
	s_nop 0
	v_cndmask_b32_e32 v228, v229, v228, vcc
	v_cndmask_b32_e32 v230, v164, v230, vcc
	v_cndmask_b32_e32 v231, v165, v231, vcc
	v_mov_b32_e32 v229, 0
	v_lshlrev_b64 v[228:229], 12, v[228:229]
	v_lshl_add_u64 v[228:229], v[230:231], 0, v[228:229]
	v_lshl_add_u64 v[228:229], v[228:229], 0, s[4:5]
	v_lshl_add_u64 v[164:165], v[228:229], 0, v[64:65]
	global_load_dwordx4 v[228:231], v[164:165], off
	v_or_b32_e32 v232, s16, v68
	v_mov_b32_e32 v234, s68
	v_mov_b32_e32 v235, s69
	v_mov_b32_e32 v166, s3
	v_mov_b32_e32 v167, s33
	v_cmp_gt_i32_e32 vcc, s8, v232
	v_add_u32_e32 v233, 0xffffc000, v232
	s_nop 0
	v_cndmask_b32_e32 v232, v233, v232, vcc
	v_cndmask_b32_e32 v234, v166, v234, vcc
	v_cndmask_b32_e32 v235, v167, v235, vcc
	v_mov_b32_e32 v233, 0
	v_lshlrev_b64 v[232:233], 12, v[232:233]
	v_lshl_add_u64 v[232:233], v[234:235], 0, v[232:233]
	v_lshl_add_u64 v[232:233], v[232:233], 0, s[4:5]
	v_lshl_add_u64 v[166:167], v[232:233], 0, v[64:65]
	global_load_dwordx4 v[232:235], v[166:167], off
	v_or_b32_e32 v236, s16, v69
	v_mov_b32_e32 v238, s68
	v_mov_b32_e32 v239, s69
	v_mov_b32_e32 v168, s3
	v_mov_b32_e32 v169, s33
	v_cmp_gt_i32_e32 vcc, s8, v236
	v_add_u32_e32 v237, 0xffffc000, v236
	s_nop 0
	v_cndmask_b32_e32 v236, v237, v236, vcc
	v_cndmask_b32_e32 v238, v168, v238, vcc
	v_cndmask_b32_e32 v239, v169, v239, vcc
	v_mov_b32_e32 v237, 0
	v_lshlrev_b64 v[236:237], 12, v[236:237]
	v_lshl_add_u64 v[236:237], v[238:239], 0, v[236:237]
	v_lshl_add_u64 v[236:237], v[236:237], 0, s[4:5]
	v_lshl_add_u64 v[168:169], v[236:237], 0, v[64:65]
	global_load_dwordx4 v[236:239], v[168:169], off
	s_add_u32 s16, s39, 160
	v_or_b32_e32 v240, s16, v66
	v_mov_b32_e32 v242, s68
	v_mov_b32_e32 v243, s69
	v_mov_b32_e32 v170, s3
	v_mov_b32_e32 v171, s33
	v_cmp_gt_i32_e32 vcc, s8, v240
	v_add_u32_e32 v241, 0xffffc000, v240
	s_nop 0
	v_cndmask_b32_e32 v240, v241, v240, vcc
	v_cndmask_b32_e32 v242, v170, v242, vcc
	v_cndmask_b32_e32 v243, v171, v243, vcc
	v_mov_b32_e32 v241, 0
	v_lshlrev_b64 v[240:241], 12, v[240:241]
	v_lshl_add_u64 v[240:241], v[242:243], 0, v[240:241]
	v_lshl_add_u64 v[240:241], v[240:241], 0, s[4:5]
	v_lshl_add_u64 v[170:171], v[240:241], 0, v[64:65]
	global_load_dwordx4 v[240:243], v[170:171], off
	v_or_b32_e32 v244, s16, v67
	v_mov_b32_e32 v246, s68
	v_mov_b32_e32 v247, s69
	v_mov_b32_e32 v172, s3
	v_mov_b32_e32 v173, s33
	v_cmp_gt_i32_e32 vcc, s8, v244
	v_add_u32_e32 v245, 0xffffc000, v244
	s_nop 0
	v_cndmask_b32_e32 v244, v245, v244, vcc
	v_cndmask_b32_e32 v246, v172, v246, vcc
	v_cndmask_b32_e32 v247, v173, v247, vcc
	v_mov_b32_e32 v245, 0
	v_lshlrev_b64 v[244:245], 12, v[244:245]
	v_lshl_add_u64 v[244:245], v[246:247], 0, v[244:245]
	v_lshl_add_u64 v[244:245], v[244:245], 0, s[4:5]
	v_lshl_add_u64 v[172:173], v[244:245], 0, v[64:65]
	global_load_dwordx4 v[244:247], v[172:173], off
	v_or_b32_e32 v248, s16, v68
	v_mov_b32_e32 v250, s68
	v_mov_b32_e32 v251, s69
	v_mov_b32_e32 v174, s3
	v_mov_b32_e32 v175, s33
	v_cmp_gt_i32_e32 vcc, s8, v248
	v_add_u32_e32 v249, 0xffffc000, v248
	s_nop 0
	v_cndmask_b32_e32 v248, v249, v248, vcc
	v_cndmask_b32_e32 v250, v174, v250, vcc
	v_cndmask_b32_e32 v251, v175, v251, vcc
	v_mov_b32_e32 v249, 0
	v_lshlrev_b64 v[248:249], 12, v[248:249]
	v_lshl_add_u64 v[248:249], v[250:251], 0, v[248:249]
	v_lshl_add_u64 v[248:249], v[248:249], 0, s[4:5]
	v_lshl_add_u64 v[174:175], v[248:249], 0, v[64:65]
	global_load_dwordx4 v[248:251], v[174:175], off
	v_or_b32_e32 v252, s16, v69
	v_mov_b32_e32 v254, s68
	v_mov_b32_e32 v255, s69
	v_mov_b32_e32 v176, s3
	v_mov_b32_e32 v177, s33
	v_cmp_gt_i32_e32 vcc, s8, v252
	v_add_u32_e32 v253, 0xffffc000, v252
	s_nop 0
	v_cndmask_b32_e32 v252, v253, v252, vcc
	v_cndmask_b32_e32 v254, v176, v254, vcc
	v_cndmask_b32_e32 v255, v177, v255, vcc
	v_mov_b32_e32 v253, 0
	v_lshlrev_b64 v[252:253], 12, v[252:253]
	v_lshl_add_u64 v[252:253], v[254:255], 0, v[252:253]
	v_lshl_add_u64 v[252:253], v[252:253], 0, s[4:5]
	v_lshl_add_u64 v[176:177], v[252:253], 0, v[64:65]
	global_load_dwordx4 v[252:255], v[176:177], off
	s_add_i32 s39, s39, 64
	s_mov_b32 s16, 0
	s_barrier
; template <int EPI, int MI>
; DI void gemm_tile(const GemmDesc& g, int tm, int tn, char* smem) {
;     ...
;     for (int mi = 0; mi < MI; ++mi) {
; #pragma unroll
;       for (int ni = 0; ni < 2; ++ni)
; #pragma unroll
;         for (int i = 0; i < 16; ++i) {
;           const int lrow = wm * 32 + (i & 3) + 8 * (i >> 2) + 4 * hh;
;           es[lrow * 128 + wn * 64 + ni * 32 + r] = acc[mi][ni][i];
;         }
;       __syncthreads();
; #pragma unroll 4
;       for (int j = 0; j < 8; ++j) {
;         const int lrow = (tid >> 5) + 8 * j;
;         const int grow = m0 + (lrow >> 5) * (32 * MI) + mi * 32 + (lrow & 31);
;         const f32x4v a4 = *(const f32x4v*)(es + lrow * 128 + c4);
;         const int rg = grow < LAT ? (grow >> 11) : 8;
;         const f32x4v m4 = rg == rgA ? m4a : m4b;
;         float* rp = (grow < LAT ? g.xres + (size_t)grow * 1024 : g.hres + (size_t)(grow - LAT) * 1024) + n0 + c4;
;         f32x4v x4 = *(const f32x4v*)rp;
;         x4 += (m4 * a4) * g.coef;
;         *(f32x4v*)rp = x4;
;       }
;       __syncthreads();
	ds_write2_b32 v108, v0, v16 offset1:32
	ds_write2_b32 v108, v1, v17 offset0:128 offset1:160
	ds_write2_b32 v80, v2, v18 offset1:32
	ds_write2_b32 v80, v3, v19 offset0:128 offset1:160
	ds_write2_b32 v81, v4, v20 offset1:32
	ds_write2_b32 v81, v5, v21 offset0:128 offset1:160
	ds_write2_b32 v82, v6, v22 offset1:32
	ds_write2_b32 v82, v7, v23 offset0:128 offset1:160
	ds_write2_b32 v71, v8, v24 offset1:32
	ds_write2_b32 v71, v9, v25 offset0:128 offset1:160
	ds_write2_b32 v72, v10, v26 offset1:32
	ds_write2_b32 v72, v11, v27 offset0:128 offset1:160
	ds_write2_b32 v73, v12, v28 offset1:32
	ds_write2_b32 v73, v13, v29 offset0:128 offset1:160
	ds_write2_b32 v74, v14, v30 offset1:32
	ds_write2_b32 v74, v15, v31 offset0:128 offset1:160
	s_waitcnt lgkmcnt(0)
	s_barrier
	ds_read_b128 v[84:87], v70
	s_mov_b32 s16, s39
	s_ashr_i32 s17, s16, 11
	v_or_b32_e32 v88, s16, v66
	v_mov_b32_e32 v89, s17
	v_cmp_gt_i32_e32 vcc, s8, v88
	ds_read_b128 v[92:95], v70 offset:4096
	s_nop 0
	v_cndmask_b32_e32 v89, 8, v89, vcc
	v_cmp_eq_u32_e64 s[0:1], s15, v89
	s_nop 1
	v_cndmask_b32_e64 v89, v103, v99, s[0:1]
	v_cndmask_b32_e64 v88, v102, v98, s[0:1]
	v_cndmask_b32_e64 v91, v105, v101, s[0:1]
	v_cndmask_b32_e64 v90, v104, v100, s[0:1]
	s_waitcnt lgkmcnt(1)
	s_waitcnt vmcnt(7)
	v_pk_fma_f32 v[84:85], v[84:85], v[88:89], v[224:225]
	v_pk_fma_f32 v[86:87], v[86:87], v[90:91], v[226:227]
	global_store_dwordx4 v[162:163], v[84:87], off
	v_or_b32_e32 v88, s16, v67
	v_mov_b32_e32 v89, s17
	v_cmp_gt_i32_e32 vcc, s8, v88
	ds_read_b128 v[84:87], v70 offset:8192
	s_nop 0
	v_cndmask_b32_e32 v89, 8, v89, vcc
	v_cmp_eq_u32_e64 s[0:1], s15, v89
	s_nop 1
	v_cndmask_b32_e64 v89, v103, v99, s[0:1]
	v_cndmask_b32_e64 v88, v102, v98, s[0:1]
	v_cndmask_b32_e64 v91, v105, v101, s[0:1]
	v_cndmask_b32_e64 v90, v104, v100, s[0:1]
	s_waitcnt lgkmcnt(1)
	s_waitcnt vmcnt(7)
	v_pk_fma_f32 v[92:93], v[92:93], v[88:89], v[228:229]
	v_pk_fma_f32 v[94:95], v[94:95], v[90:91], v[230:231]
	global_store_dwordx4 v[164:165], v[92:95], off
	v_or_b32_e32 v88, s16, v68
	v_mov_b32_e32 v89, s17
	v_cmp_gt_i32_e32 vcc, s8, v88
	ds_read_b128 v[92:95], v70 offset:12288
	s_nop 0
	v_cndmask_b32_e32 v89, 8, v89, vcc
	v_cmp_eq_u32_e64 s[0:1], s15, v89
	s_nop 1
	v_cndmask_b32_e64 v89, v103, v99, s[0:1]
	v_cndmask_b32_e64 v88, v102, v98, s[0:1]
	v_cndmask_b32_e64 v91, v105, v101, s[0:1]
	v_cndmask_b32_e64 v90, v104, v100, s[0:1]
	s_waitcnt lgkmcnt(1)
	s_waitcnt vmcnt(7)
	v_pk_fma_f32 v[84:85], v[84:85], v[88:89], v[232:233]
	v_pk_fma_f32 v[86:87], v[86:87], v[90:91], v[234:235]
	global_store_dwordx4 v[166:167], v[84:87], off
	v_or_b32_e32 v88, s16, v69
	v_mov_b32_e32 v89, s17
	v_cmp_gt_i32_e32 vcc, s8, v88
	ds_read_b128 v[84:87], v70 offset:16384
	s_nop 0
	v_cndmask_b32_e32 v89, 8, v89, vcc
	v_cmp_eq_u32_e64 s[0:1], s15, v89
	s_nop 1
	v_cndmask_b32_e64 v89, v103, v99, s[0:1]
	v_cndmask_b32_e64 v88, v102, v98, s[0:1]
	v_cndmask_b32_e64 v91, v105, v101, s[0:1]
	v_cndmask_b32_e64 v90, v104, v100, s[0:1]
	s_waitcnt lgkmcnt(1)
	s_waitcnt vmcnt(7)
	v_pk_fma_f32 v[92:93], v[92:93], v[88:89], v[236:237]
	v_pk_fma_f32 v[94:95], v[94:95], v[90:91], v[238:239]
	global_store_dwordx4 v[168:169], v[92:95], off
	s_add_u32 s16, s39, 96
	s_ashr_i32 s17, s16, 11
	v_or_b32_e32 v88, s16, v66
	v_mov_b32_e32 v89, s17
	v_cmp_gt_i32_e32 vcc, s8, v88
	ds_read_b128 v[92:95], v70 offset:20480
	s_nop 0
	v_cndmask_b32_e32 v89, 8, v89, vcc
	v_cmp_eq_u32_e64 s[0:1], s15, v89
	s_nop 1
	v_cndmask_b32_e64 v89, v103, v99, s[0:1]
	v_cndmask_b32_e64 v88, v102, v98, s[0:1]
	v_cndmask_b32_e64 v91, v105, v101, s[0:1]
	v_cndmask_b32_e64 v90, v104, v100, s[0:1]
	s_waitcnt lgkmcnt(1)
	s_waitcnt vmcnt(7)
	v_pk_fma_f32 v[84:85], v[84:85], v[88:89], v[240:241]
	v_pk_fma_f32 v[86:87], v[86:87], v[90:91], v[242:243]
	global_store_dwordx4 v[170:171], v[84:87], off
	v_or_b32_e32 v88, s16, v67
	v_mov_b32_e32 v89, s17
	v_cmp_gt_i32_e32 vcc, s8, v88
	ds_read_b128 v[84:87], v70 offset:24576
	s_nop 0
	v_cndmask_b32_e32 v89, 8, v89, vcc
	v_cmp_eq_u32_e64 s[0:1], s15, v89
	s_nop 1
	v_cndmask_b32_e64 v89, v103, v99, s[0:1]
	v_cndmask_b32_e64 v88, v102, v98, s[0:1]
	v_cndmask_b32_e64 v91, v105, v101, s[0:1]
	v_cndmask_b32_e64 v90, v104, v100, s[0:1]
	s_waitcnt lgkmcnt(1)
	s_waitcnt vmcnt(7)
	v_pk_fma_f32 v[92:93], v[92:93], v[88:89], v[244:245]
	v_pk_fma_f32 v[94:95], v[94:95], v[90:91], v[246:247]
	global_store_dwordx4 v[172:173], v[92:95], off
	v_or_b32_e32 v88, s16, v68
	v_mov_b32_e32 v89, s17
	v_cmp_gt_i32_e32 vcc, s8, v88
	ds_read_b128 v[92:95], v70 offset:28672
	s_nop 0
	v_cndmask_b32_e32 v89, 8, v89, vcc
	v_cmp_eq_u32_e64 s[0:1], s15, v89
	s_nop 1
	v_cndmask_b32_e64 v89, v103, v99, s[0:1]
	v_cndmask_b32_e64 v88, v102, v98, s[0:1]
	v_cndmask_b32_e64 v91, v105, v101, s[0:1]
	v_cndmask_b32_e64 v90, v104, v100, s[0:1]
	s_waitcnt lgkmcnt(1)
	s_waitcnt vmcnt(7)
	v_pk_fma_f32 v[84:85], v[84:85], v[88:89], v[248:249]
	v_pk_fma_f32 v[86:87], v[86:87], v[90:91], v[250:251]
	global_store_dwordx4 v[174:175], v[84:87], off
	v_or_b32_e32 v88, s16, v69
	v_mov_b32_e32 v89, s17
	v_cmp_gt_i32_e32 vcc, s8, v88
	s_nop 1
	v_cndmask_b32_e32 v89, 8, v89, vcc
	v_cmp_eq_u32_e64 s[0:1], s15, v89
	s_nop 1
	v_cndmask_b32_e64 v89, v103, v99, s[0:1]
	v_cndmask_b32_e64 v88, v102, v98, s[0:1]
	v_cndmask_b32_e64 v91, v105, v101, s[0:1]
	v_cndmask_b32_e64 v90, v104, v100, s[0:1]
	s_waitcnt lgkmcnt(0)
	s_waitcnt vmcnt(7)
	v_pk_fma_f32 v[92:93], v[92:93], v[88:89], v[252:253]
	v_pk_fma_f32 v[94:95], v[94:95], v[90:91], v[254:255]
	global_store_dwordx4 v[176:177], v[92:95], off
	v_readlane_b32 s0, v218, 38
	s_add_i32 s38, s38, s0
	v_readlane_b32 s0, v218, 31
	s_add_i32 s20, s20, s0
	v_readlane_b32 s0, v221, 13
	s_cmp_lt_i32 s38, s0
	s_barrier
	s_cbranch_scc1 .LBB0_1287

; template <int EPI, int MI>
; DI void gemm_tile(const GemmDesc& g, int tm, int tn, char* smem) {
;     ...
;     float* es = (float*)smem;
;     const int c4 = (tid & 31) * 4;
;     const int rgA = m0 < LAT ? (m0 >> 11) : 8;
;     const int mlast = m0 + BM - 1;
;     const int rgB = mlast < LAT ? (mlast >> 11) : 8;
;     const f32x4v m4a = *(const f32x4v*)(g.mod + (size_t)rgA * 9216 + g.gidx * 1024 + n0 + c4);
;     const f32x4v m4b = *(const f32x4v*)(g.mod + (size_t)rgB * 9216 + g.gidx * 1024 + n0 + c4);
; #pragma unroll
;     for (int mi = 0; mi < MI; ++mi) {
; #pragma unroll
;       for (int ni = 0; ni < 2; ++ni)
; #pragma unroll
;         for (int i = 0; i < 16; ++i) {
;           const int lrow = wm * 32 + (i & 3) + 8 * (i >> 2) + 4 * hh;
;           es[lrow * 128 + wn * 64 + ni * 32 + r] = acc[mi][ni][i];
;         }
;       __syncthreads();
; #pragma unroll 4
;       for (int j = 0; j < 8; ++j) {
;         const int lrow = (tid >> 5) + 8 * j;
;         const int grow = m0 + (lrow >> 5) * (32 * MI) + mi * 32 + (lrow & 31);
;         const f32x4v a4 = *(const f32x4v*)(es + lrow * 128 + c4);
;         const int rg = grow < LAT ? (grow >> 11) : 8;
;         const f32x4v m4 = rg == rgA ? m4a : m4b;
;         float* rp = (grow < LAT ? g.xres + (size_t)grow * 1024 : g.hres + (size_t)(grow - LAT) * 1024) + n0 + c4;
;         f32x4v x4 = *(const f32x4v*)rp;
;         x4 += (m4 * a4) * g.coef;
.LBB0_1482:
	s_min_i32 s4, s1, 0x80
	s_ashr_i32 s18, s4, 4
	s_or_b32 s4, s45, 0x7f
	s_ashr_i32 s1, s1, 4
	s_cmpk_lt_i32 s4, 0x4000
	s_mul_i32 s4, s18, 0x9000
	s_cselect_b32 s19, s1, 8
	s_mul_hi_i32 s1, s18, 0x9000
	s_add_u32 s46, s40, s4
	s_addc_u32 s47, s41, s1
	s_ashr_i32 s1, s0, 31
	v_lshlrev_b32_e32 v64, 2, v75
	s_lshl_b64 s[4:5], s[0:1], 2
	v_and_b32_e32 v72, 0x7c, v64
	s_add_u32 s0, s46, s4
	s_addc_u32 s1, s47, s5
	v_lshlrev_b32_e32 v68, 2, v72
	global_load_dwordx4 v[64:67], v68, s[0:1]
	s_mul_hi_i32 s0, s19, 0x9000
	s_mul_i32 s19, s19, 0x9000
	s_add_u32 s1, s40, s19
	s_addc_u32 s19, s41, s0
	s_add_u32 s0, s1, s4
	s_addc_u32 s1, s19, s5
	global_load_dwordx4 v[68:71], v68, s[0:1]
	v_and_b32_e32 v73, 64, v75
	v_lshl_add_u32 v77, v77, 11, 0
	v_lshlrev_b32_e32 v73, 2, v73
	v_lshlrev_b32_e32 v78, 2, v74
	v_lshlrev_b32_e32 v76, 14, v76
	v_add3_u32 v73, v77, v73, v78
	v_ashrrev_i32_e32 v75, 5, v75
	v_add_u32_e32 v73, v73, v76
	ds_write2_b32 v73, v48, v32 offset1:32
	ds_write2_b32 v73, v49, v33 offset0:128 offset1:160
	v_add_u32_e32 v48, 0x400, v73
	v_add_u32_e32 v32, 8, v75
	ds_write2_b32 v48, v50, v34 offset1:32
	ds_write2_b32 v48, v51, v35 offset0:128 offset1:160
	v_add_u32_e32 v49, 0x1000, v73
	v_and_b32_e32 v35, 31, v32
	v_add_u32_e32 v32, 24, v75
	ds_write2_b32 v49, v52, v36 offset1:32
	ds_write2_b32 v49, v53, v37 offset0:128 offset1:160
	v_add_u32_e32 v50, 0x1400, v73
	v_add_u32_e32 v51, 0x2000, v73
	v_and_b32_e32 v37, 31, v32
	v_lshlrev_b32_e32 v32, 4, v74
	ds_write2_b32 v50, v54, v38 offset1:32
	ds_write2_b32 v50, v55, v39 offset0:128 offset1:160
	ds_write2_b32 v51, v56, v40 offset1:32
	ds_write2_b32 v51, v57, v41 offset0:128 offset1:160
	v_add_u32_e32 v40, 0x2400, v73
	v_lshl_or_b32 v32, v75, 9, v32
	v_lshlrev_b32_e32 v39, 1, v75
	ds_write2_b32 v40, v58, v42 offset1:32
	ds_write2_b32 v40, v59, v43 offset0:128 offset1:160
	v_add_u32_e32 v41, 0x3000, v73
	v_add_u32_e32 v42, 0x3400, v73
	v_and_b32_e32 v34, 31, v75
	v_bitop3_b32 v36, v75, 16, 31 bitop3:0x6c
	v_add_u32_e32 v38, 0, v32
	s_mov_b32 s19, 0
	v_mov_b32_e32 v43, v39
	ds_write2_b32 v41, v60, v44 offset1:32
	ds_write2_b32 v41, v61, v45 offset0:128 offset1:160
	ds_write2_b32 v42, v62, v46 offset1:32
	ds_write2_b32 v42, v63, v47 offset0:128 offset1:160
	v_lshlrev_b32_e32 v44, 2, v72
	v_mov_b32_e32 v45, 0
	s_mov_b32 s46, s45
	v_or_b32_e32 v224, s46, v34
	v_mov_b32_e32 v226, s68
	v_mov_b32_e32 v227, s69
	v_mov_b32_e32 v80, s3
	v_mov_b32_e32 v81, s33
	v_cmp_gt_i32_e32 vcc, s8, v224
	v_add_u32_e32 v225, 0xffffc000, v224
	s_nop 0
	v_cndmask_b32_e32 v224, v225, v224, vcc
	v_cndmask_b32_e32 v226, v80, v226, vcc
	v_cndmask_b32_e32 v227, v81, v227, vcc
	v_mov_b32_e32 v225, 0
	v_lshlrev_b64 v[224:225], 12, v[224:225]
	v_lshl_add_u64 v[224:225], v[226:227], 0, v[224:225]
	v_lshl_add_u64 v[224:225], v[224:225], 0, s[4:5]
	v_lshl_add_u64 v[80:81], v[224:225], 0, v[44:45]
	global_load_dwordx4 v[224:227], v[80:81], off
	v_or_b32_e32 v228, s46, v35
	v_mov_b32_e32 v230, s68
	v_mov_b32_e32 v231, s69
	v_mov_b32_e32 v82, s3
	v_mov_b32_e32 v83, s33
	v_cmp_gt_i32_e32 vcc, s8, v228
	v_add_u32_e32 v229, 0xffffc000, v228
	s_nop 0
	v_cndmask_b32_e32 v228, v229, v228, vcc
	v_cndmask_b32_e32 v230, v82, v230, vcc
	v_cndmask_b32_e32 v231, v83, v231, vcc
	v_mov_b32_e32 v229, 0
	v_lshlrev_b64 v[228:229], 12, v[228:229]
	v_lshl_add_u64 v[228:229], v[230:231], 0, v[228:229]
	v_lshl_add_u64 v[228:229], v[228:229], 0, s[4:5]
	v_lshl_add_u64 v[82:83], v[228:229], 0, v[44:45]
	global_load_dwordx4 v[228:231], v[82:83], off
	v_or_b32_e32 v232, s46, v36
	v_mov_b32_e32 v234, s68
	v_mov_b32_e32 v235, s69
	v_mov_b32_e32 v84, s3
	v_mov_b32_e32 v85, s33
	v_cmp_gt_i32_e32 vcc, s8, v232
	v_add_u32_e32 v233, 0xffffc000, v232
	s_nop 0
	v_cndmask_b32_e32 v232, v233, v232, vcc
	v_cndmask_b32_e32 v234, v84, v234, vcc
	v_cndmask_b32_e32 v235, v85, v235, vcc
	v_mov_b32_e32 v233, 0
	v_lshlrev_b64 v[232:233], 12, v[232:233]
	v_lshl_add_u64 v[232:233], v[234:235], 0, v[232:233]
	v_lshl_add_u64 v[232:233], v[232:233], 0, s[4:5]
	v_lshl_add_u64 v[84:85], v[232:233], 0, v[44:45]
	global_load_dwordx4 v[232:235], v[84:85], off
	v_or_b32_e32 v236, s46, v37
	v_mov_b32_e32 v238, s68
	v_mov_b32_e32 v239, s69
	v_mov_b32_e32 v86, s3
	v_mov_b32_e32 v87, s33
	v_cmp_gt_i32_e32 vcc, s8, v236
	v_add_u32_e32 v237, 0xffffc000, v236
	s_nop 0
	v_cndmask_b32_e32 v236, v237, v236, vcc
	v_cndmask_b32_e32 v238, v86, v238, vcc
	v_cndmask_b32_e32 v239, v87, v239, vcc
	v_mov_b32_e32 v237, 0
	v_lshlrev_b64 v[236:237], 12, v[236:237]
	v_lshl_add_u64 v[236:237], v[238:239], 0, v[236:237]
	v_lshl_add_u64 v[236:237], v[236:237], 0, s[4:5]
	v_lshl_add_u64 v[86:87], v[236:237], 0, v[44:45]
	global_load_dwordx4 v[236:239], v[86:87], off
	s_add_u32 s46, s45, 64
	v_or_b32_e32 v240, s46, v34
	v_mov_b32_e32 v242, s68
	v_mov_b32_e32 v243, s69
	v_mov_b32_e32 v88, s3
	v_mov_b32_e32 v89, s33
	v_cmp_gt_i32_e32 vcc, s8, v240
	v_add_u32_e32 v241, 0xffffc000, v240
	s_nop 0
	v_cndmask_b32_e32 v240, v241, v240, vcc
	v_cndmask_b32_e32 v242, v88, v242, vcc
	v_cndmask_b32_e32 v243, v89, v243, vcc
	v_mov_b32_e32 v241, 0
	v_lshlrev_b64 v[240:241], 12, v[240:241]
	v_lshl_add_u64 v[240:241], v[242:243], 0, v[240:241]
	v_lshl_add_u64 v[240:241], v[240:241], 0, s[4:5]
	v_lshl_add_u64 v[88:89], v[240:241], 0, v[44:45]
	global_load_dwordx4 v[240:243], v[88:89], off
	v_or_b32_e32 v244, s46, v35
	v_mov_b32_e32 v246, s68
	v_mov_b32_e32 v247, s69
	v_mov_b32_e32 v90, s3
	v_mov_b32_e32 v91, s33
	v_cmp_gt_i32_e32 vcc, s8, v244
	v_add_u32_e32 v245, 0xffffc000, v244
	s_nop 0
	v_cndmask_b32_e32 v244, v245, v244, vcc
	v_cndmask_b32_e32 v246, v90, v246, vcc
	v_cndmask_b32_e32 v247, v91, v247, vcc
; template <int EPI, int MI>
; DI void gemm_tile(const GemmDesc& g, int tm, int tn, char* smem) {
;     ...
; #pragma unroll 4
;       for (int j = 0; j < 8; ++j) {
;         const int lrow = (tid >> 5) + 8 * j;
;         const int grow = m0 + (lrow >> 5) * (32 * MI) + mi * 32 + (lrow & 31);
;         const f32x4v a4 = *(const f32x4v*)(es + lrow * 128 + c4);
;         const int rg = grow < LAT ? (grow >> 11) : 8;
;         const f32x4v m4 = rg == rgA ? m4a : m4b;
;         float* rp = (grow < LAT ? g.xres + (size_t)grow * 1024 : g.hres + (size_t)(grow - LAT) * 1024) + n0 + c4;
;         f32x4v x4 = *(const f32x4v*)rp;
;         x4 += (m4 * a4) * g.coef;
;         *(f32x4v*)rp = x4;
;       }
	v_mov_b32_e32 v245, 0
	v_lshlrev_b64 v[244:245], 12, v[244:245]
	v_lshl_add_u64 v[244:245], v[246:247], 0, v[244:245]
	v_lshl_add_u64 v[244:245], v[244:245], 0, s[4:5]
	v_lshl_add_u64 v[90:91], v[244:245], 0, v[44:45]
	global_load_dwordx4 v[244:247], v[90:91], off
	v_or_b32_e32 v248, s46, v36
	v_mov_b32_e32 v250, s68
	v_mov_b32_e32 v251, s69
	v_mov_b32_e32 v92, s3
	v_mov_b32_e32 v93, s33
	v_cmp_gt_i32_e32 vcc, s8, v248
	v_add_u32_e32 v249, 0xffffc000, v248
	s_nop 0
	v_cndmask_b32_e32 v248, v249, v248, vcc
	v_cndmask_b32_e32 v250, v92, v250, vcc
	v_cndmask_b32_e32 v251, v93, v251, vcc
	v_mov_b32_e32 v249, 0
	v_lshlrev_b64 v[248:249], 12, v[248:249]
	v_lshl_add_u64 v[248:249], v[250:251], 0, v[248:249]
	v_lshl_add_u64 v[248:249], v[248:249], 0, s[4:5]
	v_lshl_add_u64 v[92:93], v[248:249], 0, v[44:45]
	global_load_dwordx4 v[248:251], v[92:93], off
	v_or_b32_e32 v252, s46, v37
	v_mov_b32_e32 v254, s68
	v_mov_b32_e32 v255, s69
	v_mov_b32_e32 v94, s3
	v_mov_b32_e32 v95, s33
	v_cmp_gt_i32_e32 vcc, s8, v252
	v_add_u32_e32 v253, 0xffffc000, v252
	s_nop 0
	v_cndmask_b32_e32 v252, v253, v252, vcc
	v_cndmask_b32_e32 v254, v94, v254, vcc
	v_cndmask_b32_e32 v255, v95, v255, vcc
	v_mov_b32_e32 v253, 0
	v_lshlrev_b64 v[252:253], 12, v[252:253]
	v_lshl_add_u64 v[252:253], v[254:255], 0, v[252:253]
	v_lshl_add_u64 v[252:253], v[252:253], 0, s[4:5]
	v_lshl_add_u64 v[94:95], v[252:253], 0, v[44:45]
	global_load_dwordx4 v[252:255], v[94:95], off
	s_waitcnt lgkmcnt(0)
	s_barrier
	s_waitcnt vmcnt(8)
	ds_read_b128 v[52:55], v38
	s_mov_b32 s46, s45
	s_ashr_i32 s47, s46, 11
	v_or_b32_e32 v60, s46, v34
	v_mov_b32_e32 v61, s47
	v_cmp_gt_i32_e32 vcc, s8, v60
	ds_read_b128 v[56:59], v38 offset:4096
	s_nop 0
	v_cndmask_b32_e32 v61, 8, v61, vcc
	v_cmp_eq_u32_e64 s[0:1], s18, v61
	s_nop 1
	v_cndmask_b32_e64 v61, v69, v65, s[0:1]
	v_cndmask_b32_e64 v60, v68, v64, s[0:1]
	v_cndmask_b32_e64 v63, v71, v67, s[0:1]
	v_cndmask_b32_e64 v62, v70, v66, s[0:1]
	s_waitcnt lgkmcnt(1)
	v_pk_mul_f32 v[54:55], v[54:55], v[62:63]
	v_pk_mul_f32 v[52:53], v[52:53], v[60:61]
	s_waitcnt vmcnt(7)
	v_pk_fma_f32 v[52:53], v[52:53], 0.5, v[224:225] op_sel_hi:[1,0,1]
	v_pk_fma_f32 v[54:55], v[54:55], 0.5, v[226:227] op_sel_hi:[1,0,1]
	global_store_dwordx4 v[80:81], v[52:55], off
	v_or_b32_e32 v60, s46, v35
	v_mov_b32_e32 v61, s47
	v_cmp_gt_i32_e32 vcc, s8, v60
	ds_read_b128 v[52:55], v38 offset:8192
	s_nop 0
	v_cndmask_b32_e32 v61, 8, v61, vcc
	v_cmp_eq_u32_e64 s[0:1], s18, v61
	s_nop 1
	v_cndmask_b32_e64 v61, v69, v65, s[0:1]
	v_cndmask_b32_e64 v60, v68, v64, s[0:1]
	v_cndmask_b32_e64 v63, v71, v67, s[0:1]
	v_cndmask_b32_e64 v62, v70, v66, s[0:1]
	s_waitcnt lgkmcnt(1)
	v_pk_mul_f32 v[58:59], v[58:59], v[62:63]
	v_pk_mul_f32 v[56:57], v[56:57], v[60:61]
	s_waitcnt vmcnt(7)
	v_pk_fma_f32 v[56:57], v[56:57], 0.5, v[228:229] op_sel_hi:[1,0,1]
	v_pk_fma_f32 v[58:59], v[58:59], 0.5, v[230:231] op_sel_hi:[1,0,1]
	global_store_dwordx4 v[82:83], v[56:59], off
	v_or_b32_e32 v60, s46, v36
	v_mov_b32_e32 v61, s47
	v_cmp_gt_i32_e32 vcc, s8, v60
	ds_read_b128 v[56:59], v38 offset:12288
	s_nop 0
	v_cndmask_b32_e32 v61, 8, v61, vcc
	v_cmp_eq_u32_e64 s[0:1], s18, v61
	s_nop 1
	v_cndmask_b32_e64 v61, v69, v65, s[0:1]
	v_cndmask_b32_e64 v60, v68, v64, s[0:1]
	v_cndmask_b32_e64 v63, v71, v67, s[0:1]
	v_cndmask_b32_e64 v62, v70, v66, s[0:1]
	s_waitcnt lgkmcnt(1)
	v_pk_mul_f32 v[54:55], v[54:55], v[62:63]
	v_pk_mul_f32 v[52:53], v[52:53], v[60:61]
	s_waitcnt vmcnt(7)
	v_pk_fma_f32 v[52:53], v[52:53], 0.5, v[232:233] op_sel_hi:[1,0,1]
	v_pk_fma_f32 v[54:55], v[54:55], 0.5, v[234:235] op_sel_hi:[1,0,1]
	global_store_dwordx4 v[84:85], v[52:55], off
	v_or_b32_e32 v60, s46, v37
	v_mov_b32_e32 v61, s47
	v_cmp_gt_i32_e32 vcc, s8, v60
	ds_read_b128 v[52:55], v38 offset:16384
	s_nop 0
	v_cndmask_b32_e32 v61, 8, v61, vcc
	v_cmp_eq_u32_e64 s[0:1], s18, v61
	s_nop 1
	v_cndmask_b32_e64 v61, v69, v65, s[0:1]
	v_cndmask_b32_e64 v60, v68, v64, s[0:1]
	v_cndmask_b32_e64 v63, v71, v67, s[0:1]
	v_cndmask_b32_e64 v62, v70, v66, s[0:1]
	s_waitcnt lgkmcnt(1)
	v_pk_mul_f32 v[58:59], v[58:59], v[62:63]
	v_pk_mul_f32 v[56:57], v[56:57], v[60:61]
	s_waitcnt vmcnt(7)
	v_pk_fma_f32 v[56:57], v[56:57], 0.5, v[236:237] op_sel_hi:[1,0,1]
	v_pk_fma_f32 v[58:59], v[58:59], 0.5, v[238:239] op_sel_hi:[1,0,1]
	global_store_dwordx4 v[86:87], v[56:59], off
	s_add_u32 s46, s45, 64
	s_ashr_i32 s47, s46, 11
	v_or_b32_e32 v60, s46, v34
	v_mov_b32_e32 v61, s47
	v_cmp_gt_i32_e32 vcc, s8, v60
	ds_read_b128 v[56:59], v38 offset:20480
	s_nop 0
	v_cndmask_b32_e32 v61, 8, v61, vcc
	v_cmp_eq_u32_e64 s[0:1], s18, v61
	s_nop 1
	v_cndmask_b32_e64 v61, v69, v65, s[0:1]
	v_cndmask_b32_e64 v60, v68, v64, s[0:1]
	v_cndmask_b32_e64 v63, v71, v67, s[0:1]
	v_cndmask_b32_e64 v62, v70, v66, s[0:1]
	s_waitcnt lgkmcnt(1)
	v_pk_mul_f32 v[54:55], v[54:55], v[62:63]
	v_pk_mul_f32 v[52:53], v[52:53], v[60:61]
	s_waitcnt vmcnt(7)
	v_pk_fma_f32 v[52:53], v[52:53], 0.5, v[240:241] op_sel_hi:[1,0,1]
	v_pk_fma_f32 v[54:55], v[54:55], 0.5, v[242:243] op_sel_hi:[1,0,1]
	global_store_dwordx4 v[88:89], v[52:55], off
	v_or_b32_e32 v60, s46, v35
	v_mov_b32_e32 v61, s47
	v_cmp_gt_i32_e32 vcc, s8, v60
	ds_read_b128 v[52:55], v38 offset:24576
	s_nop 0
	v_cndmask_b32_e32 v61, 8, v61, vcc
	v_cmp_eq_u32_e64 s[0:1], s18, v61
	s_nop 1
	v_cndmask_b32_e64 v61, v69, v65, s[0:1]
	v_cndmask_b32_e64 v60, v68, v64, s[0:1]
	v_cndmask_b32_e64 v63, v71, v67, s[0:1]
	v_cndmask_b32_e64 v62, v70, v66, s[0:1]
	s_waitcnt lgkmcnt(1)
	v_pk_mul_f32 v[58:59], v[58:59], v[62:63]
	v_pk_mul_f32 v[56:57], v[56:57], v[60:61]
	s_waitcnt vmcnt(7)
; template <int EPI, int MI>
; DI void gemm_tile(const GemmDesc& g, int tm, int tn, char* smem) {
;     ...
; #pragma unroll 4
;       for (int j = 0; j < 8; ++j) {
;         const int lrow = (tid >> 5) + 8 * j;
;         const int grow = m0 + (lrow >> 5) * (32 * MI) + mi * 32 + (lrow & 31);
;         const f32x4v a4 = *(const f32x4v*)(es + lrow * 128 + c4);
;         const int rg = grow < LAT ? (grow >> 11) : 8;
;         const f32x4v m4 = rg == rgA ? m4a : m4b;
;         float* rp = (grow < LAT ? g.xres + (size_t)grow * 1024 : g.hres + (size_t)(grow - LAT) * 1024) + n0 + c4;
;         f32x4v x4 = *(const f32x4v*)rp;
;         x4 += (m4 * a4) * g.coef;
;         *(f32x4v*)rp = x4;
;       }
	v_pk_fma_f32 v[56:57], v[56:57], 0.5, v[244:245] op_sel_hi:[1,0,1]
	v_pk_fma_f32 v[58:59], v[58:59], 0.5, v[246:247] op_sel_hi:[1,0,1]
	global_store_dwordx4 v[90:91], v[56:59], off
	v_or_b32_e32 v60, s46, v36
	v_mov_b32_e32 v61, s47
	v_cmp_gt_i32_e32 vcc, s8, v60
	ds_read_b128 v[56:59], v38 offset:28672
	s_nop 0
	v_cndmask_b32_e32 v61, 8, v61, vcc
	v_cmp_eq_u32_e64 s[0:1], s18, v61
	s_nop 1
	v_cndmask_b32_e64 v61, v69, v65, s[0:1]
	v_cndmask_b32_e64 v60, v68, v64, s[0:1]
	v_cndmask_b32_e64 v63, v71, v67, s[0:1]
	v_cndmask_b32_e64 v62, v70, v66, s[0:1]
	s_waitcnt lgkmcnt(1)
	v_pk_mul_f32 v[54:55], v[54:55], v[62:63]
	v_pk_mul_f32 v[52:53], v[52:53], v[60:61]
	s_waitcnt vmcnt(7)
	v_pk_fma_f32 v[52:53], v[52:53], 0.5, v[248:249] op_sel_hi:[1,0,1]
	v_pk_fma_f32 v[54:55], v[54:55], 0.5, v[250:251] op_sel_hi:[1,0,1]
	global_store_dwordx4 v[92:93], v[52:55], off
	v_or_b32_e32 v60, s46, v37
	v_mov_b32_e32 v61, s47
	v_cmp_gt_i32_e32 vcc, s8, v60
	s_nop 1
	v_cndmask_b32_e32 v61, 8, v61, vcc
	v_cmp_eq_u32_e64 s[0:1], s18, v61
	s_nop 1
	v_cndmask_b32_e64 v61, v69, v65, s[0:1]
	v_cndmask_b32_e64 v60, v68, v64, s[0:1]
	v_cndmask_b32_e64 v63, v71, v67, s[0:1]
	v_cndmask_b32_e64 v62, v70, v66, s[0:1]
	s_waitcnt lgkmcnt(0)
	v_pk_mul_f32 v[58:59], v[58:59], v[62:63]
	v_pk_mul_f32 v[56:57], v[56:57], v[60:61]
	s_waitcnt vmcnt(7)
	v_pk_fma_f32 v[56:57], v[56:57], 0.5, v[252:253] op_sel_hi:[1,0,1]
	v_pk_fma_f32 v[58:59], v[58:59], 0.5, v[254:255] op_sel_hi:[1,0,1]
	global_store_dwordx4 v[94:95], v[56:59], off
	s_add_u32 s46, s45, 32
	v_or_b32_e32 v224, s46, v34
	v_mov_b32_e32 v226, s68
	v_mov_b32_e32 v227, s69
	v_mov_b32_e32 v80, s3
	v_mov_b32_e32 v81, s33
	v_cmp_gt_i32_e32 vcc, s8, v224
	v_add_u32_e32 v225, 0xffffc000, v224
	s_nop 0
	v_cndmask_b32_e32 v224, v225, v224, vcc
	v_cndmask_b32_e32 v226, v80, v226, vcc
	v_cndmask_b32_e32 v227, v81, v227, vcc
	v_mov_b32_e32 v225, 0
	v_lshlrev_b64 v[224:225], 12, v[224:225]
	v_lshl_add_u64 v[224:225], v[226:227], 0, v[224:225]
	v_lshl_add_u64 v[224:225], v[224:225], 0, s[4:5]
	v_lshl_add_u64 v[80:81], v[224:225], 0, v[44:45]
	global_load_dwordx4 v[224:227], v[80:81], off
	v_or_b32_e32 v228, s46, v35
	v_mov_b32_e32 v230, s68
	v_mov_b32_e32 v231, s69
	v_mov_b32_e32 v82, s3
	v_mov_b32_e32 v83, s33
	v_cmp_gt_i32_e32 vcc, s8, v228
	v_add_u32_e32 v229, 0xffffc000, v228
	s_nop 0
	v_cndmask_b32_e32 v228, v229, v228, vcc
	v_cndmask_b32_e32 v230, v82, v230, vcc
	v_cndmask_b32_e32 v231, v83, v231, vcc
	v_mov_b32_e32 v229, 0
	v_lshlrev_b64 v[228:229], 12, v[228:229]
	v_lshl_add_u64 v[228:229], v[230:231], 0, v[228:229]
	v_lshl_add_u64 v[228:229], v[228:229], 0, s[4:5]
	v_lshl_add_u64 v[82:83], v[228:229], 0, v[44:45]
	global_load_dwordx4 v[228:231], v[82:83], off
	v_or_b32_e32 v232, s46, v36
	v_mov_b32_e32 v234, s68
	v_mov_b32_e32 v235, s69
	v_mov_b32_e32 v84, s3
	v_mov_b32_e32 v85, s33
	v_cmp_gt_i32_e32 vcc, s8, v232
	v_add_u32_e32 v233, 0xffffc000, v232
	s_nop 0
	v_cndmask_b32_e32 v232, v233, v232, vcc
	v_cndmask_b32_e32 v234, v84, v234, vcc
	v_cndmask_b32_e32 v235, v85, v235, vcc
	v_mov_b32_e32 v233, 0
	v_lshlrev_b64 v[232:233], 12, v[232:233]
	v_lshl_add_u64 v[232:233], v[234:235], 0, v[232:233]
	v_lshl_add_u64 v[232:233], v[232:233], 0, s[4:5]
	v_lshl_add_u64 v[84:85], v[232:233], 0, v[44:45]
	global_load_dwordx4 v[232:235], v[84:85], off
	v_or_b32_e32 v236, s46, v37
	v_mov_b32_e32 v238, s68
	v_mov_b32_e32 v239, s69
	v_mov_b32_e32 v86, s3
	v_mov_b32_e32 v87, s33
	v_cmp_gt_i32_e32 vcc, s8, v236
	v_add_u32_e32 v237, 0xffffc000, v236
	s_nop 0
	v_cndmask_b32_e32 v236, v237, v236, vcc
	v_cndmask_b32_e32 v238, v86, v238, vcc
	v_cndmask_b32_e32 v239, v87, v239, vcc
	v_mov_b32_e32 v237, 0
	v_lshlrev_b64 v[236:237], 12, v[236:237]
	v_lshl_add_u64 v[236:237], v[238:239], 0, v[236:237]
	v_lshl_add_u64 v[236:237], v[236:237], 0, s[4:5]
	v_lshl_add_u64 v[86:87], v[236:237], 0, v[44:45]
	global_load_dwordx4 v[236:239], v[86:87], off
	s_add_u32 s46, s45, 96
	v_or_b32_e32 v240, s46, v34
	v_mov_b32_e32 v242, s68
	v_mov_b32_e32 v243, s69
	v_mov_b32_e32 v88, s3
	v_mov_b32_e32 v89, s33
	v_cmp_gt_i32_e32 vcc, s8, v240
	v_add_u32_e32 v241, 0xffffc000, v240
	s_nop 0
	v_cndmask_b32_e32 v240, v241, v240, vcc
	v_cndmask_b32_e32 v242, v88, v242, vcc
	v_cndmask_b32_e32 v243, v89, v243, vcc
	v_mov_b32_e32 v241, 0
	v_lshlrev_b64 v[240:241], 12, v[240:241]
	v_lshl_add_u64 v[240:241], v[242:243], 0, v[240:241]
	v_lshl_add_u64 v[240:241], v[240:241], 0, s[4:5]
	v_lshl_add_u64 v[88:89], v[240:241], 0, v[44:45]
	global_load_dwordx4 v[240:243], v[88:89], off
	v_or_b32_e32 v244, s46, v35
	v_mov_b32_e32 v246, s68
	v_mov_b32_e32 v247, s69
	v_mov_b32_e32 v90, s3
	v_mov_b32_e32 v91, s33
	v_cmp_gt_i32_e32 vcc, s8, v244
	v_add_u32_e32 v245, 0xffffc000, v244
	s_nop 0
	v_cndmask_b32_e32 v244, v245, v244, vcc
	v_cndmask_b32_e32 v246, v90, v246, vcc
	v_cndmask_b32_e32 v247, v91, v247, vcc
	v_mov_b32_e32 v245, 0
	v_lshlrev_b64 v[244:245], 12, v[244:245]
	v_lshl_add_u64 v[244:245], v[246:247], 0, v[244:245]
	v_lshl_add_u64 v[244:245], v[244:245], 0, s[4:5]
	v_lshl_add_u64 v[90:91], v[244:245], 0, v[44:45]
	global_load_dwordx4 v[244:247], v[90:91], off
	v_or_b32_e32 v248, s46, v36
	v_mov_b32_e32 v250, s68
	v_mov_b32_e32 v251, s69
	v_mov_b32_e32 v92, s3
	v_mov_b32_e32 v93, s33
	v_cmp_gt_i32_e32 vcc, s8, v248
	v_add_u32_e32 v249, 0xffffc000, v248
	s_nop 0
	v_cndmask_b32_e32 v248, v249, v248, vcc
	v_cndmask_b32_e32 v250, v92, v250, vcc
	v_cndmask_b32_e32 v251, v93, v251, vcc
	v_mov_b32_e32 v249, 0
	v_lshlrev_b64 v[248:249], 12, v[248:249]
	v_lshl_add_u64 v[248:249], v[250:251], 0, v[248:249]
	v_lshl_add_u64 v[248:249], v[248:249], 0, s[4:5]
	v_lshl_add_u64 v[92:93], v[248:249], 0, v[44:45]
	global_load_dwordx4 v[248:251], v[92:93], off
	v_or_b32_e32 v252, s46, v37
	v_mov_b32_e32 v254, s68
	v_mov_b32_e32 v255, s69
	v_mov_b32_e32 v94, s3
	v_mov_b32_e32 v95, s33
	v_cmp_gt_i32_e32 vcc, s8, v252
	v_add_u32_e32 v253, 0xffffc000, v252
	s_nop 0
	v_cndmask_b32_e32 v252, v253, v252, vcc
	v_cndmask_b32_e32 v254, v94, v254, vcc
	v_cndmask_b32_e32 v255, v95, v255, vcc
	v_mov_b32_e32 v253, 0
	v_lshlrev_b64 v[252:253], 12, v[252:253]
	v_lshl_add_u64 v[252:253], v[254:255], 0, v[252:253]
	v_lshl_add_u64 v[252:253], v[252:253], 0, s[4:5]
	v_lshl_add_u64 v[94:95], v[252:253], 0, v[44:45]
	global_load_dwordx4 v[252:255], v[94:95], off
	s_mov_b32 s19, 0
	s_barrier
; template <int EPI, int MI>
; DI void gemm_tile(const GemmDesc& g, int tm, int tn, char* smem) {
;     ...
;     for (int mi = 0; mi < MI; ++mi) {
; #pragma unroll
;       for (int ni = 0; ni < 2; ++ni)
; #pragma unroll
;         for (int i = 0; i < 16; ++i) {
;           const int lrow = wm * 32 + (i & 3) + 8 * (i >> 2) + 4 * hh;
;           es[lrow * 128 + wn * 64 + ni * 32 + r] = acc[mi][ni][i];
;         }
;       __syncthreads();
; #pragma unroll 4
;       for (int j = 0; j < 8; ++j) {
;         const int lrow = (tid >> 5) + 8 * j;
;         const int grow = m0 + (lrow >> 5) * (32 * MI) + mi * 32 + (lrow & 31);
;         const f32x4v a4 = *(const f32x4v*)(es + lrow * 128 + c4);
;         const int rg = grow < LAT ? (grow >> 11) : 8;
;         const f32x4v m4 = rg == rgA ? m4a : m4b;
;         float* rp = (grow < LAT ? g.xres + (size_t)grow * 1024 : g.hres + (size_t)(grow - LAT) * 1024) + n0 + c4;
;         f32x4v x4 = *(const f32x4v*)rp;
;         x4 += (m4 * a4) * g.coef;
;         *(f32x4v*)rp = x4;
;       }
;       __syncthreads();
	ds_write2_b32 v73, v16, v0 offset1:32
	ds_write2_b32 v73, v17, v1 offset0:128 offset1:160
	ds_write2_b32 v48, v18, v2 offset1:32
	ds_write2_b32 v48, v19, v3 offset0:128 offset1:160
	ds_write2_b32 v49, v20, v4 offset1:32
	ds_write2_b32 v49, v21, v5 offset0:128 offset1:160
	ds_write2_b32 v50, v22, v6 offset1:32
	ds_write2_b32 v50, v23, v7 offset0:128 offset1:160
	ds_write2_b32 v51, v24, v8 offset1:32
	ds_write2_b32 v51, v25, v9 offset0:128 offset1:160
	ds_write2_b32 v40, v26, v10 offset1:32
	ds_write2_b32 v40, v27, v11 offset0:128 offset1:160
	ds_write2_b32 v41, v28, v12 offset1:32
	ds_write2_b32 v41, v29, v13 offset0:128 offset1:160
	ds_write2_b32 v42, v30, v14 offset1:32
	ds_write2_b32 v42, v31, v15 offset0:128 offset1:160
	s_waitcnt lgkmcnt(0)
	s_barrier
	ds_read_b128 v[52:55], v38
	s_add_u32 s46, s45, 32
	s_ashr_i32 s47, s46, 11
	v_or_b32_e32 v60, s46, v34
	v_mov_b32_e32 v61, s47
	v_cmp_gt_i32_e32 vcc, s8, v60
	ds_read_b128 v[56:59], v38 offset:4096
	s_nop 0
	v_cndmask_b32_e32 v61, 8, v61, vcc
	v_cmp_eq_u32_e64 s[0:1], s18, v61
	s_nop 1
	v_cndmask_b32_e64 v61, v69, v65, s[0:1]
	v_cndmask_b32_e64 v60, v68, v64, s[0:1]
	v_cndmask_b32_e64 v63, v71, v67, s[0:1]
	v_cndmask_b32_e64 v62, v70, v66, s[0:1]
	s_waitcnt lgkmcnt(1)
	v_pk_mul_f32 v[54:55], v[54:55], v[62:63]
	v_pk_mul_f32 v[52:53], v[52:53], v[60:61]
	s_waitcnt vmcnt(7)
	v_pk_fma_f32 v[52:53], v[52:53], 0.5, v[224:225] op_sel_hi:[1,0,1]
	v_pk_fma_f32 v[54:55], v[54:55], 0.5, v[226:227] op_sel_hi:[1,0,1]
	global_store_dwordx4 v[80:81], v[52:55], off
	v_or_b32_e32 v60, s46, v35
	v_mov_b32_e32 v61, s47
	v_cmp_gt_i32_e32 vcc, s8, v60
	ds_read_b128 v[52:55], v38 offset:8192
	s_nop 0
	v_cndmask_b32_e32 v61, 8, v61, vcc
	v_cmp_eq_u32_e64 s[0:1], s18, v61
	s_nop 1
	v_cndmask_b32_e64 v61, v69, v65, s[0:1]
	v_cndmask_b32_e64 v60, v68, v64, s[0:1]
	v_cndmask_b32_e64 v63, v71, v67, s[0:1]
	v_cndmask_b32_e64 v62, v70, v66, s[0:1]
	s_waitcnt lgkmcnt(1)
	v_pk_mul_f32 v[58:59], v[58:59], v[62:63]
	v_pk_mul_f32 v[56:57], v[56:57], v[60:61]
	s_waitcnt vmcnt(7)
	v_pk_fma_f32 v[56:57], v[56:57], 0.5, v[228:229] op_sel_hi:[1,0,1]
	v_pk_fma_f32 v[58:59], v[58:59], 0.5, v[230:231] op_sel_hi:[1,0,1]
	global_store_dwordx4 v[82:83], v[56:59], off
	v_or_b32_e32 v60, s46, v36
	v_mov_b32_e32 v61, s47
	v_cmp_gt_i32_e32 vcc, s8, v60
	ds_read_b128 v[56:59], v38 offset:12288
	s_nop 0
	v_cndmask_b32_e32 v61, 8, v61, vcc
	v_cmp_eq_u32_e64 s[0:1], s18, v61
	s_nop 1
	v_cndmask_b32_e64 v61, v69, v65, s[0:1]
	v_cndmask_b32_e64 v60, v68, v64, s[0:1]
	v_cndmask_b32_e64 v63, v71, v67, s[0:1]
	v_cndmask_b32_e64 v62, v70, v66, s[0:1]
	s_waitcnt lgkmcnt(1)
	v_pk_mul_f32 v[54:55], v[54:55], v[62:63]
	v_pk_mul_f32 v[52:53], v[52:53], v[60:61]
	s_waitcnt vmcnt(7)
	v_pk_fma_f32 v[52:53], v[52:53], 0.5, v[232:233] op_sel_hi:[1,0,1]
	v_pk_fma_f32 v[54:55], v[54:55], 0.5, v[234:235] op_sel_hi:[1,0,1]
	global_store_dwordx4 v[84:85], v[52:55], off
	v_or_b32_e32 v60, s46, v37
	v_mov_b32_e32 v61, s47
	v_cmp_gt_i32_e32 vcc, s8, v60
	ds_read_b128 v[52:55], v38 offset:16384
	s_nop 0
	v_cndmask_b32_e32 v61, 8, v61, vcc
	v_cmp_eq_u32_e64 s[0:1], s18, v61
	s_nop 1
	v_cndmask_b32_e64 v61, v69, v65, s[0:1]
	v_cndmask_b32_e64 v60, v68, v64, s[0:1]
	v_cndmask_b32_e64 v63, v71, v67, s[0:1]
	v_cndmask_b32_e64 v62, v70, v66, s[0:1]
	s_waitcnt lgkmcnt(1)
	v_pk_mul_f32 v[58:59], v[58:59], v[62:63]
	v_pk_mul_f32 v[56:57], v[56:57], v[60:61]
	s_waitcnt vmcnt(7)
	v_pk_fma_f32 v[56:57], v[56:57], 0.5, v[236:237] op_sel_hi:[1,0,1]
	v_pk_fma_f32 v[58:59], v[58:59], 0.5, v[238:239] op_sel_hi:[1,0,1]
	global_store_dwordx4 v[86:87], v[56:59], off
	s_add_u32 s46, s45, 96
	s_ashr_i32 s47, s46, 11
	v_or_b32_e32 v60, s46, v34
	v_mov_b32_e32 v61, s47
	v_cmp_gt_i32_e32 vcc, s8, v60
	ds_read_b128 v[56:59], v38 offset:20480
	s_nop 0
	v_cndmask_b32_e32 v61, 8, v61, vcc
	v_cmp_eq_u32_e64 s[0:1], s18, v61
	s_nop 1
	v_cndmask_b32_e64 v61, v69, v65, s[0:1]
	v_cndmask_b32_e64 v60, v68, v64, s[0:1]
	v_cndmask_b32_e64 v63, v71, v67, s[0:1]
	v_cndmask_b32_e64 v62, v70, v66, s[0:1]
	s_waitcnt lgkmcnt(1)
	v_pk_mul_f32 v[54:55], v[54:55], v[62:63]
	v_pk_mul_f32 v[52:53], v[52:53], v[60:61]
	s_waitcnt vmcnt(7)
	v_pk_fma_f32 v[52:53], v[52:53], 0.5, v[240:241] op_sel_hi:[1,0,1]
	v_pk_fma_f32 v[54:55], v[54:55], 0.5, v[242:243] op_sel_hi:[1,0,1]
	global_store_dwordx4 v[88:89], v[52:55], off
	v_or_b32_e32 v60, s46, v35
	v_mov_b32_e32 v61, s47
	v_cmp_gt_i32_e32 vcc, s8, v60
	ds_read_b128 v[52:55], v38 offset:24576
	s_nop 0
	v_cndmask_b32_e32 v61, 8, v61, vcc
	v_cmp_eq_u32_e64 s[0:1], s18, v61
	s_nop 1
	v_cndmask_b32_e64 v61, v69, v65, s[0:1]
	v_cndmask_b32_e64 v60, v68, v64, s[0:1]
	v_cndmask_b32_e64 v63, v71, v67, s[0:1]
	v_cndmask_b32_e64 v62, v70, v66, s[0:1]
	s_waitcnt lgkmcnt(1)
	v_pk_mul_f32 v[58:59], v[58:59], v[62:63]
	v_pk_mul_f32 v[56:57], v[56:57], v[60:61]
	s_waitcnt vmcnt(7)
	v_pk_fma_f32 v[56:57], v[56:57], 0.5, v[244:245] op_sel_hi:[1,0,1]
	v_pk_fma_f32 v[58:59], v[58:59], 0.5, v[246:247] op_sel_hi:[1,0,1]
	global_store_dwordx4 v[90:91], v[56:59], off
	v_or_b32_e32 v60, s46, v36
	v_mov_b32_e32 v61, s47
	v_cmp_gt_i32_e32 vcc, s8, v60
	ds_read_b128 v[56:59], v38 offset:28672
	s_nop 0
	v_cndmask_b32_e32 v61, 8, v61, vcc
	v_cmp_eq_u32_e64 s[0:1], s18, v61
	s_nop 1
	v_cndmask_b32_e64 v61, v69, v65, s[0:1]
	v_cndmask_b32_e64 v60, v68, v64, s[0:1]
	v_cndmask_b32_e64 v63, v71, v67, s[0:1]
	v_cndmask_b32_e64 v62, v70, v66, s[0:1]
	s_waitcnt lgkmcnt(1)
	v_pk_mul_f32 v[54:55], v[54:55], v[62:63]
	v_pk_mul_f32 v[52:53], v[52:53], v[60:61]
	s_waitcnt vmcnt(7)
	v_pk_fma_f32 v[52:53], v[52:53], 0.5, v[248:249] op_sel_hi:[1,0,1]
	v_pk_fma_f32 v[54:55], v[54:55], 0.5, v[250:251] op_sel_hi:[1,0,1]
	global_store_dwordx4 v[92:93], v[52:55], off
	v_or_b32_e32 v60, s46, v37
	v_mov_b32_e32 v61, s47
	v_cmp_gt_i32_e32 vcc, s8, v60
	s_nop 1
	v_cndmask_b32_e32 v61, 8, v61, vcc
	v_cmp_eq_u32_e64 s[0:1], s18, v61
	s_nop 1
	v_cndmask_b32_e64 v61, v69, v65, s[0:1]
	v_cndmask_b32_e64 v60, v68, v64, s[0:1]
	v_cndmask_b32_e64 v63, v71, v67, s[0:1]
	v_cndmask_b32_e64 v62, v70, v66, s[0:1]
	s_waitcnt lgkmcnt(0)
	v_pk_mul_f32 v[58:59], v[58:59], v[62:63]
	v_pk_mul_f32 v[56:57], v[56:57], v[60:61]
	s_waitcnt vmcnt(7)
	v_pk_fma_f32 v[56:57], v[56:57], 0.5, v[252:253] op_sel_hi:[1,0,1]
	v_pk_fma_f32 v[58:59], v[58:59], 0.5, v[254:255] op_sel_hi:[1,0,1]
	global_store_dwordx4 v[94:95], v[56:59], off
	v_readlane_b32 s0, v218, 38
	s_add_i32 s44, s44, s0
	v_readlane_b32 s0, v218, 39
	s_add_i32 s17, s17, s0
	s_cmp_lt_i32 s44, s20
	s_barrier
	s_cbranch_scc1 .LBB0_1478

; template <int EPI, int MI>
; DI void gemm_tile(const GemmDesc& g, int tm, int tn, char* smem) {
;     ...
;     float* es = (float*)smem;
;     const int c4 = (tid & 31) * 4;
;     const int rgA = m0 < LAT ? (m0 >> 11) : 8;
;     const int mlast = m0 + BM - 1;
;     const int rgB = mlast < LAT ? (mlast >> 11) : 8;
;     const f32x4v m4a = *(const f32x4v*)(g.mod + (size_t)rgA * 9216 + g.gidx * 1024 + n0 + c4);
;     const f32x4v m4b = *(const f32x4v*)(g.mod + (size_t)rgB * 9216 + g.gidx * 1024 + n0 + c4);
; #pragma unroll
;     for (int mi = 0; mi < MI; ++mi) {
; #pragma unroll
;       for (int ni = 0; ni < 2; ++ni)
; #pragma unroll
;         for (int i = 0; i < 16; ++i) {
;           const int lrow = wm * 32 + (i & 3) + 8 * (i >> 2) + 4 * hh;
;           es[lrow * 128 + wn * 64 + ni * 32 + r] = acc[mi][ni][i];
;         }
;       __syncthreads();
; #pragma unroll 4
;       for (int j = 0; j < 8; ++j) {
;         const int lrow = (tid >> 5) + 8 * j;
;         const int grow = m0 + (lrow >> 5) * (32 * MI) + mi * 32 + (lrow & 31);
;         const f32x4v a4 = *(const f32x4v*)(es + lrow * 128 + c4);
;         const int rg = grow < LAT ? (grow >> 11) : 8;
;         const f32x4v m4 = rg == rgA ? m4a : m4b;
;         float* rp = (grow < LAT ? g.xres + (size_t)grow * 1024 : g.hres + (size_t)(grow - LAT) * 1024) + n0 + c4;
;         f32x4v x4 = *(const f32x4v*)rp;
;         x4 += (m4 * a4) * g.coef;
.LBB0_1495:
	s_ashr_i32 s4, s41, 11
	s_cmpk_lt_i32 s1, 0x56
	s_cselect_b32 s15, s4, 8
	s_add_i32 s4, s41, 0xbf
	s_ashr_i32 s4, s4, 11
	s_cmpk_lt_i32 s1, 0x55
	s_cselect_b32 s16, s4, 8
	s_mul_i32 s4, s15, 0x9000
	s_mul_hi_i32 s1, s15, 0x9000
	s_add_u32 s17, s20, s4
	s_addc_u32 s18, s38, s1
	s_ashr_i32 s1, s0, 31
	v_lshlrev_b32_e32 v98, 2, v97
	s_lshl_b64 s[4:5], s[0:1], 2
	v_and_b32_e32 v106, 0x7c, v98
	s_add_u32 s0, s17, s4
	s_addc_u32 s1, s18, s5
	v_lshlrev_b32_e32 v102, 2, v106
	global_load_dwordx4 v[98:101], v102, s[0:1]
	s_mul_hi_i32 s0, s16, 0x9000
	s_mul_i32 s16, s16, 0x9000
	s_add_u32 s1, s20, s16
	s_addc_u32 s16, s38, s0
	s_add_u32 s0, s1, s4
	s_addc_u32 s1, s16, s5
	global_load_dwordx4 v[102:105], v102, s[0:1]
	v_and_b32_e32 v107, 64, v97
	v_lshlrev_b32_e32 v115, 11, v115
	v_lshlrev_b32_e32 v107, 2, v107
	v_lshlrev_b32_e32 v109, 14, v109
	v_add3_u32 v107, 0, v115, v107
	v_lshlrev_b32_e32 v115, 2, v108
	v_ashrrev_i32_e32 v97, 5, v97
	v_add3_u32 v107, v107, v115, v109
	ds_write2_b32 v107, v80, v64 offset1:32
	ds_write2_b32 v107, v81, v65 offset0:128 offset1:160
	v_add_u32_e32 v80, 0x400, v107
	v_add_u32_e32 v64, 8, v97
	ds_write2_b32 v80, v82, v66 offset1:32
	ds_write2_b32 v80, v83, v67 offset0:128 offset1:160
	v_add_u32_e32 v81, 0x1000, v107
	v_add_u32_e32 v82, 0x1400, v107
	v_and_b32_e32 v67, 31, v64
	v_add_u32_e32 v64, 24, v97
	ds_write2_b32 v81, v84, v68 offset1:32
	ds_write2_b32 v81, v85, v69 offset0:128 offset1:160
	ds_write2_b32 v82, v86, v70 offset1:32
	ds_write2_b32 v82, v87, v71 offset0:128 offset1:160
	v_add_u32_e32 v71, 0x2000, v107
	v_and_b32_e32 v69, 31, v64
	v_lshlrev_b32_e32 v64, 4, v108
	ds_write2_b32 v71, v88, v72 offset1:32
	ds_write2_b32 v71, v89, v73 offset0:128 offset1:160
	v_add_u32_e32 v72, 0x2400, v107
	v_lshl_or_b32 v64, v97, 9, v64
	ds_write2_b32 v72, v90, v74 offset1:32
	ds_write2_b32 v72, v91, v75 offset0:128 offset1:160
	v_add_u32_e32 v73, 0x3000, v107
	v_add_u32_e32 v74, 0x3400, v107
	v_and_b32_e32 v66, 31, v97
	v_bitop3_b32 v68, v97, 16, 31 bitop3:0x6c
	v_add_u32_e32 v70, 0, v64
	s_mov_b32 s16, 0
	v_mov_b32_e32 v75, v97
	ds_write2_b32 v73, v92, v76 offset1:32
	ds_write2_b32 v73, v93, v77 offset0:128 offset1:160
	ds_write2_b32 v74, v94, v78 offset1:32
	ds_write2_b32 v74, v95, v79 offset0:128 offset1:160
	v_lshlrev_b32_e32 v64, 2, v106
	v_mov_b32_e32 v65, 0
	s_mov_b32 s16, s41
	v_or_b32_e32 v224, s16, v66
	v_mov_b32_e32 v226, s68
	v_mov_b32_e32 v227, s69
	v_mov_b32_e32 v162, s3
	v_mov_b32_e32 v163, s33
	v_cmp_gt_i32_e32 vcc, s8, v224
	v_add_u32_e32 v225, 0xffffc000, v224
	s_nop 0
	v_cndmask_b32_e32 v224, v225, v224, vcc
	v_cndmask_b32_e32 v226, v162, v226, vcc
	v_cndmask_b32_e32 v227, v163, v227, vcc
	v_mov_b32_e32 v225, 0
	v_lshlrev_b64 v[224:225], 12, v[224:225]
	v_lshl_add_u64 v[224:225], v[226:227], 0, v[224:225]
	v_lshl_add_u64 v[224:225], v[224:225], 0, s[4:5]
	v_lshl_add_u64 v[162:163], v[224:225], 0, v[64:65]
	global_load_dwordx4 v[224:227], v[162:163], off
	v_or_b32_e32 v228, s16, v67
	v_mov_b32_e32 v230, s68
	v_mov_b32_e32 v231, s69
	v_mov_b32_e32 v164, s3
	v_mov_b32_e32 v165, s33
	v_cmp_gt_i32_e32 vcc, s8, v228
	v_add_u32_e32 v229, 0xffffc000, v228
	s_nop 0
	v_cndmask_b32_e32 v228, v229, v228, vcc
	v_cndmask_b32_e32 v230, v164, v230, vcc
	v_cndmask_b32_e32 v231, v165, v231, vcc
	v_mov_b32_e32 v229, 0
	v_lshlrev_b64 v[228:229], 12, v[228:229]
	v_lshl_add_u64 v[228:229], v[230:231], 0, v[228:229]
	v_lshl_add_u64 v[228:229], v[228:229], 0, s[4:5]
	v_lshl_add_u64 v[164:165], v[228:229], 0, v[64:65]
	global_load_dwordx4 v[228:231], v[164:165], off
	v_or_b32_e32 v232, s16, v68
	v_mov_b32_e32 v234, s68
	v_mov_b32_e32 v235, s69
	v_mov_b32_e32 v166, s3
	v_mov_b32_e32 v167, s33
	v_cmp_gt_i32_e32 vcc, s8, v232
	v_add_u32_e32 v233, 0xffffc000, v232
	s_nop 0
	v_cndmask_b32_e32 v232, v233, v232, vcc
	v_cndmask_b32_e32 v234, v166, v234, vcc
	v_cndmask_b32_e32 v235, v167, v235, vcc
	v_mov_b32_e32 v233, 0
	v_lshlrev_b64 v[232:233], 12, v[232:233]
	v_lshl_add_u64 v[232:233], v[234:235], 0, v[232:233]
	v_lshl_add_u64 v[232:233], v[232:233], 0, s[4:5]
	v_lshl_add_u64 v[166:167], v[232:233], 0, v[64:65]
	global_load_dwordx4 v[232:235], v[166:167], off
	v_or_b32_e32 v236, s16, v69
	v_mov_b32_e32 v238, s68
	v_mov_b32_e32 v239, s69
	v_mov_b32_e32 v168, s3
	v_mov_b32_e32 v169, s33
	v_cmp_gt_i32_e32 vcc, s8, v236
	v_add_u32_e32 v237, 0xffffc000, v236
	s_nop 0
	v_cndmask_b32_e32 v236, v237, v236, vcc
	v_cndmask_b32_e32 v238, v168, v238, vcc
	v_cndmask_b32_e32 v239, v169, v239, vcc
	v_mov_b32_e32 v237, 0
	v_lshlrev_b64 v[236:237], 12, v[236:237]
	v_lshl_add_u64 v[236:237], v[238:239], 0, v[236:237]
	v_lshl_add_u64 v[236:237], v[236:237], 0, s[4:5]
	v_lshl_add_u64 v[168:169], v[236:237], 0, v[64:65]
	global_load_dwordx4 v[236:239], v[168:169], off
	s_add_u32 s16, s41, 96
	v_or_b32_e32 v240, s16, v66
	v_mov_b32_e32 v242, s68
	v_mov_b32_e32 v243, s69
	v_mov_b32_e32 v170, s3
	v_mov_b32_e32 v171, s33
	v_cmp_gt_i32_e32 vcc, s8, v240
	v_add_u32_e32 v241, 0xffffc000, v240
	s_nop 0
	v_cndmask_b32_e32 v240, v241, v240, vcc
	v_cndmask_b32_e32 v242, v170, v242, vcc
	v_cndmask_b32_e32 v243, v171, v243, vcc
	v_mov_b32_e32 v241, 0
	v_lshlrev_b64 v[240:241], 12, v[240:241]
	v_lshl_add_u64 v[240:241], v[242:243], 0, v[240:241]
	v_lshl_add_u64 v[240:241], v[240:241], 0, s[4:5]
	v_lshl_add_u64 v[170:171], v[240:241], 0, v[64:65]
	global_load_dwordx4 v[240:243], v[170:171], off
	v_or_b32_e32 v244, s16, v67
	v_mov_b32_e32 v246, s68
	v_mov_b32_e32 v247, s69
	v_mov_b32_e32 v172, s3
	v_mov_b32_e32 v173, s33
	v_cmp_gt_i32_e32 vcc, s8, v244
	v_add_u32_e32 v245, 0xffffc000, v244
	s_nop 0
	v_cndmask_b32_e32 v244, v245, v244, vcc
; template <int EPI, int MI>
; DI void gemm_tile(const GemmDesc& g, int tm, int tn, char* smem) {
;     ...
; #pragma unroll 4
;       for (int j = 0; j < 8; ++j) {
;         const int lrow = (tid >> 5) + 8 * j;
;         const int grow = m0 + (lrow >> 5) * (32 * MI) + mi * 32 + (lrow & 31);
;         const f32x4v a4 = *(const f32x4v*)(es + lrow * 128 + c4);
;         const int rg = grow < LAT ? (grow >> 11) : 8;
;         const f32x4v m4 = rg == rgA ? m4a : m4b;
;         float* rp = (grow < LAT ? g.xres + (size_t)grow * 1024 : g.hres + (size_t)(grow - LAT) * 1024) + n0 + c4;
;         f32x4v x4 = *(const f32x4v*)rp;
;         x4 += (m4 * a4) * g.coef;
;         *(f32x4v*)rp = x4;
;       }
	v_cndmask_b32_e32 v246, v172, v246, vcc
	v_cndmask_b32_e32 v247, v173, v247, vcc
	v_mov_b32_e32 v245, 0
	v_lshlrev_b64 v[244:245], 12, v[244:245]
	v_lshl_add_u64 v[244:245], v[246:247], 0, v[244:245]
	v_lshl_add_u64 v[244:245], v[244:245], 0, s[4:5]
	v_lshl_add_u64 v[172:173], v[244:245], 0, v[64:65]
	global_load_dwordx4 v[244:247], v[172:173], off
	v_or_b32_e32 v248, s16, v68
	v_mov_b32_e32 v250, s68
	v_mov_b32_e32 v251, s69
	v_mov_b32_e32 v174, s3
	v_mov_b32_e32 v175, s33
	v_cmp_gt_i32_e32 vcc, s8, v248
	v_add_u32_e32 v249, 0xffffc000, v248
	s_nop 0
	v_cndmask_b32_e32 v248, v249, v248, vcc
	v_cndmask_b32_e32 v250, v174, v250, vcc
	v_cndmask_b32_e32 v251, v175, v251, vcc
	v_mov_b32_e32 v249, 0
	v_lshlrev_b64 v[248:249], 12, v[248:249]
	v_lshl_add_u64 v[248:249], v[250:251], 0, v[248:249]
	v_lshl_add_u64 v[248:249], v[248:249], 0, s[4:5]
	v_lshl_add_u64 v[174:175], v[248:249], 0, v[64:65]
	global_load_dwordx4 v[248:251], v[174:175], off
	v_or_b32_e32 v252, s16, v69
	v_mov_b32_e32 v254, s68
	v_mov_b32_e32 v255, s69
	v_mov_b32_e32 v176, s3
	v_mov_b32_e32 v177, s33
	v_cmp_gt_i32_e32 vcc, s8, v252
	v_add_u32_e32 v253, 0xffffc000, v252
	s_nop 0
	v_cndmask_b32_e32 v252, v253, v252, vcc
	v_cndmask_b32_e32 v254, v176, v254, vcc
	v_cndmask_b32_e32 v255, v177, v255, vcc
	v_mov_b32_e32 v253, 0
	v_lshlrev_b64 v[252:253], 12, v[252:253]
	v_lshl_add_u64 v[252:253], v[254:255], 0, v[252:253]
	v_lshl_add_u64 v[252:253], v[252:253], 0, s[4:5]
	v_lshl_add_u64 v[176:177], v[252:253], 0, v[64:65]
	global_load_dwordx4 v[252:255], v[176:177], off
	s_waitcnt lgkmcnt(0)
	s_barrier
	s_waitcnt vmcnt(8)
	ds_read_b128 v[84:87], v70
	s_mov_b32 s16, s41
	s_ashr_i32 s17, s16, 11
	v_or_b32_e32 v88, s16, v66
	v_mov_b32_e32 v89, s17
	v_cmp_gt_i32_e32 vcc, s8, v88
	ds_read_b128 v[92:95], v70 offset:4096
	s_nop 0
	v_cndmask_b32_e32 v89, 8, v89, vcc
	v_cmp_eq_u32_e64 s[0:1], s15, v89
	s_nop 1
	v_cndmask_b32_e64 v89, v103, v99, s[0:1]
	v_cndmask_b32_e64 v88, v102, v98, s[0:1]
	v_cndmask_b32_e64 v91, v105, v101, s[0:1]
	v_cndmask_b32_e64 v90, v104, v100, s[0:1]
	s_waitcnt lgkmcnt(1)
	v_pk_mul_f32 v[86:87], v[86:87], v[90:91]
	v_pk_mul_f32 v[84:85], v[84:85], v[88:89]
	s_waitcnt vmcnt(7)
	v_pk_fma_f32 v[84:85], v[84:85], 0.5, v[224:225] op_sel_hi:[1,0,1]
	v_pk_fma_f32 v[86:87], v[86:87], 0.5, v[226:227] op_sel_hi:[1,0,1]
	global_store_dwordx4 v[162:163], v[84:87], off
	v_or_b32_e32 v88, s16, v67
	v_mov_b32_e32 v89, s17
	v_cmp_gt_i32_e32 vcc, s8, v88
	ds_read_b128 v[84:87], v70 offset:8192
	s_nop 0
	v_cndmask_b32_e32 v89, 8, v89, vcc
	v_cmp_eq_u32_e64 s[0:1], s15, v89
	s_nop 1
	v_cndmask_b32_e64 v89, v103, v99, s[0:1]
	v_cndmask_b32_e64 v88, v102, v98, s[0:1]
	v_cndmask_b32_e64 v91, v105, v101, s[0:1]
	v_cndmask_b32_e64 v90, v104, v100, s[0:1]
	s_waitcnt lgkmcnt(1)
	v_pk_mul_f32 v[94:95], v[94:95], v[90:91]
	v_pk_mul_f32 v[92:93], v[92:93], v[88:89]
	s_waitcnt vmcnt(7)
	v_pk_fma_f32 v[92:93], v[92:93], 0.5, v[228:229] op_sel_hi:[1,0,1]
	v_pk_fma_f32 v[94:95], v[94:95], 0.5, v[230:231] op_sel_hi:[1,0,1]
	global_store_dwordx4 v[164:165], v[92:95], off
	v_or_b32_e32 v88, s16, v68
	v_mov_b32_e32 v89, s17
	v_cmp_gt_i32_e32 vcc, s8, v88
	ds_read_b128 v[92:95], v70 offset:12288
	s_nop 0
	v_cndmask_b32_e32 v89, 8, v89, vcc
	v_cmp_eq_u32_e64 s[0:1], s15, v89
	s_nop 1
	v_cndmask_b32_e64 v89, v103, v99, s[0:1]
	v_cndmask_b32_e64 v88, v102, v98, s[0:1]
	v_cndmask_b32_e64 v91, v105, v101, s[0:1]
	v_cndmask_b32_e64 v90, v104, v100, s[0:1]
	s_waitcnt lgkmcnt(1)
	v_pk_mul_f32 v[86:87], v[86:87], v[90:91]
	v_pk_mul_f32 v[84:85], v[84:85], v[88:89]
	s_waitcnt vmcnt(7)
	v_pk_fma_f32 v[84:85], v[84:85], 0.5, v[232:233] op_sel_hi:[1,0,1]
	v_pk_fma_f32 v[86:87], v[86:87], 0.5, v[234:235] op_sel_hi:[1,0,1]
	global_store_dwordx4 v[166:167], v[84:87], off
	v_or_b32_e32 v88, s16, v69
	v_mov_b32_e32 v89, s17
	v_cmp_gt_i32_e32 vcc, s8, v88
	ds_read_b128 v[84:87], v70 offset:16384
	s_nop 0
	v_cndmask_b32_e32 v89, 8, v89, vcc
	v_cmp_eq_u32_e64 s[0:1], s15, v89
	s_nop 1
	v_cndmask_b32_e64 v89, v103, v99, s[0:1]
	v_cndmask_b32_e64 v88, v102, v98, s[0:1]
	v_cndmask_b32_e64 v91, v105, v101, s[0:1]
	v_cndmask_b32_e64 v90, v104, v100, s[0:1]
	s_waitcnt lgkmcnt(1)
	v_pk_mul_f32 v[94:95], v[94:95], v[90:91]
	v_pk_mul_f32 v[92:93], v[92:93], v[88:89]
	s_waitcnt vmcnt(7)
	v_pk_fma_f32 v[92:93], v[92:93], 0.5, v[236:237] op_sel_hi:[1,0,1]
	v_pk_fma_f32 v[94:95], v[94:95], 0.5, v[238:239] op_sel_hi:[1,0,1]
	global_store_dwordx4 v[168:169], v[92:95], off
	s_add_u32 s16, s41, 96
	s_ashr_i32 s17, s16, 11
	v_or_b32_e32 v88, s16, v66
	v_mov_b32_e32 v89, s17
	v_cmp_gt_i32_e32 vcc, s8, v88
	ds_read_b128 v[92:95], v70 offset:20480
	s_nop 0
	v_cndmask_b32_e32 v89, 8, v89, vcc
	v_cmp_eq_u32_e64 s[0:1], s15, v89
	s_nop 1
	v_cndmask_b32_e64 v89, v103, v99, s[0:1]
	v_cndmask_b32_e64 v88, v102, v98, s[0:1]
	v_cndmask_b32_e64 v91, v105, v101, s[0:1]
	v_cndmask_b32_e64 v90, v104, v100, s[0:1]
	s_waitcnt lgkmcnt(1)
	v_pk_mul_f32 v[86:87], v[86:87], v[90:91]
	v_pk_mul_f32 v[84:85], v[84:85], v[88:89]
	s_waitcnt vmcnt(7)
	v_pk_fma_f32 v[84:85], v[84:85], 0.5, v[240:241] op_sel_hi:[1,0,1]
	v_pk_fma_f32 v[86:87], v[86:87], 0.5, v[242:243] op_sel_hi:[1,0,1]
	global_store_dwordx4 v[170:171], v[84:87], off
	v_or_b32_e32 v88, s16, v67
	v_mov_b32_e32 v89, s17
	v_cmp_gt_i32_e32 vcc, s8, v88
	ds_read_b128 v[84:87], v70 offset:24576
	s_nop 0
	v_cndmask_b32_e32 v89, 8, v89, vcc
	v_cmp_eq_u32_e64 s[0:1], s15, v89
	s_nop 1
	v_cndmask_b32_e64 v89, v103, v99, s[0:1]
	v_cndmask_b32_e64 v88, v102, v98, s[0:1]
	v_cndmask_b32_e64 v91, v105, v101, s[0:1]
	v_cndmask_b32_e64 v90, v104, v100, s[0:1]
	s_waitcnt lgkmcnt(1)
; template <int EPI, int MI>
; DI void gemm_tile(const GemmDesc& g, int tm, int tn, char* smem) {
;     ...
; #pragma unroll 4
;       for (int j = 0; j < 8; ++j) {
;         const int lrow = (tid >> 5) + 8 * j;
;         const int grow = m0 + (lrow >> 5) * (32 * MI) + mi * 32 + (lrow & 31);
;         const f32x4v a4 = *(const f32x4v*)(es + lrow * 128 + c4);
;         const int rg = grow < LAT ? (grow >> 11) : 8;
;         const f32x4v m4 = rg == rgA ? m4a : m4b;
;         float* rp = (grow < LAT ? g.xres + (size_t)grow * 1024 : g.hres + (size_t)(grow - LAT) * 1024) + n0 + c4;
;         f32x4v x4 = *(const f32x4v*)rp;
;         x4 += (m4 * a4) * g.coef;
;         *(f32x4v*)rp = x4;
;       }
	v_pk_mul_f32 v[94:95], v[94:95], v[90:91]
	v_pk_mul_f32 v[92:93], v[92:93], v[88:89]
	s_waitcnt vmcnt(7)
	v_pk_fma_f32 v[92:93], v[92:93], 0.5, v[244:245] op_sel_hi:[1,0,1]
	v_pk_fma_f32 v[94:95], v[94:95], 0.5, v[246:247] op_sel_hi:[1,0,1]
	global_store_dwordx4 v[172:173], v[92:95], off
	v_or_b32_e32 v88, s16, v68
	v_mov_b32_e32 v89, s17
	v_cmp_gt_i32_e32 vcc, s8, v88
	ds_read_b128 v[92:95], v70 offset:28672
	s_nop 0
	v_cndmask_b32_e32 v89, 8, v89, vcc
	v_cmp_eq_u32_e64 s[0:1], s15, v89
	s_nop 1
	v_cndmask_b32_e64 v89, v103, v99, s[0:1]
	v_cndmask_b32_e64 v88, v102, v98, s[0:1]
	v_cndmask_b32_e64 v91, v105, v101, s[0:1]
	v_cndmask_b32_e64 v90, v104, v100, s[0:1]
	s_waitcnt lgkmcnt(1)
	v_pk_mul_f32 v[86:87], v[86:87], v[90:91]
	v_pk_mul_f32 v[84:85], v[84:85], v[88:89]
	s_waitcnt vmcnt(7)
	v_pk_fma_f32 v[84:85], v[84:85], 0.5, v[248:249] op_sel_hi:[1,0,1]
	v_pk_fma_f32 v[86:87], v[86:87], 0.5, v[250:251] op_sel_hi:[1,0,1]
	global_store_dwordx4 v[174:175], v[84:87], off
	v_or_b32_e32 v88, s16, v69
	v_mov_b32_e32 v89, s17
	v_cmp_gt_i32_e32 vcc, s8, v88
	s_nop 1
	v_cndmask_b32_e32 v89, 8, v89, vcc
	v_cmp_eq_u32_e64 s[0:1], s15, v89
	s_nop 1
	v_cndmask_b32_e64 v89, v103, v99, s[0:1]
	v_cndmask_b32_e64 v88, v102, v98, s[0:1]
	v_cndmask_b32_e64 v91, v105, v101, s[0:1]
	v_cndmask_b32_e64 v90, v104, v100, s[0:1]
	s_waitcnt lgkmcnt(0)
	v_pk_mul_f32 v[94:95], v[94:95], v[90:91]
	v_pk_mul_f32 v[92:93], v[92:93], v[88:89]
	s_waitcnt vmcnt(7)
	v_pk_fma_f32 v[92:93], v[92:93], 0.5, v[252:253] op_sel_hi:[1,0,1]
	v_pk_fma_f32 v[94:95], v[94:95], 0.5, v[254:255] op_sel_hi:[1,0,1]
	global_store_dwordx4 v[176:177], v[92:95], off
	s_add_u32 s16, s41, 32
	v_or_b32_e32 v224, s16, v66
	v_mov_b32_e32 v226, s68
	v_mov_b32_e32 v227, s69
	v_mov_b32_e32 v162, s3
	v_mov_b32_e32 v163, s33
	v_cmp_gt_i32_e32 vcc, s8, v224
	v_add_u32_e32 v225, 0xffffc000, v224
	s_nop 0
	v_cndmask_b32_e32 v224, v225, v224, vcc
	v_cndmask_b32_e32 v226, v162, v226, vcc
	v_cndmask_b32_e32 v227, v163, v227, vcc
	v_mov_b32_e32 v225, 0
	v_lshlrev_b64 v[224:225], 12, v[224:225]
	v_lshl_add_u64 v[224:225], v[226:227], 0, v[224:225]
	v_lshl_add_u64 v[224:225], v[224:225], 0, s[4:5]
	v_lshl_add_u64 v[162:163], v[224:225], 0, v[64:65]
	global_load_dwordx4 v[224:227], v[162:163], off
	v_or_b32_e32 v228, s16, v67
	v_mov_b32_e32 v230, s68
	v_mov_b32_e32 v231, s69
	v_mov_b32_e32 v164, s3
	v_mov_b32_e32 v165, s33
	v_cmp_gt_i32_e32 vcc, s8, v228
	v_add_u32_e32 v229, 0xffffc000, v228
	s_nop 0
	v_cndmask_b32_e32 v228, v229, v228, vcc
	v_cndmask_b32_e32 v230, v164, v230, vcc
	v_cndmask_b32_e32 v231, v165, v231, vcc
	v_mov_b32_e32 v229, 0
	v_lshlrev_b64 v[228:229], 12, v[228:229]
	v_lshl_add_u64 v[228:229], v[230:231], 0, v[228:229]
	v_lshl_add_u64 v[228:229], v[228:229], 0, s[4:5]
	v_lshl_add_u64 v[164:165], v[228:229], 0, v[64:65]
	global_load_dwordx4 v[228:231], v[164:165], off
	v_or_b32_e32 v232, s16, v68
	v_mov_b32_e32 v234, s68
	v_mov_b32_e32 v235, s69
	v_mov_b32_e32 v166, s3
	v_mov_b32_e32 v167, s33
	v_cmp_gt_i32_e32 vcc, s8, v232
	v_add_u32_e32 v233, 0xffffc000, v232
	s_nop 0
	v_cndmask_b32_e32 v232, v233, v232, vcc
	v_cndmask_b32_e32 v234, v166, v234, vcc
	v_cndmask_b32_e32 v235, v167, v235, vcc
	v_mov_b32_e32 v233, 0
	v_lshlrev_b64 v[232:233], 12, v[232:233]
	v_lshl_add_u64 v[232:233], v[234:235], 0, v[232:233]
	v_lshl_add_u64 v[232:233], v[232:233], 0, s[4:5]
	v_lshl_add_u64 v[166:167], v[232:233], 0, v[64:65]
	global_load_dwordx4 v[232:235], v[166:167], off
	v_or_b32_e32 v236, s16, v69
	v_mov_b32_e32 v238, s68
	v_mov_b32_e32 v239, s69
	v_mov_b32_e32 v168, s3
	v_mov_b32_e32 v169, s33
	v_cmp_gt_i32_e32 vcc, s8, v236
	v_add_u32_e32 v237, 0xffffc000, v236
	s_nop 0
	v_cndmask_b32_e32 v236, v237, v236, vcc
	v_cndmask_b32_e32 v238, v168, v238, vcc
	v_cndmask_b32_e32 v239, v169, v239, vcc
	v_mov_b32_e32 v237, 0
	v_lshlrev_b64 v[236:237], 12, v[236:237]
	v_lshl_add_u64 v[236:237], v[238:239], 0, v[236:237]
	v_lshl_add_u64 v[236:237], v[236:237], 0, s[4:5]
	v_lshl_add_u64 v[168:169], v[236:237], 0, v[64:65]
	global_load_dwordx4 v[236:239], v[168:169], off
	s_add_u32 s16, s41, 128
	v_or_b32_e32 v240, s16, v66
	v_mov_b32_e32 v242, s68
	v_mov_b32_e32 v243, s69
	v_mov_b32_e32 v170, s3
	v_mov_b32_e32 v171, s33
	v_cmp_gt_i32_e32 vcc, s8, v240
	v_add_u32_e32 v241, 0xffffc000, v240
	s_nop 0
	v_cndmask_b32_e32 v240, v241, v240, vcc
	v_cndmask_b32_e32 v242, v170, v242, vcc
	v_cndmask_b32_e32 v243, v171, v243, vcc
	v_mov_b32_e32 v241, 0
	v_lshlrev_b64 v[240:241], 12, v[240:241]
	v_lshl_add_u64 v[240:241], v[242:243], 0, v[240:241]
	v_lshl_add_u64 v[240:241], v[240:241], 0, s[4:5]
	v_lshl_add_u64 v[170:171], v[240:241], 0, v[64:65]
	global_load_dwordx4 v[240:243], v[170:171], off
	v_or_b32_e32 v244, s16, v67
	v_mov_b32_e32 v246, s68
	v_mov_b32_e32 v247, s69
	v_mov_b32_e32 v172, s3
	v_mov_b32_e32 v173, s33
	v_cmp_gt_i32_e32 vcc, s8, v244
	v_add_u32_e32 v245, 0xffffc000, v244
	s_nop 0
	v_cndmask_b32_e32 v244, v245, v244, vcc
	v_cndmask_b32_e32 v246, v172, v246, vcc
	v_cndmask_b32_e32 v247, v173, v247, vcc
	v_mov_b32_e32 v245, 0
	v_lshlrev_b64 v[244:245], 12, v[244:245]
	v_lshl_add_u64 v[244:245], v[246:247], 0, v[244:245]
	v_lshl_add_u64 v[244:245], v[244:245], 0, s[4:5]
	v_lshl_add_u64 v[172:173], v[244:245], 0, v[64:65]
	global_load_dwordx4 v[244:247], v[172:173], off
	v_or_b32_e32 v248, s16, v68
	v_mov_b32_e32 v250, s68
	v_mov_b32_e32 v251, s69
	v_mov_b32_e32 v174, s3
	v_mov_b32_e32 v175, s33
	v_cmp_gt_i32_e32 vcc, s8, v248
	v_add_u32_e32 v249, 0xffffc000, v248
	s_nop 0
	v_cndmask_b32_e32 v248, v249, v248, vcc
	v_cndmask_b32_e32 v250, v174, v250, vcc
	v_cndmask_b32_e32 v251, v175, v251, vcc
	v_mov_b32_e32 v249, 0
	v_lshlrev_b64 v[248:249], 12, v[248:249]
	v_lshl_add_u64 v[248:249], v[250:251], 0, v[248:249]
	v_lshl_add_u64 v[248:249], v[248:249], 0, s[4:5]
	v_lshl_add_u64 v[174:175], v[248:249], 0, v[64:65]
	global_load_dwordx4 v[248:251], v[174:175], off
	v_or_b32_e32 v252, s16, v69
	v_mov_b32_e32 v254, s68
	v_mov_b32_e32 v255, s69
	v_mov_b32_e32 v176, s3
	v_mov_b32_e32 v177, s33
	v_cmp_gt_i32_e32 vcc, s8, v252
	v_add_u32_e32 v253, 0xffffc000, v252
	s_nop 0
	v_cndmask_b32_e32 v252, v253, v252, vcc
	v_cndmask_b32_e32 v254, v176, v254, vcc
	v_cndmask_b32_e32 v255, v177, v255, vcc
	v_mov_b32_e32 v253, 0
	v_lshlrev_b64 v[252:253], 12, v[252:253]
	v_lshl_add_u64 v[252:253], v[254:255], 0, v[252:253]
	v_lshl_add_u64 v[252:253], v[252:253], 0, s[4:5]
	v_lshl_add_u64 v[176:177], v[252:253], 0, v[64:65]
	global_load_dwordx4 v[252:255], v[176:177], off
	s_barrier
; template <int EPI, int MI>
; DI void gemm_tile(const GemmDesc& g, int tm, int tn, char* smem) {
;     ...
;     for (int mi = 0; mi < MI; ++mi) {
; #pragma unroll
;       for (int ni = 0; ni < 2; ++ni)
; #pragma unroll
;         for (int i = 0; i < 16; ++i) {
;           const int lrow = wm * 32 + (i & 3) + 8 * (i >> 2) + 4 * hh;
;           es[lrow * 128 + wn * 64 + ni * 32 + r] = acc[mi][ni][i];
;         }
;       __syncthreads();
; #pragma unroll 4
;       for (int j = 0; j < 8; ++j) {
;         const int lrow = (tid >> 5) + 8 * j;
;         const int grow = m0 + (lrow >> 5) * (32 * MI) + mi * 32 + (lrow & 31);
;         const f32x4v a4 = *(const f32x4v*)(es + lrow * 128 + c4);
;         const int rg = grow < LAT ? (grow >> 11) : 8;
;         const f32x4v m4 = rg == rgA ? m4a : m4b;
;         float* rp = (grow < LAT ? g.xres + (size_t)grow * 1024 : g.hres + (size_t)(grow - LAT) * 1024) + n0 + c4;
;         f32x4v x4 = *(const f32x4v*)rp;
;         x4 += (m4 * a4) * g.coef;
;         *(f32x4v*)rp = x4;
;       }
	ds_write2_b32 v107, v48, v32 offset1:32
	ds_write2_b32 v107, v49, v33 offset0:128 offset1:160
	ds_write2_b32 v80, v50, v34 offset1:32
	ds_write2_b32 v80, v51, v35 offset0:128 offset1:160
	ds_write2_b32 v81, v52, v36 offset1:32
	ds_write2_b32 v81, v53, v37 offset0:128 offset1:160
	ds_write2_b32 v82, v54, v38 offset1:32
	ds_write2_b32 v82, v55, v39 offset0:128 offset1:160
	ds_write2_b32 v71, v56, v40 offset1:32
	ds_write2_b32 v71, v57, v41 offset0:128 offset1:160
	ds_write2_b32 v72, v58, v42 offset1:32
	ds_write2_b32 v72, v59, v43 offset0:128 offset1:160
	ds_write2_b32 v73, v60, v44 offset1:32
	ds_write2_b32 v73, v61, v45 offset0:128 offset1:160
	ds_write2_b32 v74, v62, v46 offset1:32
	ds_write2_b32 v74, v63, v47 offset0:128 offset1:160
	s_or_b32 s16, s41, 32
	s_mov_b32 s17, 0
	v_mov_b32_e32 v32, v97
	s_waitcnt lgkmcnt(0)
	s_barrier
	ds_read_b128 v[84:87], v70
	s_add_u32 s16, s41, 32
	s_ashr_i32 s17, s16, 11
	v_or_b32_e32 v88, s16, v66
	v_mov_b32_e32 v89, s17
	v_cmp_gt_i32_e32 vcc, s8, v88
	ds_read_b128 v[92:95], v70 offset:4096
	s_nop 0
	v_cndmask_b32_e32 v89, 8, v89, vcc
	v_cmp_eq_u32_e64 s[0:1], s15, v89
	s_nop 1
	v_cndmask_b32_e64 v89, v103, v99, s[0:1]
	v_cndmask_b32_e64 v88, v102, v98, s[0:1]
	v_cndmask_b32_e64 v91, v105, v101, s[0:1]
	v_cndmask_b32_e64 v90, v104, v100, s[0:1]
	s_waitcnt lgkmcnt(1)
	v_pk_mul_f32 v[86:87], v[86:87], v[90:91]
	v_pk_mul_f32 v[84:85], v[84:85], v[88:89]
	s_waitcnt vmcnt(7)
	v_pk_fma_f32 v[84:85], v[84:85], 0.5, v[224:225] op_sel_hi:[1,0,1]
	v_pk_fma_f32 v[86:87], v[86:87], 0.5, v[226:227] op_sel_hi:[1,0,1]
	global_store_dwordx4 v[162:163], v[84:87], off
	v_or_b32_e32 v88, s16, v67
	v_mov_b32_e32 v89, s17
	v_cmp_gt_i32_e32 vcc, s8, v88
	ds_read_b128 v[84:87], v70 offset:8192
	s_nop 0
	v_cndmask_b32_e32 v89, 8, v89, vcc
	v_cmp_eq_u32_e64 s[0:1], s15, v89
	s_nop 1
	v_cndmask_b32_e64 v89, v103, v99, s[0:1]
	v_cndmask_b32_e64 v88, v102, v98, s[0:1]
	v_cndmask_b32_e64 v91, v105, v101, s[0:1]
	v_cndmask_b32_e64 v90, v104, v100, s[0:1]
	s_waitcnt lgkmcnt(1)
	v_pk_mul_f32 v[94:95], v[94:95], v[90:91]
	v_pk_mul_f32 v[92:93], v[92:93], v[88:89]
	s_waitcnt vmcnt(7)
	v_pk_fma_f32 v[92:93], v[92:93], 0.5, v[228:229] op_sel_hi:[1,0,1]
	v_pk_fma_f32 v[94:95], v[94:95], 0.5, v[230:231] op_sel_hi:[1,0,1]
	global_store_dwordx4 v[164:165], v[92:95], off
	v_or_b32_e32 v88, s16, v68
	v_mov_b32_e32 v89, s17
	v_cmp_gt_i32_e32 vcc, s8, v88
	ds_read_b128 v[92:95], v70 offset:12288
	s_nop 0
	v_cndmask_b32_e32 v89, 8, v89, vcc
	v_cmp_eq_u32_e64 s[0:1], s15, v89
	s_nop 1
	v_cndmask_b32_e64 v89, v103, v99, s[0:1]
	v_cndmask_b32_e64 v88, v102, v98, s[0:1]
	v_cndmask_b32_e64 v91, v105, v101, s[0:1]
	v_cndmask_b32_e64 v90, v104, v100, s[0:1]
	s_waitcnt lgkmcnt(1)
	v_pk_mul_f32 v[86:87], v[86:87], v[90:91]
	v_pk_mul_f32 v[84:85], v[84:85], v[88:89]
	s_waitcnt vmcnt(7)
	v_pk_fma_f32 v[84:85], v[84:85], 0.5, v[232:233] op_sel_hi:[1,0,1]
	v_pk_fma_f32 v[86:87], v[86:87], 0.5, v[234:235] op_sel_hi:[1,0,1]
	global_store_dwordx4 v[166:167], v[84:87], off
	v_or_b32_e32 v88, s16, v69
	v_mov_b32_e32 v89, s17
	v_cmp_gt_i32_e32 vcc, s8, v88
	ds_read_b128 v[84:87], v70 offset:16384
	s_nop 0
	v_cndmask_b32_e32 v89, 8, v89, vcc
	v_cmp_eq_u32_e64 s[0:1], s15, v89
	s_nop 1
	v_cndmask_b32_e64 v89, v103, v99, s[0:1]
	v_cndmask_b32_e64 v88, v102, v98, s[0:1]
	v_cndmask_b32_e64 v91, v105, v101, s[0:1]
	v_cndmask_b32_e64 v90, v104, v100, s[0:1]
	s_waitcnt lgkmcnt(1)
	v_pk_mul_f32 v[94:95], v[94:95], v[90:91]
	v_pk_mul_f32 v[92:93], v[92:93], v[88:89]
	s_waitcnt vmcnt(7)
	v_pk_fma_f32 v[92:93], v[92:93], 0.5, v[236:237] op_sel_hi:[1,0,1]
	v_pk_fma_f32 v[94:95], v[94:95], 0.5, v[238:239] op_sel_hi:[1,0,1]
	global_store_dwordx4 v[168:169], v[92:95], off
	s_add_u32 s16, s41, 128
	s_ashr_i32 s17, s16, 11
	v_or_b32_e32 v88, s16, v66
	v_mov_b32_e32 v89, s17
	v_cmp_gt_i32_e32 vcc, s8, v88
	ds_read_b128 v[92:95], v70 offset:20480
	s_nop 0
	v_cndmask_b32_e32 v89, 8, v89, vcc
	v_cmp_eq_u32_e64 s[0:1], s15, v89
	s_nop 1
	v_cndmask_b32_e64 v89, v103, v99, s[0:1]
	v_cndmask_b32_e64 v88, v102, v98, s[0:1]
	v_cndmask_b32_e64 v91, v105, v101, s[0:1]
	v_cndmask_b32_e64 v90, v104, v100, s[0:1]
	s_waitcnt lgkmcnt(1)
	v_pk_mul_f32 v[86:87], v[86:87], v[90:91]
	v_pk_mul_f32 v[84:85], v[84:85], v[88:89]
	s_waitcnt vmcnt(7)
	v_pk_fma_f32 v[84:85], v[84:85], 0.5, v[240:241] op_sel_hi:[1,0,1]
	v_pk_fma_f32 v[86:87], v[86:87], 0.5, v[242:243] op_sel_hi:[1,0,1]
	global_store_dwordx4 v[170:171], v[84:87], off
	v_or_b32_e32 v88, s16, v67
	v_mov_b32_e32 v89, s17
	v_cmp_gt_i32_e32 vcc, s8, v88
	ds_read_b128 v[84:87], v70 offset:24576
	s_nop 0
	v_cndmask_b32_e32 v89, 8, v89, vcc
	v_cmp_eq_u32_e64 s[0:1], s15, v89
	s_nop 1
	v_cndmask_b32_e64 v89, v103, v99, s[0:1]
	v_cndmask_b32_e64 v88, v102, v98, s[0:1]
	v_cndmask_b32_e64 v91, v105, v101, s[0:1]
	v_cndmask_b32_e64 v90, v104, v100, s[0:1]
	s_waitcnt lgkmcnt(1)
	v_pk_mul_f32 v[94:95], v[94:95], v[90:91]
	v_pk_mul_f32 v[92:93], v[92:93], v[88:89]
	s_waitcnt vmcnt(7)
	v_pk_fma_f32 v[92:93], v[92:93], 0.5, v[244:245] op_sel_hi:[1,0,1]
	v_pk_fma_f32 v[94:95], v[94:95], 0.5, v[246:247] op_sel_hi:[1,0,1]
	global_store_dwordx4 v[172:173], v[92:95], off
	v_or_b32_e32 v88, s16, v68
	v_mov_b32_e32 v89, s17
	v_cmp_gt_i32_e32 vcc, s8, v88
	ds_read_b128 v[92:95], v70 offset:28672
	s_nop 0
	v_cndmask_b32_e32 v89, 8, v89, vcc
	v_cmp_eq_u32_e64 s[0:1], s15, v89
	s_nop 1
	v_cndmask_b32_e64 v89, v103, v99, s[0:1]
	v_cndmask_b32_e64 v88, v102, v98, s[0:1]
	v_cndmask_b32_e64 v91, v105, v101, s[0:1]
	v_cndmask_b32_e64 v90, v104, v100, s[0:1]
	s_waitcnt lgkmcnt(1)
	v_pk_mul_f32 v[86:87], v[86:87], v[90:91]
	v_pk_mul_f32 v[84:85], v[84:85], v[88:89]
	s_waitcnt vmcnt(7)
; template <int EPI, int MI>
; DI void gemm_tile(const GemmDesc& g, int tm, int tn, char* smem) {
;     ...
; #pragma unroll 4
;       for (int j = 0; j < 8; ++j) {
;         const int lrow = (tid >> 5) + 8 * j;
;         const int grow = m0 + (lrow >> 5) * (32 * MI) + mi * 32 + (lrow & 31);
;         const f32x4v a4 = *(const f32x4v*)(es + lrow * 128 + c4);
;         const int rg = grow < LAT ? (grow >> 11) : 8;
;         const f32x4v m4 = rg == rgA ? m4a : m4b;
;         float* rp = (grow < LAT ? g.xres + (size_t)grow * 1024 : g.hres + (size_t)(grow - LAT) * 1024) + n0 + c4;
;         f32x4v x4 = *(const f32x4v*)rp;
;         x4 += (m4 * a4) * g.coef;
;         *(f32x4v*)rp = x4;
;       }
;       __syncthreads();
	v_pk_fma_f32 v[84:85], v[84:85], 0.5, v[248:249] op_sel_hi:[1,0,1]
	v_pk_fma_f32 v[86:87], v[86:87], 0.5, v[250:251] op_sel_hi:[1,0,1]
	global_store_dwordx4 v[174:175], v[84:87], off
	v_or_b32_e32 v88, s16, v69
	v_mov_b32_e32 v89, s17
	v_cmp_gt_i32_e32 vcc, s8, v88
	s_nop 1
	v_cndmask_b32_e32 v89, 8, v89, vcc
	v_cmp_eq_u32_e64 s[0:1], s15, v89
	s_nop 1
	v_cndmask_b32_e64 v89, v103, v99, s[0:1]
	v_cndmask_b32_e64 v88, v102, v98, s[0:1]
	v_cndmask_b32_e64 v91, v105, v101, s[0:1]
	v_cndmask_b32_e64 v90, v104, v100, s[0:1]
	s_waitcnt lgkmcnt(0)
	v_pk_mul_f32 v[94:95], v[94:95], v[90:91]
	v_pk_mul_f32 v[92:93], v[92:93], v[88:89]
	s_waitcnt vmcnt(7)
	v_pk_fma_f32 v[92:93], v[92:93], 0.5, v[252:253] op_sel_hi:[1,0,1]
	v_pk_fma_f32 v[94:95], v[94:95], 0.5, v[254:255] op_sel_hi:[1,0,1]
	global_store_dwordx4 v[176:177], v[92:95], off
	s_add_u32 s16, s41, 64
	v_or_b32_e32 v224, s16, v66
	v_mov_b32_e32 v226, s68
	v_mov_b32_e32 v227, s69
	v_mov_b32_e32 v162, s3
	v_mov_b32_e32 v163, s33
	v_cmp_gt_i32_e32 vcc, s8, v224
	v_add_u32_e32 v225, 0xffffc000, v224
	s_nop 0
	v_cndmask_b32_e32 v224, v225, v224, vcc
	v_cndmask_b32_e32 v226, v162, v226, vcc
	v_cndmask_b32_e32 v227, v163, v227, vcc
	v_mov_b32_e32 v225, 0
	v_lshlrev_b64 v[224:225], 12, v[224:225]
	v_lshl_add_u64 v[224:225], v[226:227], 0, v[224:225]
	v_lshl_add_u64 v[224:225], v[224:225], 0, s[4:5]
	v_lshl_add_u64 v[162:163], v[224:225], 0, v[64:65]
	global_load_dwordx4 v[224:227], v[162:163], off
	v_or_b32_e32 v228, s16, v67
	v_mov_b32_e32 v230, s68
	v_mov_b32_e32 v231, s69
	v_mov_b32_e32 v164, s3
	v_mov_b32_e32 v165, s33
	v_cmp_gt_i32_e32 vcc, s8, v228
	v_add_u32_e32 v229, 0xffffc000, v228
	s_nop 0
	v_cndmask_b32_e32 v228, v229, v228, vcc
	v_cndmask_b32_e32 v230, v164, v230, vcc
	v_cndmask_b32_e32 v231, v165, v231, vcc
	v_mov_b32_e32 v229, 0
	v_lshlrev_b64 v[228:229], 12, v[228:229]
	v_lshl_add_u64 v[228:229], v[230:231], 0, v[228:229]
	v_lshl_add_u64 v[228:229], v[228:229], 0, s[4:5]
	v_lshl_add_u64 v[164:165], v[228:229], 0, v[64:65]
	global_load_dwordx4 v[228:231], v[164:165], off
	v_or_b32_e32 v232, s16, v68
	v_mov_b32_e32 v234, s68
	v_mov_b32_e32 v235, s69
	v_mov_b32_e32 v166, s3
	v_mov_b32_e32 v167, s33
	v_cmp_gt_i32_e32 vcc, s8, v232
	v_add_u32_e32 v233, 0xffffc000, v232
	s_nop 0
	v_cndmask_b32_e32 v232, v233, v232, vcc
	v_cndmask_b32_e32 v234, v166, v234, vcc
	v_cndmask_b32_e32 v235, v167, v235, vcc
	v_mov_b32_e32 v233, 0
	v_lshlrev_b64 v[232:233], 12, v[232:233]
	v_lshl_add_u64 v[232:233], v[234:235], 0, v[232:233]
	v_lshl_add_u64 v[232:233], v[232:233], 0, s[4:5]
	v_lshl_add_u64 v[166:167], v[232:233], 0, v[64:65]
	global_load_dwordx4 v[232:235], v[166:167], off
	v_or_b32_e32 v236, s16, v69
	v_mov_b32_e32 v238, s68
	v_mov_b32_e32 v239, s69
	v_mov_b32_e32 v168, s3
	v_mov_b32_e32 v169, s33
	v_cmp_gt_i32_e32 vcc, s8, v236
	v_add_u32_e32 v237, 0xffffc000, v236
	s_nop 0
	v_cndmask_b32_e32 v236, v237, v236, vcc
	v_cndmask_b32_e32 v238, v168, v238, vcc
	v_cndmask_b32_e32 v239, v169, v239, vcc
	v_mov_b32_e32 v237, 0
	v_lshlrev_b64 v[236:237], 12, v[236:237]
	v_lshl_add_u64 v[236:237], v[238:239], 0, v[236:237]
	v_lshl_add_u64 v[236:237], v[236:237], 0, s[4:5]
	v_lshl_add_u64 v[168:169], v[236:237], 0, v[64:65]
	global_load_dwordx4 v[236:239], v[168:169], off
	s_add_u32 s16, s41, 160
	v_or_b32_e32 v240, s16, v66
	v_mov_b32_e32 v242, s68
	v_mov_b32_e32 v243, s69
	v_mov_b32_e32 v170, s3
	v_mov_b32_e32 v171, s33
	v_cmp_gt_i32_e32 vcc, s8, v240
	v_add_u32_e32 v241, 0xffffc000, v240
	s_nop 0
	v_cndmask_b32_e32 v240, v241, v240, vcc
	v_cndmask_b32_e32 v242, v170, v242, vcc
	v_cndmask_b32_e32 v243, v171, v243, vcc
	v_mov_b32_e32 v241, 0
	v_lshlrev_b64 v[240:241], 12, v[240:241]
	v_lshl_add_u64 v[240:241], v[242:243], 0, v[240:241]
	v_lshl_add_u64 v[240:241], v[240:241], 0, s[4:5]
	v_lshl_add_u64 v[170:171], v[240:241], 0, v[64:65]
	global_load_dwordx4 v[240:243], v[170:171], off
	v_or_b32_e32 v244, s16, v67
	v_mov_b32_e32 v246, s68
	v_mov_b32_e32 v247, s69
	v_mov_b32_e32 v172, s3
	v_mov_b32_e32 v173, s33
	v_cmp_gt_i32_e32 vcc, s8, v244
	v_add_u32_e32 v245, 0xffffc000, v244
	s_nop 0
	v_cndmask_b32_e32 v244, v245, v244, vcc
	v_cndmask_b32_e32 v246, v172, v246, vcc
	v_cndmask_b32_e32 v247, v173, v247, vcc
	v_mov_b32_e32 v245, 0
	v_lshlrev_b64 v[244:245], 12, v[244:245]
	v_lshl_add_u64 v[244:245], v[246:247], 0, v[244:245]
	v_lshl_add_u64 v[244:245], v[244:245], 0, s[4:5]
	v_lshl_add_u64 v[172:173], v[244:245], 0, v[64:65]
	global_load_dwordx4 v[244:247], v[172:173], off
	v_or_b32_e32 v248, s16, v68
	v_mov_b32_e32 v250, s68
	v_mov_b32_e32 v251, s69
	v_mov_b32_e32 v174, s3
	v_mov_b32_e32 v175, s33
	v_cmp_gt_i32_e32 vcc, s8, v248
	v_add_u32_e32 v249, 0xffffc000, v248
	s_nop 0
	v_cndmask_b32_e32 v248, v249, v248, vcc
	v_cndmask_b32_e32 v250, v174, v250, vcc
	v_cndmask_b32_e32 v251, v175, v251, vcc
	v_mov_b32_e32 v249, 0
	v_lshlrev_b64 v[248:249], 12, v[248:249]
	v_lshl_add_u64 v[248:249], v[250:251], 0, v[248:249]
	v_lshl_add_u64 v[248:249], v[248:249], 0, s[4:5]
	v_lshl_add_u64 v[174:175], v[248:249], 0, v[64:65]
	global_load_dwordx4 v[248:251], v[174:175], off
	v_or_b32_e32 v252, s16, v69
	v_mov_b32_e32 v254, s68
	v_mov_b32_e32 v255, s69
	v_mov_b32_e32 v176, s3
	v_mov_b32_e32 v177, s33
	v_cmp_gt_i32_e32 vcc, s8, v252
	v_add_u32_e32 v253, 0xffffc000, v252
	s_nop 0
	v_cndmask_b32_e32 v252, v253, v252, vcc
	v_cndmask_b32_e32 v254, v176, v254, vcc
	v_cndmask_b32_e32 v255, v177, v255, vcc
	v_mov_b32_e32 v253, 0
	v_lshlrev_b64 v[252:253], 12, v[252:253]
	v_lshl_add_u64 v[252:253], v[254:255], 0, v[252:253]
	v_lshl_add_u64 v[252:253], v[252:253], 0, s[4:5]
	v_lshl_add_u64 v[176:177], v[252:253], 0, v[64:65]
	global_load_dwordx4 v[252:255], v[176:177], off
	s_add_i32 s41, s41, 64
	s_mov_b32 s16, 0
	s_barrier
; template <int EPI, int MI>
; DI void gemm_tile(const GemmDesc& g, int tm, int tn, char* smem) {
;     ...
;     for (int mi = 0; mi < MI; ++mi) {
; #pragma unroll
;       for (int ni = 0; ni < 2; ++ni)
; #pragma unroll
;         for (int i = 0; i < 16; ++i) {
;           const int lrow = wm * 32 + (i & 3) + 8 * (i >> 2) + 4 * hh;
;           es[lrow * 128 + wn * 64 + ni * 32 + r] = acc[mi][ni][i];
;         }
;       __syncthreads();
; #pragma unroll 4
;       for (int j = 0; j < 8; ++j) {
;         const int lrow = (tid >> 5) + 8 * j;
;         const int grow = m0 + (lrow >> 5) * (32 * MI) + mi * 32 + (lrow & 31);
;         const f32x4v a4 = *(const f32x4v*)(es + lrow * 128 + c4);
;         const int rg = grow < LAT ? (grow >> 11) : 8;
;         const f32x4v m4 = rg == rgA ? m4a : m4b;
;         float* rp = (grow < LAT ? g.xres + (size_t)grow * 1024 : g.hres + (size_t)(grow - LAT) * 1024) + n0 + c4;
;         f32x4v x4 = *(const f32x4v*)rp;
;         x4 += (m4 * a4) * g.coef;
;         *(f32x4v*)rp = x4;
;       }
;       __syncthreads();
	ds_write2_b32 v107, v16, v0 offset1:32
	ds_write2_b32 v107, v17, v1 offset0:128 offset1:160
	ds_write2_b32 v80, v18, v2 offset1:32
	ds_write2_b32 v80, v19, v3 offset0:128 offset1:160
	ds_write2_b32 v81, v20, v4 offset1:32
	ds_write2_b32 v81, v21, v5 offset0:128 offset1:160
	ds_write2_b32 v82, v22, v6 offset1:32
	ds_write2_b32 v82, v23, v7 offset0:128 offset1:160
	ds_write2_b32 v71, v24, v8 offset1:32
	ds_write2_b32 v71, v25, v9 offset0:128 offset1:160
	ds_write2_b32 v72, v26, v10 offset1:32
	ds_write2_b32 v72, v27, v11 offset0:128 offset1:160
	ds_write2_b32 v73, v28, v12 offset1:32
	ds_write2_b32 v73, v29, v13 offset0:128 offset1:160
	ds_write2_b32 v74, v30, v14 offset1:32
	ds_write2_b32 v74, v31, v15 offset0:128 offset1:160
	s_waitcnt lgkmcnt(0)
	s_barrier
	ds_read_b128 v[84:87], v70
	s_mov_b32 s16, s41
	s_ashr_i32 s17, s16, 11
	v_or_b32_e32 v88, s16, v66
	v_mov_b32_e32 v89, s17
	v_cmp_gt_i32_e32 vcc, s8, v88
	ds_read_b128 v[92:95], v70 offset:4096
	s_nop 0
	v_cndmask_b32_e32 v89, 8, v89, vcc
	v_cmp_eq_u32_e64 s[0:1], s15, v89
	s_nop 1
	v_cndmask_b32_e64 v89, v103, v99, s[0:1]
	v_cndmask_b32_e64 v88, v102, v98, s[0:1]
	v_cndmask_b32_e64 v91, v105, v101, s[0:1]
	v_cndmask_b32_e64 v90, v104, v100, s[0:1]
	s_waitcnt lgkmcnt(1)
	v_pk_mul_f32 v[86:87], v[86:87], v[90:91]
	v_pk_mul_f32 v[84:85], v[84:85], v[88:89]
	s_waitcnt vmcnt(7)
	v_pk_fma_f32 v[84:85], v[84:85], 0.5, v[224:225] op_sel_hi:[1,0,1]
	v_pk_fma_f32 v[86:87], v[86:87], 0.5, v[226:227] op_sel_hi:[1,0,1]
	global_store_dwordx4 v[162:163], v[84:87], off
	v_or_b32_e32 v88, s16, v67
	v_mov_b32_e32 v89, s17
	v_cmp_gt_i32_e32 vcc, s8, v88
	ds_read_b128 v[84:87], v70 offset:8192
	s_nop 0
	v_cndmask_b32_e32 v89, 8, v89, vcc
	v_cmp_eq_u32_e64 s[0:1], s15, v89
	s_nop 1
	v_cndmask_b32_e64 v89, v103, v99, s[0:1]
	v_cndmask_b32_e64 v88, v102, v98, s[0:1]
	v_cndmask_b32_e64 v91, v105, v101, s[0:1]
	v_cndmask_b32_e64 v90, v104, v100, s[0:1]
	s_waitcnt lgkmcnt(1)
	v_pk_mul_f32 v[94:95], v[94:95], v[90:91]
	v_pk_mul_f32 v[92:93], v[92:93], v[88:89]
	s_waitcnt vmcnt(7)
	v_pk_fma_f32 v[92:93], v[92:93], 0.5, v[228:229] op_sel_hi:[1,0,1]
	v_pk_fma_f32 v[94:95], v[94:95], 0.5, v[230:231] op_sel_hi:[1,0,1]
	global_store_dwordx4 v[164:165], v[92:95], off
	v_or_b32_e32 v88, s16, v68
	v_mov_b32_e32 v89, s17
	v_cmp_gt_i32_e32 vcc, s8, v88
	ds_read_b128 v[92:95], v70 offset:12288
	s_nop 0
	v_cndmask_b32_e32 v89, 8, v89, vcc
	v_cmp_eq_u32_e64 s[0:1], s15, v89
	s_nop 1
	v_cndmask_b32_e64 v89, v103, v99, s[0:1]
	v_cndmask_b32_e64 v88, v102, v98, s[0:1]
	v_cndmask_b32_e64 v91, v105, v101, s[0:1]
	v_cndmask_b32_e64 v90, v104, v100, s[0:1]
	s_waitcnt lgkmcnt(1)
	v_pk_mul_f32 v[86:87], v[86:87], v[90:91]
	v_pk_mul_f32 v[84:85], v[84:85], v[88:89]
	s_waitcnt vmcnt(7)
	v_pk_fma_f32 v[84:85], v[84:85], 0.5, v[232:233] op_sel_hi:[1,0,1]
	v_pk_fma_f32 v[86:87], v[86:87], 0.5, v[234:235] op_sel_hi:[1,0,1]
	global_store_dwordx4 v[166:167], v[84:87], off
	v_or_b32_e32 v88, s16, v69
	v_mov_b32_e32 v89, s17
	v_cmp_gt_i32_e32 vcc, s8, v88
	ds_read_b128 v[84:87], v70 offset:16384
	s_nop 0
	v_cndmask_b32_e32 v89, 8, v89, vcc
	v_cmp_eq_u32_e64 s[0:1], s15, v89
	s_nop 1
	v_cndmask_b32_e64 v89, v103, v99, s[0:1]
	v_cndmask_b32_e64 v88, v102, v98, s[0:1]
	v_cndmask_b32_e64 v91, v105, v101, s[0:1]
	v_cndmask_b32_e64 v90, v104, v100, s[0:1]
	s_waitcnt lgkmcnt(1)
	v_pk_mul_f32 v[94:95], v[94:95], v[90:91]
	v_pk_mul_f32 v[92:93], v[92:93], v[88:89]
	s_waitcnt vmcnt(7)
	v_pk_fma_f32 v[92:93], v[92:93], 0.5, v[236:237] op_sel_hi:[1,0,1]
	v_pk_fma_f32 v[94:95], v[94:95], 0.5, v[238:239] op_sel_hi:[1,0,1]
	global_store_dwordx4 v[168:169], v[92:95], off
	s_add_u32 s16, s41, 96
	s_ashr_i32 s17, s16, 11
	v_or_b32_e32 v88, s16, v66
	v_mov_b32_e32 v89, s17
	v_cmp_gt_i32_e32 vcc, s8, v88
	ds_read_b128 v[92:95], v70 offset:20480
	s_nop 0
	v_cndmask_b32_e32 v89, 8, v89, vcc
	v_cmp_eq_u32_e64 s[0:1], s15, v89
	s_nop 1
	v_cndmask_b32_e64 v89, v103, v99, s[0:1]
	v_cndmask_b32_e64 v88, v102, v98, s[0:1]
	v_cndmask_b32_e64 v91, v105, v101, s[0:1]
	v_cndmask_b32_e64 v90, v104, v100, s[0:1]
	s_waitcnt lgkmcnt(1)
	v_pk_mul_f32 v[86:87], v[86:87], v[90:91]
	v_pk_mul_f32 v[84:85], v[84:85], v[88:89]
	s_waitcnt vmcnt(7)
	v_pk_fma_f32 v[84:85], v[84:85], 0.5, v[240:241] op_sel_hi:[1,0,1]
	v_pk_fma_f32 v[86:87], v[86:87], 0.5, v[242:243] op_sel_hi:[1,0,1]
	global_store_dwordx4 v[170:171], v[84:87], off
	v_or_b32_e32 v88, s16, v67
	v_mov_b32_e32 v89, s17
	v_cmp_gt_i32_e32 vcc, s8, v88
	ds_read_b128 v[84:87], v70 offset:24576
	s_nop 0
	v_cndmask_b32_e32 v89, 8, v89, vcc
	v_cmp_eq_u32_e64 s[0:1], s15, v89
	s_nop 1
	v_cndmask_b32_e64 v89, v103, v99, s[0:1]
	v_cndmask_b32_e64 v88, v102, v98, s[0:1]
	v_cndmask_b32_e64 v91, v105, v101, s[0:1]
	v_cndmask_b32_e64 v90, v104, v100, s[0:1]
	s_waitcnt lgkmcnt(1)
	v_pk_mul_f32 v[94:95], v[94:95], v[90:91]
	v_pk_mul_f32 v[92:93], v[92:93], v[88:89]
	s_waitcnt vmcnt(7)
	v_pk_fma_f32 v[92:93], v[92:93], 0.5, v[244:245] op_sel_hi:[1,0,1]
	v_pk_fma_f32 v[94:95], v[94:95], 0.5, v[246:247] op_sel_hi:[1,0,1]
	global_store_dwordx4 v[172:173], v[92:95], off
	v_or_b32_e32 v88, s16, v68
	v_mov_b32_e32 v89, s17
	v_cmp_gt_i32_e32 vcc, s8, v88
	ds_read_b128 v[92:95], v70 offset:28672
	s_nop 0
	v_cndmask_b32_e32 v89, 8, v89, vcc
	v_cmp_eq_u32_e64 s[0:1], s15, v89
	s_nop 1
	v_cndmask_b32_e64 v89, v103, v99, s[0:1]
	v_cndmask_b32_e64 v88, v102, v98, s[0:1]
	v_cndmask_b32_e64 v91, v105, v101, s[0:1]
	v_cndmask_b32_e64 v90, v104, v100, s[0:1]
	s_waitcnt lgkmcnt(1)
	v_pk_mul_f32 v[86:87], v[86:87], v[90:91]
	v_pk_mul_f32 v[84:85], v[84:85], v[88:89]
	s_waitcnt vmcnt(7)
	v_pk_fma_f32 v[84:85], v[84:85], 0.5, v[248:249] op_sel_hi:[1,0,1]
	v_pk_fma_f32 v[86:87], v[86:87], 0.5, v[250:251] op_sel_hi:[1,0,1]
	global_store_dwordx4 v[174:175], v[84:87], off
	v_or_b32_e32 v88, s16, v69
	v_mov_b32_e32 v89, s17
	v_cmp_gt_i32_e32 vcc, s8, v88
	s_nop 1
	v_cndmask_b32_e32 v89, 8, v89, vcc
	v_cmp_eq_u32_e64 s[0:1], s15, v89
	s_nop 1
	v_cndmask_b32_e64 v89, v103, v99, s[0:1]
	v_cndmask_b32_e64 v88, v102, v98, s[0:1]
	v_cndmask_b32_e64 v91, v105, v101, s[0:1]
	v_cndmask_b32_e64 v90, v104, v100, s[0:1]
	s_waitcnt lgkmcnt(0)
	v_pk_mul_f32 v[94:95], v[94:95], v[90:91]
	v_pk_mul_f32 v[92:93], v[92:93], v[88:89]
	s_waitcnt vmcnt(7)
	v_pk_fma_f32 v[92:93], v[92:93], 0.5, v[252:253] op_sel_hi:[1,0,1]
	v_pk_fma_f32 v[94:95], v[94:95], 0.5, v[254:255] op_sel_hi:[1,0,1]
	global_store_dwordx4 v[176:177], v[92:95], off
	v_readlane_b32 s0, v218, 38
	s_add_i32 s40, s40, s0
	v_readlane_b32 s0, v218, 31
	s_add_i32 s39, s39, s0
	v_readlane_b32 s0, v221, 13
	s_cmp_ge_i32 s40, s0
	s_barrier
	s_cbranch_scc0 .LBB0_1491
